# plus GEMM K loops: first iteration peeled with srcC=0, accumulator zeroing v_movs removed
# baseline (speedup 1.0000x reference)
; #define STAGE(P, g) do { const char* g_ = (const char*)(g); \
;         __builtin_amdgcn_global_load_lds((const unsigned*)(g_ + so0), (lds_u32*)((lds_u8*)(P) + sb0), 16, 0, 0); \
;         __builtin_amdgcn_global_load_lds((const unsigned*)(g_ + so1), (lds_u32*)((lds_u8*)(P) + sb0 + 8192), 16, 0, 0); } while (0)
; #define LDA(dst, b, h) for (int m = 0; m < 4; ++m) for (int k = 0; k < 2; ++k) \
;         dst[m][k] = *reinterpret_cast<const bf16x8*>((char*)SA(b, h) + lds_byte(wr * 64 + m * 16 + fr, k * 32 + fq * 8))
; #define LDB(dst, b, h) for (int n = 0; n < 2; ++n) for (int k = 0; k < 2; ++k) \
;         dst[n][k] = *reinterpret_cast<const bf16x8*>((char*)SB(b, h) + lds_byte(wc * 32 + n * 16 + fr, k * 32 + fq * 8))
; #define MMA(ai, bj, At_, Bt_) do { __builtin_amdgcn_s_setprio(1); \
;         for (int m = 0; m < 4; ++m) for (int n = 0; n < 2; ++n) for (int k = 0; k < 2; ++k) \
;             acc[ai][bj][m][n] = __builtin_amdgcn_mfma_f32_16x16x32_bf16(At_[m][k], Bt_[n][k], acc[ai][bj][m][n], 0, 0, 0); \
;         __builtin_amdgcn_s_setprio(0); } while (0)
; #define WAIT_V(n) asm volatile("s_waitcnt vmcnt(" #n ")" ::: "memory")
; #define WAIT_L(n) asm volatile("s_waitcnt lgkmcnt(" #n ")" ::: "memory")
; #define BAR __builtin_amdgcn_s_barrier()
; #define SCHED __builtin_amdgcn_sched_barrier(0)
; template <int EPI, int K, int LNI = -1>
; DI void ph_gemm(const Params& p, const bf16_t* __restrict__ A, const bf16_t* __restrict__ Bt, int N, float* s_aux) {
;     ...
;     f32x4 acc[2][2][4][2] = {};
;     ...
;         for (int t = 0; t < nt; t += 2) {
;             const bool last = (t == nt - 2);
;             const bf16_t* a1 = cA + (size_t)(t + 1) * kstep;
;             const bf16_t* a2 = last ? nA : cA + (size_t)(t + 2) * kstep; const bf16_t* b2 = last ? nB : cB + (size_t)(t + 2) * kstep;
;             const bf16_t* a3 = a2 + kstep; const bf16_t* b3 = b2 + kstep;
;             LDB(B0, 0, 0); LDB(B1, 0, 1); SCHED; LDA(At, 0, 0); STAGE(SA(1, 1), a1 + hstep);
;             WAIT_V(8); WAIT_L(0); BAR; MMA(0, 0, At, B0); MMA(0, 1, At, B1); BAR; SCHED;
;             LDA(At, 0, 1); STAGE(SB(0, 0), b2); STAGE(SB(0, 1), b2 + hstep); STAGE(SA(0, 0), a2);
.LBB0_136:
	s_ashr_i32 s53, s52, 31
	s_lshl_b64 s[66:67], s[52:53], 19
	s_add_u32 s7, s40, s66
	s_addc_u32 s13, s41, s67
	s_ashr_i32 s61, s60, 31
	s_lshl_b64 s[70:71], s[60:61], 19
	s_add_u32 s16, s56, s70
	s_addc_u32 s17, s57, s71
	s_add_u32 s18, s56, s8
	s_addc_u32 s19, s57, s9
	s_add_u32 s20, s35, s10
	v_lshl_add_u64 v[138:139], v[134:135], 0, s[8:9]
	v_lshl_add_u64 v[140:141], v[136:137], 0, s[8:9]
	s_addc_u32 s21, s79, s11
	s_mov_b32 s22, -2
	s_mov_b64 s[8:9], 0
	ds_read_b128 v[142:145], v164
	ds_read_b128 v[178:181], v164 offset:1024
	ds_read_b128 v[182:185], v164 offset:2048
	ds_read_b128 v[186:189], v164 offset:3072
	ds_read_b128 v[190:193], v165
	ds_read_b128 v[194:197], v165 offset:1024
	ds_read_b128 v[198:201], v165 offset:2048
	ds_read_b128 v[202:205], v165 offset:3072
	s_add_u32 s10, s18, s8
	s_addc_u32 s11, s19, s9
	s_add_u32 s10, s10, 0xb840100
	s_addc_u32 s11, s11, 0
	s_add_u32 s23, s20, s8
	s_addc_u32 s24, s21, s9
	s_cmpk_eq_i32 s8, 0x700
	s_cselect_b32 s15, s13, s11
	s_cselect_b32 s14, s7, s10
	s_cselect_b32 s11, s17, s24
	s_cselect_b32 s10, s16, s23
	v_readfirstlane_b32 s23, v170
	v_lshl_add_u64 v[146:147], v[138:139], 0, s[8:9]
	s_mov_b32 m0, s23
	v_readfirstlane_b32 s23, v171
	ds_read_b128 v[206:209], v166
	ds_read_b128 v[212:215], v166 offset:1024
	ds_read_b128 v[216:219], v167
	ds_read_b128 v[220:223], v167 offset:1024
	ds_read_b128 v[224:227], v168
	ds_read_b128 v[228:231], v168 offset:1024
	ds_read_b128 v[232:235], v169
	ds_read_b128 v[236:239], v169 offset:1024
	global_load_lds_dwordx4 v[146:147], off
	v_lshl_add_u64 v[146:147], v[140:141], 0, s[8:9]
	s_mov_b32 m0, s23
	s_nop 0
	global_load_lds_dwordx4 v[146:147], off
	s_waitcnt vmcnt(8)
	s_waitcnt lgkmcnt(0)
	s_barrier
	s_setprio 1
	s_waitcnt lgkmcnt(0)
	v_mfma_f32_16x16x32_bf16 v[124:127], v[206:209], v[142:145], 0
	v_mfma_f32_16x16x32_bf16 v[120:123], v[206:209], v[182:185], 0
	v_mfma_f32_16x16x32_bf16 v[108:111], v[216:219], v[142:145], 0
	v_mfma_f32_16x16x32_bf16 v[104:107], v[216:219], v[182:185], 0
	v_mfma_f32_16x16x32_bf16 v[92:95], v[224:227], v[142:145], 0
	v_mfma_f32_16x16x32_bf16 v[88:91], v[224:227], v[182:185], 0
	v_mfma_f32_16x16x32_bf16 v[76:79], v[232:235], v[142:145], 0
	v_mfma_f32_16x16x32_bf16 v[72:75], v[232:235], v[182:185], 0
	v_mfma_f32_16x16x32_bf16 v[124:127], v[212:215], v[178:181], v[124:127]
	v_mfma_f32_16x16x32_bf16 v[120:123], v[212:215], v[186:189], v[120:123]
	v_mfma_f32_16x16x32_bf16 v[108:111], v[220:223], v[178:181], v[108:111]
	v_mfma_f32_16x16x32_bf16 v[104:107], v[220:223], v[186:189], v[104:107]
	v_mfma_f32_16x16x32_bf16 v[92:95], v[228:231], v[178:181], v[92:95]
	v_mfma_f32_16x16x32_bf16 v[88:91], v[228:231], v[186:189], v[88:91]
	v_mfma_f32_16x16x32_bf16 v[76:79], v[236:239], v[178:181], v[76:79]
	v_mfma_f32_16x16x32_bf16 v[72:75], v[236:239], v[186:189], v[72:75]
	s_setprio 0
	s_setprio 1
	v_mfma_f32_16x16x32_bf16 v[116:119], v[206:209], v[190:193], 0
	v_mfma_f32_16x16x32_bf16 v[112:115], v[206:209], v[198:201], 0
	v_mfma_f32_16x16x32_bf16 v[100:103], v[216:219], v[190:193], 0
	v_mfma_f32_16x16x32_bf16 v[96:99], v[216:219], v[198:201], 0
	v_mfma_f32_16x16x32_bf16 v[84:87], v[224:227], v[190:193], 0
	v_mfma_f32_16x16x32_bf16 v[80:83], v[224:227], v[198:201], 0
	v_mfma_f32_16x16x32_bf16 v[68:71], v[232:235], v[190:193], 0
	v_mfma_f32_16x16x32_bf16 v[64:67], v[232:235], v[198:201], 0
	v_mfma_f32_16x16x32_bf16 v[116:119], v[212:215], v[194:197], v[116:119]
	v_mfma_f32_16x16x32_bf16 v[112:115], v[212:215], v[202:205], v[112:115]
	v_mfma_f32_16x16x32_bf16 v[100:103], v[220:223], v[194:197], v[100:103]
	v_mfma_f32_16x16x32_bf16 v[96:99], v[220:223], v[202:205], v[96:99]
	v_mfma_f32_16x16x32_bf16 v[84:87], v[228:231], v[194:197], v[84:87]
	v_mfma_f32_16x16x32_bf16 v[80:83], v[228:231], v[202:205], v[80:83]
	v_mfma_f32_16x16x32_bf16 v[68:71], v[236:239], v[194:197], v[68:71]
	v_mfma_f32_16x16x32_bf16 v[64:67], v[236:239], v[202:205], v[64:67]
	s_setprio 0
	s_barrier
	v_readfirstlane_b32 s23, v148
	v_lshl_add_u64 v[146:147], s[10:11], 0, v[128:129]
	s_mov_b32 m0, s23
	v_readfirstlane_b32 s23, v149
	s_add_u32 s24, s10, 0x40000
	ds_read_b128 v[206:209], v166 offset:16384
	ds_read_b128 v[212:215], v166 offset:17408
	ds_read_b128 v[216:219], v167 offset:16384
	ds_read_b128 v[220:223], v167 offset:17408
	ds_read_b128 v[224:227], v168 offset:16384
	ds_read_b128 v[228:231], v168 offset:17408
	ds_read_b128 v[232:235], v169 offset:16384
	ds_read_b128 v[236:239], v169 offset:17408
	global_load_lds_dwordx4 v[146:147], off
	v_lshl_add_u64 v[240:241], s[10:11], 0, v[130:131]
	s_mov_b32 m0, s23
	s_addc_u32 s25, s11, 0
	v_readfirstlane_b32 s23, v150
	global_load_lds_dwordx4 v[240:241], off
	v_lshl_add_u64 v[242:243], s[24:25], 0, v[128:129]
	s_mov_b32 m0, s23
	v_readfirstlane_b32 s23, v151
	global_load_lds_dwordx4 v[242:243], off
	v_lshl_add_u64 v[242:243], s[24:25], 0, v[130:131]
	s_mov_b32 m0, s23
	v_readfirstlane_b32 s23, v152
	global_load_lds_dwordx4 v[242:243], off
	v_lshl_add_u64 v[242:243], s[14:15], 0, v[128:129]
	s_mov_b32 m0, s23
	v_readfirstlane_b32 s23, v153
	global_load_lds_dwordx4 v[242:243], off
	v_lshl_add_u64 v[244:245], s[14:15], 0, v[130:131]
	s_mov_b32 m0, s23
	s_nop 0
	global_load_lds_dwordx4 v[244:245], off
	s_waitcnt vmcnt(8)
	s_waitcnt lgkmcnt(0)
	s_barrier
; #define STAGE(P, g) do { const char* g_ = (const char*)(g); \
;         __builtin_amdgcn_global_load_lds((const unsigned*)(g_ + so0), (lds_u32*)((lds_u8*)(P) + sb0), 16, 0, 0); \
;         __builtin_amdgcn_global_load_lds((const unsigned*)(g_ + so1), (lds_u32*)((lds_u8*)(P) + sb0 + 8192), 16, 0, 0); } while (0)
; #define LDA(dst, b, h) for (int m = 0; m < 4; ++m) for (int k = 0; k < 2; ++k) \
;         dst[m][k] = *reinterpret_cast<const bf16x8*>((char*)SA(b, h) + lds_byte(wr * 64 + m * 16 + fr, k * 32 + fq * 8))
; #define LDB(dst, b, h) for (int n = 0; n < 2; ++n) for (int k = 0; k < 2; ++k) \
;         dst[n][k] = *reinterpret_cast<const bf16x8*>((char*)SB(b, h) + lds_byte(wc * 32 + n * 16 + fr, k * 32 + fq * 8))
; #define MMA(ai, bj, At_, Bt_) do { __builtin_amdgcn_s_setprio(1); \
;         for (int m = 0; m < 4; ++m) for (int n = 0; n < 2; ++n) for (int k = 0; k < 2; ++k) \
;             acc[ai][bj][m][n] = __builtin_amdgcn_mfma_f32_16x16x32_bf16(At_[m][k], Bt_[n][k], acc[ai][bj][m][n], 0, 0, 0); \
;         __builtin_amdgcn_s_setprio(0); } while (0)
; #define WAIT_V(n) asm volatile("s_waitcnt vmcnt(" #n ")" ::: "memory")
; #define WAIT_L(n) asm volatile("s_waitcnt lgkmcnt(" #n ")" ::: "memory")
; #define BAR __builtin_amdgcn_s_barrier()
; #define SCHED __builtin_amdgcn_sched_barrier(0)
; template <int EPI, int K, int LNI = -1>
; DI void ph_gemm(const Params& p, const bf16_t* __restrict__ A, const bf16_t* __restrict__ Bt, int N, float* s_aux) {
;     ...
;             WAIT_V(8); WAIT_L(0); BAR; MMA(1, 0, At, B0); MMA(1, 1, At, B1); BAR; SCHED;
;             LDB(B0, 1, 0); LDB(B1, 1, 1); SCHED; LDA(At, 1, 0); STAGE(SA(0, 1), a2 + hstep);
;             WAIT_V(8); WAIT_L(0); BAR; MMA(0, 0, At, B0); MMA(0, 1, At, B1); BAR; SCHED;
	s_setprio 1
	s_waitcnt lgkmcnt(0)
	v_mfma_f32_16x16x32_bf16 v[60:63], v[206:209], v[142:145], 0
	v_mfma_f32_16x16x32_bf16 v[56:59], v[206:209], v[182:185], 0
	v_mfma_f32_16x16x32_bf16 v[44:47], v[216:219], v[142:145], 0
	v_mfma_f32_16x16x32_bf16 v[40:43], v[216:219], v[182:185], 0
	v_mfma_f32_16x16x32_bf16 v[28:31], v[224:227], v[142:145], 0
	v_mfma_f32_16x16x32_bf16 v[24:27], v[224:227], v[182:185], 0
	v_mfma_f32_16x16x32_bf16 v[12:15], v[232:235], v[142:145], 0
	v_mfma_f32_16x16x32_bf16 v[8:11], v[232:235], v[182:185], 0
	v_mfma_f32_16x16x32_bf16 v[60:63], v[212:215], v[178:181], v[60:63]
	v_mfma_f32_16x16x32_bf16 v[56:59], v[212:215], v[186:189], v[56:59]
	v_mfma_f32_16x16x32_bf16 v[44:47], v[220:223], v[178:181], v[44:47]
	v_mfma_f32_16x16x32_bf16 v[40:43], v[220:223], v[186:189], v[40:43]
	v_mfma_f32_16x16x32_bf16 v[28:31], v[228:231], v[178:181], v[28:31]
	v_mfma_f32_16x16x32_bf16 v[24:27], v[228:231], v[186:189], v[24:27]
	v_mfma_f32_16x16x32_bf16 v[12:15], v[236:239], v[178:181], v[12:15]
	v_mfma_f32_16x16x32_bf16 v[8:11], v[236:239], v[186:189], v[8:11]
	s_setprio 0
	s_setprio 1
	v_mfma_f32_16x16x32_bf16 v[52:55], v[206:209], v[190:193], 0
	v_mfma_f32_16x16x32_bf16 v[48:51], v[206:209], v[198:201], 0
	v_mfma_f32_16x16x32_bf16 v[36:39], v[216:219], v[190:193], 0
	v_mfma_f32_16x16x32_bf16 v[32:35], v[216:219], v[198:201], 0
	v_mfma_f32_16x16x32_bf16 v[20:23], v[224:227], v[190:193], 0
	v_mfma_f32_16x16x32_bf16 v[16:19], v[224:227], v[198:201], 0
	v_mfma_f32_16x16x32_bf16 v[4:7], v[232:235], v[190:193], 0
	v_mfma_f32_16x16x32_bf16 v[0:3], v[232:235], v[198:201], 0
	v_mfma_f32_16x16x32_bf16 v[52:55], v[212:215], v[194:197], v[52:55]
	v_mfma_f32_16x16x32_bf16 v[48:51], v[212:215], v[202:205], v[48:51]
	v_mfma_f32_16x16x32_bf16 v[36:39], v[220:223], v[194:197], v[36:39]
	v_mfma_f32_16x16x32_bf16 v[32:35], v[220:223], v[202:205], v[32:35]
	v_mfma_f32_16x16x32_bf16 v[20:23], v[228:231], v[194:197], v[20:23]
	v_mfma_f32_16x16x32_bf16 v[16:19], v[228:231], v[202:205], v[16:19]
	v_mfma_f32_16x16x32_bf16 v[4:7], v[236:239], v[194:197], v[4:7]
	v_mfma_f32_16x16x32_bf16 v[0:3], v[236:239], v[202:205], v[0:3]
	s_setprio 0
	s_barrier
	ds_read_b128 v[142:145], v172
	ds_read_b128 v[178:181], v172 offset:1024
	ds_read_b128 v[182:185], v172 offset:2048
	ds_read_b128 v[186:189], v172 offset:3072
	ds_read_b128 v[190:193], v173
	ds_read_b128 v[194:197], v173 offset:1024
	ds_read_b128 v[198:201], v173 offset:2048
	ds_read_b128 v[202:205], v173 offset:3072
	s_add_u32 s14, s14, 0x40000
	s_addc_u32 s15, s15, 0
	v_readfirstlane_b32 s23, v154
	v_lshl_add_u64 v[246:247], s[14:15], 0, v[128:129]
	s_mov_b32 m0, s23
	ds_read_b128 v[206:209], v166 offset:32768
	ds_read_b128 v[212:215], v166 offset:33792
	ds_read_b128 v[216:219], v167 offset:32768
	ds_read_b128 v[220:223], v167 offset:33792
	ds_read_b128 v[224:227], v168 offset:32768
	ds_read_b128 v[228:231], v168 offset:33792
	ds_read_b128 v[232:235], v169 offset:32768
	ds_read_b128 v[236:239], v169 offset:33792
	global_load_lds_dwordx4 v[246:247], off
	v_lshl_add_u64 v[246:247], s[14:15], 0, v[130:131]
	v_readfirstlane_b32 s14, v155
	s_mov_b32 m0, s14
	s_nop 0
	global_load_lds_dwordx4 v[246:247], off
	s_waitcnt vmcnt(8)
	s_waitcnt lgkmcnt(0)
	s_barrier
	s_setprio 1
	s_waitcnt lgkmcnt(0)
	v_mfma_f32_16x16x32_bf16 v[124:127], v[206:209], v[142:145], v[124:127]
	v_mfma_f32_16x16x32_bf16 v[120:123], v[206:209], v[182:185], v[120:123]
	v_mfma_f32_16x16x32_bf16 v[108:111], v[216:219], v[142:145], v[108:111]
	v_mfma_f32_16x16x32_bf16 v[104:107], v[216:219], v[182:185], v[104:107]
	v_mfma_f32_16x16x32_bf16 v[92:95], v[224:227], v[142:145], v[92:95]
	v_mfma_f32_16x16x32_bf16 v[88:91], v[224:227], v[182:185], v[88:91]
	v_mfma_f32_16x16x32_bf16 v[76:79], v[232:235], v[142:145], v[76:79]
	v_mfma_f32_16x16x32_bf16 v[72:75], v[232:235], v[182:185], v[72:75]
	v_mfma_f32_16x16x32_bf16 v[124:127], v[212:215], v[178:181], v[124:127]
	v_mfma_f32_16x16x32_bf16 v[120:123], v[212:215], v[186:189], v[120:123]
	v_mfma_f32_16x16x32_bf16 v[108:111], v[220:223], v[178:181], v[108:111]
	v_mfma_f32_16x16x32_bf16 v[104:107], v[220:223], v[186:189], v[104:107]
	v_mfma_f32_16x16x32_bf16 v[92:95], v[228:231], v[178:181], v[92:95]
	v_mfma_f32_16x16x32_bf16 v[88:91], v[228:231], v[186:189], v[88:91]
	v_mfma_f32_16x16x32_bf16 v[76:79], v[236:239], v[178:181], v[76:79]
	v_mfma_f32_16x16x32_bf16 v[72:75], v[236:239], v[186:189], v[72:75]
	s_setprio 0
	s_setprio 1
	v_mfma_f32_16x16x32_bf16 v[116:119], v[206:209], v[190:193], v[116:119]
	v_mfma_f32_16x16x32_bf16 v[112:115], v[206:209], v[198:201], v[112:115]
	v_mfma_f32_16x16x32_bf16 v[100:103], v[216:219], v[190:193], v[100:103]
	v_mfma_f32_16x16x32_bf16 v[96:99], v[216:219], v[198:201], v[96:99]
	v_mfma_f32_16x16x32_bf16 v[84:87], v[224:227], v[190:193], v[84:87]
	v_mfma_f32_16x16x32_bf16 v[80:83], v[224:227], v[198:201], v[80:83]
	v_mfma_f32_16x16x32_bf16 v[68:71], v[232:235], v[190:193], v[68:71]
	v_mfma_f32_16x16x32_bf16 v[64:67], v[232:235], v[198:201], v[64:67]
	v_mfma_f32_16x16x32_bf16 v[116:119], v[212:215], v[194:197], v[116:119]
	v_mfma_f32_16x16x32_bf16 v[112:115], v[212:215], v[202:205], v[112:115]
	v_mfma_f32_16x16x32_bf16 v[100:103], v[220:223], v[194:197], v[100:103]
	v_mfma_f32_16x16x32_bf16 v[96:99], v[220:223], v[202:205], v[96:99]
	v_mfma_f32_16x16x32_bf16 v[84:87], v[228:231], v[194:197], v[84:87]
	v_mfma_f32_16x16x32_bf16 v[80:83], v[228:231], v[202:205], v[80:83]
	v_mfma_f32_16x16x32_bf16 v[68:71], v[236:239], v[194:197], v[68:71]
	v_mfma_f32_16x16x32_bf16 v[64:67], v[236:239], v[202:205], v[64:67]
	s_setprio 0
	s_barrier
; #define STAGE(P, g) do { const char* g_ = (const char*)(g); \
;         __builtin_amdgcn_global_load_lds((const unsigned*)(g_ + so0), (lds_u32*)((lds_u8*)(P) + sb0), 16, 0, 0); \
;         __builtin_amdgcn_global_load_lds((const unsigned*)(g_ + so1), (lds_u32*)((lds_u8*)(P) + sb0 + 8192), 16, 0, 0); } while (0)
; #define LDA(dst, b, h) for (int m = 0; m < 4; ++m) for (int k = 0; k < 2; ++k) \
;         dst[m][k] = *reinterpret_cast<const bf16x8*>((char*)SA(b, h) + lds_byte(wr * 64 + m * 16 + fr, k * 32 + fq * 8))
; #define MMA(ai, bj, At_, Bt_) do { __builtin_amdgcn_s_setprio(1); \
;         for (int m = 0; m < 4; ++m) for (int n = 0; n < 2; ++n) for (int k = 0; k < 2; ++k) \
;             acc[ai][bj][m][n] = __builtin_amdgcn_mfma_f32_16x16x32_bf16(At_[m][k], Bt_[n][k], acc[ai][bj][m][n], 0, 0, 0); \
;         __builtin_amdgcn_s_setprio(0); } while (0)
; #define WAIT_V(n) asm volatile("s_waitcnt vmcnt(" #n ")" ::: "memory")
; #define WAIT_L(n) asm volatile("s_waitcnt lgkmcnt(" #n ")" ::: "memory")
; #define BAR __builtin_amdgcn_s_barrier()
; #define SCHED __builtin_amdgcn_sched_barrier(0)
; template <int EPI, int K, int LNI = -1>
; DI void ph_gemm(const Params& p, const bf16_t* __restrict__ A, const bf16_t* __restrict__ Bt, int N, float* s_aux) {
;     ...
;         for (int t = 0; t < nt; t += 2) {
;     ...
;             LDA(At, 1, 1); STAGE(SB(1, 0), b3); STAGE(SB(1, 1), b3 + hstep); STAGE(SA(1, 0), a3);
;             WAIT_V(8); WAIT_L(0); BAR; MMA(1, 0, At, B0); MMA(1, 1, At, B1); BAR; SCHED;
	v_readfirstlane_b32 s14, v156
	v_lshl_add_u64 v[146:147], v[146:147], 0, s[42:43]
	s_mov_b32 m0, s14
	v_readfirstlane_b32 s14, v157
	s_add_u32 s10, s10, 0x40080
	ds_read_b128 v[206:209], v166 offset:49152
	ds_read_b128 v[212:215], v166 offset:50176
	ds_read_b128 v[216:219], v167 offset:49152
	ds_read_b128 v[220:223], v167 offset:50176
	ds_read_b128 v[224:227], v168 offset:49152
	ds_read_b128 v[228:231], v168 offset:50176
	ds_read_b128 v[232:235], v169 offset:49152
	ds_read_b128 v[236:239], v169 offset:50176
	global_load_lds_dwordx4 v[146:147], off
	v_lshl_add_u64 v[146:147], v[240:241], 0, s[42:43]
	s_mov_b32 m0, s14
	s_addc_u32 s11, s11, 0
	v_readfirstlane_b32 s14, v160
	global_load_lds_dwordx4 v[146:147], off
	v_lshl_add_u64 v[146:147], s[10:11], 0, v[128:129]
	s_mov_b32 m0, s14
	s_nop 0
	global_load_lds_dwordx4 v[146:147], off
	v_lshl_add_u64 v[146:147], s[10:11], 0, v[130:131]
	v_readfirstlane_b32 s10, v161
	s_mov_b32 m0, s10
	v_readfirstlane_b32 s10, v158
	global_load_lds_dwordx4 v[146:147], off
	v_lshl_add_u64 v[146:147], v[242:243], 0, s[42:43]
	s_mov_b32 m0, s10
	v_readfirstlane_b32 s10, v159
	global_load_lds_dwordx4 v[146:147], off
	v_lshl_add_u64 v[146:147], v[244:245], 0, s[42:43]
	s_mov_b32 m0, s10
	s_nop 0
	global_load_lds_dwordx4 v[146:147], off
	s_waitcnt vmcnt(8)
	s_waitcnt lgkmcnt(0)
	s_barrier
	s_setprio 1
	s_waitcnt lgkmcnt(0)
	v_mfma_f32_16x16x32_bf16 v[60:63], v[206:209], v[142:145], v[60:63]
	v_mfma_f32_16x16x32_bf16 v[56:59], v[206:209], v[182:185], v[56:59]
	v_mfma_f32_16x16x32_bf16 v[44:47], v[216:219], v[142:145], v[44:47]
	v_mfma_f32_16x16x32_bf16 v[40:43], v[216:219], v[182:185], v[40:43]
	v_mfma_f32_16x16x32_bf16 v[28:31], v[224:227], v[142:145], v[28:31]
	v_mfma_f32_16x16x32_bf16 v[24:27], v[224:227], v[182:185], v[24:27]
	v_mfma_f32_16x16x32_bf16 v[12:15], v[232:235], v[142:145], v[12:15]
	v_mfma_f32_16x16x32_bf16 v[8:11], v[232:235], v[182:185], v[8:11]
	v_mfma_f32_16x16x32_bf16 v[60:63], v[212:215], v[178:181], v[60:63]
	v_mfma_f32_16x16x32_bf16 v[56:59], v[212:215], v[186:189], v[56:59]
	v_mfma_f32_16x16x32_bf16 v[44:47], v[220:223], v[178:181], v[44:47]
	v_mfma_f32_16x16x32_bf16 v[40:43], v[220:223], v[186:189], v[40:43]
	v_mfma_f32_16x16x32_bf16 v[28:31], v[228:231], v[178:181], v[28:31]
	v_mfma_f32_16x16x32_bf16 v[24:27], v[228:231], v[186:189], v[24:27]
	v_mfma_f32_16x16x32_bf16 v[12:15], v[236:239], v[178:181], v[12:15]
	v_mfma_f32_16x16x32_bf16 v[8:11], v[236:239], v[186:189], v[8:11]
	s_setprio 0
	s_setprio 1
	v_mfma_f32_16x16x32_bf16 v[52:55], v[206:209], v[190:193], v[52:55]
	v_mfma_f32_16x16x32_bf16 v[48:51], v[206:209], v[198:201], v[48:51]
	v_mfma_f32_16x16x32_bf16 v[36:39], v[216:219], v[190:193], v[36:39]
	v_mfma_f32_16x16x32_bf16 v[32:35], v[216:219], v[198:201], v[32:35]
	v_mfma_f32_16x16x32_bf16 v[20:23], v[224:227], v[190:193], v[20:23]
	v_mfma_f32_16x16x32_bf16 v[16:19], v[224:227], v[198:201], v[16:19]
	v_mfma_f32_16x16x32_bf16 v[4:7], v[232:235], v[190:193], v[4:7]
	v_mfma_f32_16x16x32_bf16 v[0:3], v[232:235], v[198:201], v[0:3]
	v_mfma_f32_16x16x32_bf16 v[52:55], v[212:215], v[194:197], v[52:55]
	v_mfma_f32_16x16x32_bf16 v[48:51], v[212:215], v[202:205], v[48:51]
	v_mfma_f32_16x16x32_bf16 v[36:39], v[220:223], v[194:197], v[36:39]
	v_mfma_f32_16x16x32_bf16 v[32:35], v[220:223], v[202:205], v[32:35]
	v_mfma_f32_16x16x32_bf16 v[20:23], v[228:231], v[194:197], v[20:23]
	v_mfma_f32_16x16x32_bf16 v[16:19], v[228:231], v[202:205], v[16:19]
	v_mfma_f32_16x16x32_bf16 v[4:7], v[236:239], v[194:197], v[4:7]
	v_mfma_f32_16x16x32_bf16 v[0:3], v[236:239], v[202:205], v[0:3]
	s_setprio 0
	s_barrier
	s_add_i32 s22, s22, 2
	s_add_u32 s8, s8, 0x100
	s_addc_u32 s9, s9, 0
	s_cmp_gt_u32 s22, 13

; #define STAGE(P, g) do { const char* g_ = (const char*)(g); \
;         __builtin_amdgcn_global_load_lds((const unsigned*)(g_ + so0), (lds_u32*)((lds_u8*)(P) + sb0), 16, 0, 0); \
;         __builtin_amdgcn_global_load_lds((const unsigned*)(g_ + so1), (lds_u32*)((lds_u8*)(P) + sb0 + 8192), 16, 0, 0); } while (0)
; #define LDA(dst, b, h) for (int m = 0; m < 4; ++m) for (int k = 0; k < 2; ++k) \
;         dst[m][k] = *reinterpret_cast<const bf16x8*>((char*)SA(b, h) + lds_byte(wr * 64 + m * 16 + fr, k * 32 + fq * 8))
; #define LDB(dst, b, h) for (int n = 0; n < 2; ++n) for (int k = 0; k < 2; ++k) \
;         dst[n][k] = *reinterpret_cast<const bf16x8*>((char*)SB(b, h) + lds_byte(wc * 32 + n * 16 + fr, k * 32 + fq * 8))
; #define MMA(ai, bj, At_, Bt_) do { __builtin_amdgcn_s_setprio(1); \
;         for (int m = 0; m < 4; ++m) for (int n = 0; n < 2; ++n) for (int k = 0; k < 2; ++k) \
;             acc[ai][bj][m][n] = __builtin_amdgcn_mfma_f32_16x16x32_bf16(At_[m][k], Bt_[n][k], acc[ai][bj][m][n], 0, 0, 0); \
;         __builtin_amdgcn_s_setprio(0); } while (0)
; #define WAIT_V(n) asm volatile("s_waitcnt vmcnt(" #n ")" ::: "memory")
; #define WAIT_L(n) asm volatile("s_waitcnt lgkmcnt(" #n ")" ::: "memory")
; #define BAR __builtin_amdgcn_s_barrier()
; #define SCHED __builtin_amdgcn_sched_barrier(0)
; template <int EPI, int K, int LNI = -1>
; DI void ph_gemm(const Params& p, const bf16_t* __restrict__ A, const bf16_t* __restrict__ Bt, int N, float* s_aux) {
;     ...
;     f32x4 acc[2][2][4][2] = {};
;     ...
;         for (int t = 0; t < nt; t += 2) {
;             const bool last = (t == nt - 2);
;             const bf16_t* a1 = cA + (size_t)(t + 1) * kstep;
;             const bf16_t* a2 = last ? nA : cA + (size_t)(t + 2) * kstep; const bf16_t* b2 = last ? nB : cB + (size_t)(t + 2) * kstep;
;             const bf16_t* a3 = a2 + kstep; const bf16_t* b3 = b2 + kstep;
;             LDB(B0, 0, 0); LDB(B1, 0, 1); SCHED; LDA(At, 0, 0); STAGE(SA(1, 1), a1 + hstep);
;             WAIT_V(8); WAIT_L(0); BAR; MMA(0, 0, At, B0); MMA(0, 1, At, B1); BAR; SCHED;
;             LDA(At, 0, 1); STAGE(SB(0, 0), b2); STAGE(SB(0, 1), b2 + hstep); STAGE(SA(0, 0), a2);
.LBB0_793:
	s_ashr_i32 s13, s12, 31
	s_lshl_b64 s[18:19], s[12:13], 19
	s_add_u32 s13, s40, s18
	s_addc_u32 s42, s41, s19
	s_ashr_i32 s15, s14, 31
	s_lshl_b64 s[20:21], s[14:15], 19
	s_add_u32 s15, s8, s20
	s_addc_u32 s43, s9, s21
	s_add_u32 s48, s56, s26
	s_addc_u32 s49, s57, s27
	s_add_u32 s50, s25, s28
	v_lshl_add_u64 v[136:137], v[132:133], 0, s[26:27]
	v_lshl_add_u64 v[138:139], v[134:135], 0, s[26:27]
	s_addc_u32 s51, s35, s29
	s_mov_b32 s52, -2
	s_mov_b64 s[26:27], 0
	ds_read_b128 v[168:171], v158
	ds_read_b128 v[172:175], v158 offset:1024
	ds_read_b128 v[176:179], v158 offset:2048
	ds_read_b128 v[180:183], v158 offset:3072
	ds_read_b128 v[184:187], v159
	ds_read_b128 v[188:191], v159 offset:1024
	ds_read_b128 v[192:195], v159 offset:2048
	ds_read_b128 v[196:199], v159 offset:3072
	s_add_u32 s28, s48, s26
	s_addc_u32 s29, s49, s27
	s_add_u32 s28, s28, 0xb840100
	s_addc_u32 s29, s29, 0
	s_add_u32 s53, s50, s26
	s_addc_u32 s60, s51, s27
	s_cmpk_eq_i32 s26, 0x700
	s_cselect_b32 s45, s42, s29
	s_cselect_b32 s44, s13, s28
	s_cselect_b32 s29, s43, s60
	s_cselect_b32 s28, s15, s53
	v_readfirstlane_b32 s53, v164
	v_lshl_add_u64 v[140:141], v[136:137], 0, s[26:27]
	s_mov_b32 m0, s53
	v_readfirstlane_b32 s53, v165
	ds_read_b128 v[200:203], v160
	ds_read_b128 v[204:207], v160 offset:1024
	ds_read_b128 v[212:215], v161
	ds_read_b128 v[216:219], v161 offset:1024
	ds_read_b128 v[220:223], v162
	ds_read_b128 v[224:227], v162 offset:1024
	ds_read_b128 v[228:231], v163
	ds_read_b128 v[232:235], v163 offset:1024
	global_load_lds_dwordx4 v[140:141], off
	v_lshl_add_u64 v[140:141], v[138:139], 0, s[26:27]
	s_mov_b32 m0, s53
	s_nop 0
	global_load_lds_dwordx4 v[140:141], off
	s_waitcnt vmcnt(8)
	s_waitcnt lgkmcnt(0)
	s_barrier
	s_setprio 1
	s_waitcnt lgkmcnt(0)
	v_mfma_f32_16x16x32_bf16 v[124:127], v[200:203], v[168:171], 0
	v_mfma_f32_16x16x32_bf16 v[120:123], v[200:203], v[176:179], 0
	v_mfma_f32_16x16x32_bf16 v[116:119], v[212:215], v[168:171], 0
	v_mfma_f32_16x16x32_bf16 v[108:111], v[212:215], v[176:179], 0
	v_mfma_f32_16x16x32_bf16 v[100:103], v[220:223], v[168:171], 0
	v_mfma_f32_16x16x32_bf16 v[88:91], v[220:223], v[176:179], 0
	v_mfma_f32_16x16x32_bf16 v[84:87], v[228:231], v[168:171], 0
	v_mfma_f32_16x16x32_bf16 v[76:79], v[228:231], v[176:179], 0
	v_mfma_f32_16x16x32_bf16 v[124:127], v[204:207], v[172:175], v[124:127]
	v_mfma_f32_16x16x32_bf16 v[120:123], v[204:207], v[180:183], v[120:123]
	v_mfma_f32_16x16x32_bf16 v[116:119], v[216:219], v[172:175], v[116:119]
	v_mfma_f32_16x16x32_bf16 v[108:111], v[216:219], v[180:183], v[108:111]
	v_mfma_f32_16x16x32_bf16 v[100:103], v[224:227], v[172:175], v[100:103]
	v_mfma_f32_16x16x32_bf16 v[88:91], v[224:227], v[180:183], v[88:91]
	v_mfma_f32_16x16x32_bf16 v[84:87], v[232:235], v[172:175], v[84:87]
	v_mfma_f32_16x16x32_bf16 v[76:79], v[232:235], v[180:183], v[76:79]
	s_setprio 0
	s_setprio 1
	v_mfma_f32_16x16x32_bf16 v[112:115], v[200:203], v[184:187], 0
	v_mfma_f32_16x16x32_bf16 v[104:107], v[200:203], v[192:195], 0
	v_mfma_f32_16x16x32_bf16 v[96:99], v[212:215], v[184:187], 0
	v_mfma_f32_16x16x32_bf16 v[92:95], v[212:215], v[192:195], 0
	v_mfma_f32_16x16x32_bf16 v[80:83], v[220:223], v[184:187], 0
	v_mfma_f32_16x16x32_bf16 v[72:75], v[220:223], v[192:195], 0
	v_mfma_f32_16x16x32_bf16 v[68:71], v[228:231], v[184:187], 0
	v_mfma_f32_16x16x32_bf16 v[64:67], v[228:231], v[192:195], 0
	v_mfma_f32_16x16x32_bf16 v[112:115], v[204:207], v[188:191], v[112:115]
	v_mfma_f32_16x16x32_bf16 v[104:107], v[204:207], v[196:199], v[104:107]
	v_mfma_f32_16x16x32_bf16 v[96:99], v[216:219], v[188:191], v[96:99]
	v_mfma_f32_16x16x32_bf16 v[92:95], v[216:219], v[196:199], v[92:95]
	v_mfma_f32_16x16x32_bf16 v[80:83], v[224:227], v[188:191], v[80:83]
	v_mfma_f32_16x16x32_bf16 v[72:75], v[224:227], v[196:199], v[72:75]
	v_mfma_f32_16x16x32_bf16 v[68:71], v[232:235], v[188:191], v[68:71]
	v_mfma_f32_16x16x32_bf16 v[64:67], v[232:235], v[196:199], v[64:67]
	s_setprio 0
	s_barrier
	v_readfirstlane_b32 s53, v142
	v_lshl_add_u64 v[140:141], s[28:29], 0, v[128:129]
	s_mov_b32 m0, s53
	v_readfirstlane_b32 s53, v143
	s_add_u32 s60, s28, 0x40000
	ds_read_b128 v[200:203], v160 offset:16384
	ds_read_b128 v[204:207], v160 offset:17408
	ds_read_b128 v[212:215], v161 offset:16384
	ds_read_b128 v[216:219], v161 offset:17408
	ds_read_b128 v[220:223], v162 offset:16384
	ds_read_b128 v[224:227], v162 offset:17408
	ds_read_b128 v[228:231], v163 offset:16384
	ds_read_b128 v[232:235], v163 offset:17408
	global_load_lds_dwordx4 v[140:141], off
	v_lshl_add_u64 v[208:209], s[28:29], 0, v[130:131]
	s_mov_b32 m0, s53
	s_addc_u32 s61, s29, 0
	v_readfirstlane_b32 s53, v144
	global_load_lds_dwordx4 v[208:209], off
	v_lshl_add_u64 v[236:237], s[60:61], 0, v[128:129]
	s_mov_b32 m0, s53
	v_readfirstlane_b32 s53, v145
	global_load_lds_dwordx4 v[236:237], off
	v_lshl_add_u64 v[236:237], s[60:61], 0, v[130:131]
	s_mov_b32 m0, s53
	v_readfirstlane_b32 s53, v146
	global_load_lds_dwordx4 v[236:237], off
	v_lshl_add_u64 v[236:237], s[44:45], 0, v[128:129]
	s_mov_b32 m0, s53
	v_readfirstlane_b32 s53, v147
	global_load_lds_dwordx4 v[236:237], off
	v_lshl_add_u64 v[238:239], s[44:45], 0, v[130:131]
	s_mov_b32 m0, s53
	s_nop 0
	global_load_lds_dwordx4 v[238:239], off
	s_waitcnt vmcnt(8)
	s_waitcnt lgkmcnt(0)
	s_barrier
; #define STAGE(P, g) do { const char* g_ = (const char*)(g); \
;         __builtin_amdgcn_global_load_lds((const unsigned*)(g_ + so0), (lds_u32*)((lds_u8*)(P) + sb0), 16, 0, 0); \
;         __builtin_amdgcn_global_load_lds((const unsigned*)(g_ + so1), (lds_u32*)((lds_u8*)(P) + sb0 + 8192), 16, 0, 0); } while (0)
; #define LDA(dst, b, h) for (int m = 0; m < 4; ++m) for (int k = 0; k < 2; ++k) \
;         dst[m][k] = *reinterpret_cast<const bf16x8*>((char*)SA(b, h) + lds_byte(wr * 64 + m * 16 + fr, k * 32 + fq * 8))
; #define LDB(dst, b, h) for (int n = 0; n < 2; ++n) for (int k = 0; k < 2; ++k) \
;         dst[n][k] = *reinterpret_cast<const bf16x8*>((char*)SB(b, h) + lds_byte(wc * 32 + n * 16 + fr, k * 32 + fq * 8))
; #define MMA(ai, bj, At_, Bt_) do { __builtin_amdgcn_s_setprio(1); \
;         for (int m = 0; m < 4; ++m) for (int n = 0; n < 2; ++n) for (int k = 0; k < 2; ++k) \
;             acc[ai][bj][m][n] = __builtin_amdgcn_mfma_f32_16x16x32_bf16(At_[m][k], Bt_[n][k], acc[ai][bj][m][n], 0, 0, 0); \
;         __builtin_amdgcn_s_setprio(0); } while (0)
; #define WAIT_V(n) asm volatile("s_waitcnt vmcnt(" #n ")" ::: "memory")
; #define WAIT_L(n) asm volatile("s_waitcnt lgkmcnt(" #n ")" ::: "memory")
; #define BAR __builtin_amdgcn_s_barrier()
; #define SCHED __builtin_amdgcn_sched_barrier(0)
; template <int EPI, int K, int LNI = -1>
; DI void ph_gemm(const Params& p, const bf16_t* __restrict__ A, const bf16_t* __restrict__ Bt, int N, float* s_aux) {
;     ...
;             WAIT_V(8); WAIT_L(0); BAR; MMA(1, 0, At, B0); MMA(1, 1, At, B1); BAR; SCHED;
;             LDB(B0, 1, 0); LDB(B1, 1, 1); SCHED; LDA(At, 1, 0); STAGE(SA(0, 1), a2 + hstep);
;             WAIT_V(8); WAIT_L(0); BAR; MMA(0, 0, At, B0); MMA(0, 1, At, B1); BAR; SCHED;
	s_setprio 1
	s_waitcnt lgkmcnt(0)
	v_mfma_f32_16x16x32_bf16 v[60:63], v[200:203], v[168:171], 0
	v_mfma_f32_16x16x32_bf16 v[56:59], v[200:203], v[176:179], 0
	v_mfma_f32_16x16x32_bf16 v[44:47], v[212:215], v[168:171], 0
	v_mfma_f32_16x16x32_bf16 v[40:43], v[212:215], v[176:179], 0
	v_mfma_f32_16x16x32_bf16 v[36:39], v[220:223], v[168:171], 0
	v_mfma_f32_16x16x32_bf16 v[28:31], v[220:223], v[176:179], 0
	v_mfma_f32_16x16x32_bf16 v[20:23], v[228:231], v[168:171], 0
	v_mfma_f32_16x16x32_bf16 v[12:15], v[228:231], v[176:179], 0
	v_mfma_f32_16x16x32_bf16 v[60:63], v[204:207], v[172:175], v[60:63]
	v_mfma_f32_16x16x32_bf16 v[56:59], v[204:207], v[180:183], v[56:59]
	v_mfma_f32_16x16x32_bf16 v[44:47], v[216:219], v[172:175], v[44:47]
	v_mfma_f32_16x16x32_bf16 v[40:43], v[216:219], v[180:183], v[40:43]
	v_mfma_f32_16x16x32_bf16 v[36:39], v[224:227], v[172:175], v[36:39]
	v_mfma_f32_16x16x32_bf16 v[28:31], v[224:227], v[180:183], v[28:31]
	v_mfma_f32_16x16x32_bf16 v[20:23], v[232:235], v[172:175], v[20:23]
	v_mfma_f32_16x16x32_bf16 v[12:15], v[232:235], v[180:183], v[12:15]
	s_setprio 0
	s_setprio 1
	v_mfma_f32_16x16x32_bf16 v[52:55], v[200:203], v[184:187], 0
	v_mfma_f32_16x16x32_bf16 v[48:51], v[200:203], v[192:195], 0
	v_mfma_f32_16x16x32_bf16 v[32:35], v[212:215], v[184:187], 0
	v_mfma_f32_16x16x32_bf16 v[24:27], v[212:215], v[192:195], 0
	v_mfma_f32_16x16x32_bf16 v[16:19], v[220:223], v[184:187], 0
	v_mfma_f32_16x16x32_bf16 v[8:11], v[220:223], v[192:195], 0
	v_mfma_f32_16x16x32_bf16 v[4:7], v[228:231], v[184:187], 0
	v_mfma_f32_16x16x32_bf16 v[0:3], v[228:231], v[192:195], 0
	v_mfma_f32_16x16x32_bf16 v[52:55], v[204:207], v[188:191], v[52:55]
	v_mfma_f32_16x16x32_bf16 v[48:51], v[204:207], v[196:199], v[48:51]
	v_mfma_f32_16x16x32_bf16 v[32:35], v[216:219], v[188:191], v[32:35]
	v_mfma_f32_16x16x32_bf16 v[24:27], v[216:219], v[196:199], v[24:27]
	v_mfma_f32_16x16x32_bf16 v[16:19], v[224:227], v[188:191], v[16:19]
	v_mfma_f32_16x16x32_bf16 v[8:11], v[224:227], v[196:199], v[8:11]
	v_mfma_f32_16x16x32_bf16 v[4:7], v[232:235], v[188:191], v[4:7]
	v_mfma_f32_16x16x32_bf16 v[0:3], v[232:235], v[196:199], v[0:3]
	s_setprio 0
	s_barrier
	ds_read_b128 v[168:171], v166
	ds_read_b128 v[172:175], v166 offset:1024
	ds_read_b128 v[176:179], v166 offset:2048
	ds_read_b128 v[180:183], v166 offset:3072
	ds_read_b128 v[184:187], v167
	ds_read_b128 v[188:191], v167 offset:1024
	ds_read_b128 v[192:195], v167 offset:2048
	ds_read_b128 v[196:199], v167 offset:3072
	s_add_u32 s44, s44, 0x40000
	s_addc_u32 s45, s45, 0
	v_readfirstlane_b32 s53, v148
	v_lshl_add_u64 v[240:241], s[44:45], 0, v[128:129]
	s_mov_b32 m0, s53
	ds_read_b128 v[200:203], v160 offset:32768
	ds_read_b128 v[204:207], v160 offset:33792
	ds_read_b128 v[212:215], v161 offset:32768
	ds_read_b128 v[216:219], v161 offset:33792
	ds_read_b128 v[220:223], v162 offset:32768
	ds_read_b128 v[224:227], v162 offset:33792
	ds_read_b128 v[228:231], v163 offset:32768
	ds_read_b128 v[232:235], v163 offset:33792
	global_load_lds_dwordx4 v[240:241], off
	v_lshl_add_u64 v[240:241], s[44:45], 0, v[130:131]
	v_readfirstlane_b32 s44, v149
	s_mov_b32 m0, s44
	s_nop 0
	global_load_lds_dwordx4 v[240:241], off
	s_waitcnt vmcnt(8)
	s_waitcnt lgkmcnt(0)
	s_barrier
	s_setprio 1
	s_waitcnt lgkmcnt(0)
	v_mfma_f32_16x16x32_bf16 v[124:127], v[200:203], v[168:171], v[124:127]
	v_mfma_f32_16x16x32_bf16 v[120:123], v[200:203], v[176:179], v[120:123]
	v_mfma_f32_16x16x32_bf16 v[116:119], v[212:215], v[168:171], v[116:119]
	v_mfma_f32_16x16x32_bf16 v[108:111], v[212:215], v[176:179], v[108:111]
	v_mfma_f32_16x16x32_bf16 v[100:103], v[220:223], v[168:171], v[100:103]
	v_mfma_f32_16x16x32_bf16 v[88:91], v[220:223], v[176:179], v[88:91]
	v_mfma_f32_16x16x32_bf16 v[84:87], v[228:231], v[168:171], v[84:87]
	v_mfma_f32_16x16x32_bf16 v[76:79], v[228:231], v[176:179], v[76:79]
	v_mfma_f32_16x16x32_bf16 v[124:127], v[204:207], v[172:175], v[124:127]
	v_mfma_f32_16x16x32_bf16 v[120:123], v[204:207], v[180:183], v[120:123]
	v_mfma_f32_16x16x32_bf16 v[116:119], v[216:219], v[172:175], v[116:119]
	v_mfma_f32_16x16x32_bf16 v[108:111], v[216:219], v[180:183], v[108:111]
	v_mfma_f32_16x16x32_bf16 v[100:103], v[224:227], v[172:175], v[100:103]
	v_mfma_f32_16x16x32_bf16 v[88:91], v[224:227], v[180:183], v[88:91]
	v_mfma_f32_16x16x32_bf16 v[84:87], v[232:235], v[172:175], v[84:87]
	v_mfma_f32_16x16x32_bf16 v[76:79], v[232:235], v[180:183], v[76:79]
	s_setprio 0
	s_setprio 1
	v_mfma_f32_16x16x32_bf16 v[112:115], v[200:203], v[184:187], v[112:115]
	v_mfma_f32_16x16x32_bf16 v[104:107], v[200:203], v[192:195], v[104:107]
	v_mfma_f32_16x16x32_bf16 v[96:99], v[212:215], v[184:187], v[96:99]
	v_mfma_f32_16x16x32_bf16 v[92:95], v[212:215], v[192:195], v[92:95]
	v_mfma_f32_16x16x32_bf16 v[80:83], v[220:223], v[184:187], v[80:83]
	v_mfma_f32_16x16x32_bf16 v[72:75], v[220:223], v[192:195], v[72:75]
	v_mfma_f32_16x16x32_bf16 v[68:71], v[228:231], v[184:187], v[68:71]
	v_mfma_f32_16x16x32_bf16 v[64:67], v[228:231], v[192:195], v[64:67]
	v_mfma_f32_16x16x32_bf16 v[112:115], v[204:207], v[188:191], v[112:115]
	v_mfma_f32_16x16x32_bf16 v[104:107], v[204:207], v[196:199], v[104:107]
	v_mfma_f32_16x16x32_bf16 v[96:99], v[216:219], v[188:191], v[96:99]
	v_mfma_f32_16x16x32_bf16 v[92:95], v[216:219], v[196:199], v[92:95]
	v_mfma_f32_16x16x32_bf16 v[80:83], v[224:227], v[188:191], v[80:83]
	v_mfma_f32_16x16x32_bf16 v[72:75], v[224:227], v[196:199], v[72:75]
	v_mfma_f32_16x16x32_bf16 v[68:71], v[232:235], v[188:191], v[68:71]
	v_mfma_f32_16x16x32_bf16 v[64:67], v[232:235], v[196:199], v[64:67]
	s_setprio 0
	s_barrier
; #define STAGE(P, g) do { const char* g_ = (const char*)(g); \
;         __builtin_amdgcn_global_load_lds((const unsigned*)(g_ + so0), (lds_u32*)((lds_u8*)(P) + sb0), 16, 0, 0); \
;         __builtin_amdgcn_global_load_lds((const unsigned*)(g_ + so1), (lds_u32*)((lds_u8*)(P) + sb0 + 8192), 16, 0, 0); } while (0)
; #define LDA(dst, b, h) for (int m = 0; m < 4; ++m) for (int k = 0; k < 2; ++k) \
;         dst[m][k] = *reinterpret_cast<const bf16x8*>((char*)SA(b, h) + lds_byte(wr * 64 + m * 16 + fr, k * 32 + fq * 8))
; #define MMA(ai, bj, At_, Bt_) do { __builtin_amdgcn_s_setprio(1); \
;         for (int m = 0; m < 4; ++m) for (int n = 0; n < 2; ++n) for (int k = 0; k < 2; ++k) \
;             acc[ai][bj][m][n] = __builtin_amdgcn_mfma_f32_16x16x32_bf16(At_[m][k], Bt_[n][k], acc[ai][bj][m][n], 0, 0, 0); \
;         __builtin_amdgcn_s_setprio(0); } while (0)
; #define WAIT_V(n) asm volatile("s_waitcnt vmcnt(" #n ")" ::: "memory")
; #define WAIT_L(n) asm volatile("s_waitcnt lgkmcnt(" #n ")" ::: "memory")
; #define BAR __builtin_amdgcn_s_barrier()
; #define SCHED __builtin_amdgcn_sched_barrier(0)
; template <int EPI, int K, int LNI = -1>
; DI void ph_gemm(const Params& p, const bf16_t* __restrict__ A, const bf16_t* __restrict__ Bt, int N, float* s_aux) {
;     ...
;         for (int t = 0; t < nt; t += 2) {
;     ...
;             LDA(At, 1, 1); STAGE(SB(1, 0), b3); STAGE(SB(1, 1), b3 + hstep); STAGE(SA(1, 0), a3);
;             WAIT_V(8); WAIT_L(0); BAR; MMA(1, 0, At, B0); MMA(1, 1, At, B1); BAR; SCHED;
	v_readfirstlane_b32 s44, v150
	v_lshl_add_u64 v[140:141], v[140:141], 0, s[6:7]
	s_mov_b32 m0, s44
	v_readfirstlane_b32 s44, v151
	s_add_u32 s28, s28, 0x40080
	ds_read_b128 v[200:203], v160 offset:49152
	ds_read_b128 v[204:207], v160 offset:50176
	ds_read_b128 v[212:215], v161 offset:49152
	ds_read_b128 v[216:219], v161 offset:50176
	ds_read_b128 v[220:223], v162 offset:49152
	ds_read_b128 v[224:227], v162 offset:50176
	ds_read_b128 v[228:231], v163 offset:49152
	ds_read_b128 v[232:235], v163 offset:50176
	global_load_lds_dwordx4 v[140:141], off
	v_lshl_add_u64 v[140:141], v[208:209], 0, s[6:7]
	s_mov_b32 m0, s44
	s_addc_u32 s29, s29, 0
	v_readfirstlane_b32 s44, v154
	global_load_lds_dwordx4 v[140:141], off
	v_lshl_add_u64 v[140:141], s[28:29], 0, v[128:129]
	s_mov_b32 m0, s44
	s_nop 0
	global_load_lds_dwordx4 v[140:141], off
	v_lshl_add_u64 v[140:141], s[28:29], 0, v[130:131]
	v_readfirstlane_b32 s28, v155
	s_mov_b32 m0, s28
	v_readfirstlane_b32 s28, v152
	global_load_lds_dwordx4 v[140:141], off
	v_lshl_add_u64 v[140:141], v[236:237], 0, s[6:7]
	s_mov_b32 m0, s28
	v_readfirstlane_b32 s28, v153
	global_load_lds_dwordx4 v[140:141], off
	v_lshl_add_u64 v[140:141], v[238:239], 0, s[6:7]
	s_mov_b32 m0, s28
	s_nop 0
	global_load_lds_dwordx4 v[140:141], off
	s_waitcnt vmcnt(8)
	s_waitcnt lgkmcnt(0)
	s_barrier
	s_setprio 1
	s_waitcnt lgkmcnt(0)
	v_mfma_f32_16x16x32_bf16 v[60:63], v[200:203], v[168:171], v[60:63]
	v_mfma_f32_16x16x32_bf16 v[56:59], v[200:203], v[176:179], v[56:59]
	v_mfma_f32_16x16x32_bf16 v[44:47], v[212:215], v[168:171], v[44:47]
	v_mfma_f32_16x16x32_bf16 v[40:43], v[212:215], v[176:179], v[40:43]
	v_mfma_f32_16x16x32_bf16 v[36:39], v[220:223], v[168:171], v[36:39]
	v_mfma_f32_16x16x32_bf16 v[28:31], v[220:223], v[176:179], v[28:31]
	v_mfma_f32_16x16x32_bf16 v[20:23], v[228:231], v[168:171], v[20:23]
	v_mfma_f32_16x16x32_bf16 v[12:15], v[228:231], v[176:179], v[12:15]
	v_mfma_f32_16x16x32_bf16 v[60:63], v[204:207], v[172:175], v[60:63]
	v_mfma_f32_16x16x32_bf16 v[56:59], v[204:207], v[180:183], v[56:59]
	v_mfma_f32_16x16x32_bf16 v[44:47], v[216:219], v[172:175], v[44:47]
	v_mfma_f32_16x16x32_bf16 v[40:43], v[216:219], v[180:183], v[40:43]
	v_mfma_f32_16x16x32_bf16 v[36:39], v[224:227], v[172:175], v[36:39]
	v_mfma_f32_16x16x32_bf16 v[28:31], v[224:227], v[180:183], v[28:31]
	v_mfma_f32_16x16x32_bf16 v[20:23], v[232:235], v[172:175], v[20:23]
	v_mfma_f32_16x16x32_bf16 v[12:15], v[232:235], v[180:183], v[12:15]
	s_setprio 0
	s_setprio 1
	v_mfma_f32_16x16x32_bf16 v[52:55], v[200:203], v[184:187], v[52:55]
	v_mfma_f32_16x16x32_bf16 v[48:51], v[200:203], v[192:195], v[48:51]
	v_mfma_f32_16x16x32_bf16 v[32:35], v[212:215], v[184:187], v[32:35]
	v_mfma_f32_16x16x32_bf16 v[24:27], v[212:215], v[192:195], v[24:27]
	v_mfma_f32_16x16x32_bf16 v[16:19], v[220:223], v[184:187], v[16:19]
	v_mfma_f32_16x16x32_bf16 v[8:11], v[220:223], v[192:195], v[8:11]
	v_mfma_f32_16x16x32_bf16 v[4:7], v[228:231], v[184:187], v[4:7]
	v_mfma_f32_16x16x32_bf16 v[0:3], v[228:231], v[192:195], v[0:3]
	v_mfma_f32_16x16x32_bf16 v[52:55], v[204:207], v[188:191], v[52:55]
	v_mfma_f32_16x16x32_bf16 v[48:51], v[204:207], v[196:199], v[48:51]
	v_mfma_f32_16x16x32_bf16 v[32:35], v[216:219], v[188:191], v[32:35]
	v_mfma_f32_16x16x32_bf16 v[24:27], v[216:219], v[196:199], v[24:27]
	v_mfma_f32_16x16x32_bf16 v[16:19], v[224:227], v[188:191], v[16:19]
	v_mfma_f32_16x16x32_bf16 v[8:11], v[224:227], v[196:199], v[8:11]
	v_mfma_f32_16x16x32_bf16 v[4:7], v[232:235], v[188:191], v[4:7]
	v_mfma_f32_16x16x32_bf16 v[0:3], v[232:235], v[196:199], v[0:3]
	s_setprio 0
	s_barrier
	s_add_i32 s52, s52, 2
	s_add_u32 s26, s26, 0x100
	s_addc_u32 s27, s27, 0
	s_cmp_gt_u32 s52, 13

; #define STAGE(P, g) do { const char* g_ = (const char*)(g); \
;         __builtin_amdgcn_global_load_lds((const unsigned*)(g_ + so0), (lds_u32*)((lds_u8*)(P) + sb0), 16, 0, 0); \
;         __builtin_amdgcn_global_load_lds((const unsigned*)(g_ + so1), (lds_u32*)((lds_u8*)(P) + sb0 + 8192), 16, 0, 0); } while (0)
; #define LDA(dst, b, h) for (int m = 0; m < 4; ++m) for (int k = 0; k < 2; ++k) \
;         dst[m][k] = *reinterpret_cast<const bf16x8*>((char*)SA(b, h) + lds_byte(wr * 64 + m * 16 + fr, k * 32 + fq * 8))
; #define LDB(dst, b, h) for (int n = 0; n < 2; ++n) for (int k = 0; k < 2; ++k) \
;         dst[n][k] = *reinterpret_cast<const bf16x8*>((char*)SB(b, h) + lds_byte(wc * 32 + n * 16 + fr, k * 32 + fq * 8))
; #define MMA(ai, bj, At_, Bt_) do { __builtin_amdgcn_s_setprio(1); \
;         for (int m = 0; m < 4; ++m) for (int n = 0; n < 2; ++n) for (int k = 0; k < 2; ++k) \
;             acc[ai][bj][m][n] = __builtin_amdgcn_mfma_f32_16x16x32_bf16(At_[m][k], Bt_[n][k], acc[ai][bj][m][n], 0, 0, 0); \
;         __builtin_amdgcn_s_setprio(0); } while (0)
; #define WAIT_V(n) asm volatile("s_waitcnt vmcnt(" #n ")" ::: "memory")
; #define WAIT_L(n) asm volatile("s_waitcnt lgkmcnt(" #n ")" ::: "memory")
; #define BAR __builtin_amdgcn_s_barrier()
; #define SCHED __builtin_amdgcn_sched_barrier(0)
; template <int EPI, int K, int LNI = -1>
; DI void ph_gemm(const Params& p, const bf16_t* __restrict__ A, const bf16_t* __restrict__ Bt, int N, float* s_aux) {
;     ...
;     f32x4 acc[2][2][4][2] = {};
;     ...
;         for (int t = 0; t < nt; t += 2) {
;             const bool last = (t == nt - 2);
;             const bf16_t* a1 = cA + (size_t)(t + 1) * kstep;
;             const bf16_t* a2 = last ? nA : cA + (size_t)(t + 2) * kstep; const bf16_t* b2 = last ? nB : cB + (size_t)(t + 2) * kstep;
;             const bf16_t* a3 = a2 + kstep; const bf16_t* b3 = b2 + kstep;
;             LDB(B0, 0, 0); LDB(B1, 0, 1); SCHED; LDA(At, 0, 0); STAGE(SA(1, 1), a1 + hstep);
;             WAIT_V(8); WAIT_L(0); BAR; MMA(0, 0, At, B0); MMA(0, 1, At, B1); BAR; SCHED;
;             LDA(At, 0, 1); STAGE(SB(0, 0), b2); STAGE(SB(0, 1), b2 + hstep); STAGE(SA(0, 0), a2);
.LBB0_927:
	s_ashr_i32 s15, s14, 31
	s_lshl_b64 s[20:21], s[14:15], 19
	s_add_u32 s15, s40, s20
	s_addc_u32 s42, s41, s21
	s_ashr_i32 s19, s18, 31
	s_lshl_b64 s[22:23], s[18:19], 19
	s_add_u32 s19, s8, s22
	s_addc_u32 s43, s9, s23
	s_add_u32 s50, s56, s28
	s_addc_u32 s51, s57, s29
	s_add_u32 s52, s35, s44
	v_lshl_add_u64 v[136:137], v[132:133], 0, s[28:29]
	v_lshl_add_u64 v[138:139], v[134:135], 0, s[28:29]
	s_addc_u32 s53, s48, s45
	s_mov_b32 s60, -2
	s_mov_b64 s[28:29], 0
	ds_read_b128 v[166:169], v156
	ds_read_b128 v[170:173], v156 offset:1024
	ds_read_b128 v[174:177], v156 offset:2048
	ds_read_b128 v[178:181], v156 offset:3072
	ds_read_b128 v[182:185], v157
	ds_read_b128 v[186:189], v157 offset:1024
	ds_read_b128 v[190:193], v157 offset:2048
	ds_read_b128 v[194:197], v157 offset:3072
	s_add_u32 s44, s50, s28
	s_addc_u32 s45, s51, s29
	s_add_u32 s44, s44, 0xb840100
	s_addc_u32 s45, s45, 0
	s_add_u32 s61, s52, s28
	s_addc_u32 s66, s53, s29
	s_cmpk_eq_i32 s28, 0x700
	s_cselect_b32 s47, s42, s45
	s_cselect_b32 s46, s15, s44
	s_cselect_b32 s45, s43, s66
	s_cselect_b32 s44, s19, s61
	v_readfirstlane_b32 s61, v162
	v_lshl_add_u64 v[232:233], v[136:137], 0, s[28:29]
	s_mov_b32 m0, s61
	v_readfirstlane_b32 s61, v163
	ds_read_b128 v[198:201], v158
	ds_read_b128 v[202:205], v158 offset:1024
	ds_read_b128 v[206:209], v159
	ds_read_b128 v[212:215], v159 offset:1024
	ds_read_b128 v[216:219], v160
	ds_read_b128 v[220:223], v160 offset:1024
	ds_read_b128 v[224:227], v161
	ds_read_b128 v[228:231], v161 offset:1024
	global_load_lds_dwordx4 v[232:233], off
	v_lshl_add_u64 v[232:233], v[138:139], 0, s[28:29]
	s_mov_b32 m0, s61
	s_nop 0
	global_load_lds_dwordx4 v[232:233], off
	s_waitcnt vmcnt(8)
	s_waitcnt lgkmcnt(0)
	s_barrier
	s_setprio 1
	s_waitcnt lgkmcnt(0)
	v_mfma_f32_16x16x32_bf16 v[124:127], v[198:201], v[166:169], 0
	v_mfma_f32_16x16x32_bf16 v[120:123], v[198:201], v[174:177], 0
	v_mfma_f32_16x16x32_bf16 v[108:111], v[206:209], v[166:169], 0
	v_mfma_f32_16x16x32_bf16 v[104:107], v[206:209], v[174:177], 0
	v_mfma_f32_16x16x32_bf16 v[92:95], v[216:219], v[166:169], 0
	v_mfma_f32_16x16x32_bf16 v[88:91], v[216:219], v[174:177], 0
	v_mfma_f32_16x16x32_bf16 v[76:79], v[224:227], v[166:169], 0
	v_mfma_f32_16x16x32_bf16 v[72:75], v[224:227], v[174:177], 0
	v_mfma_f32_16x16x32_bf16 v[124:127], v[202:205], v[170:173], v[124:127]
	v_mfma_f32_16x16x32_bf16 v[120:123], v[202:205], v[178:181], v[120:123]
	v_mfma_f32_16x16x32_bf16 v[108:111], v[212:215], v[170:173], v[108:111]
	v_mfma_f32_16x16x32_bf16 v[104:107], v[212:215], v[178:181], v[104:107]
	v_mfma_f32_16x16x32_bf16 v[92:95], v[220:223], v[170:173], v[92:95]
	v_mfma_f32_16x16x32_bf16 v[88:91], v[220:223], v[178:181], v[88:91]
	v_mfma_f32_16x16x32_bf16 v[76:79], v[228:231], v[170:173], v[76:79]
	v_mfma_f32_16x16x32_bf16 v[72:75], v[228:231], v[178:181], v[72:75]
	s_setprio 0
	s_setprio 1
	v_mfma_f32_16x16x32_bf16 v[116:119], v[198:201], v[182:185], 0
	v_mfma_f32_16x16x32_bf16 v[112:115], v[198:201], v[190:193], 0
	v_mfma_f32_16x16x32_bf16 v[100:103], v[206:209], v[182:185], 0
	v_mfma_f32_16x16x32_bf16 v[96:99], v[206:209], v[190:193], 0
	v_mfma_f32_16x16x32_bf16 v[84:87], v[216:219], v[182:185], 0
	v_mfma_f32_16x16x32_bf16 v[80:83], v[216:219], v[190:193], 0
	v_mfma_f32_16x16x32_bf16 v[68:71], v[224:227], v[182:185], 0
	v_mfma_f32_16x16x32_bf16 v[64:67], v[224:227], v[190:193], 0
	v_mfma_f32_16x16x32_bf16 v[116:119], v[202:205], v[186:189], v[116:119]
	v_mfma_f32_16x16x32_bf16 v[112:115], v[202:205], v[194:197], v[112:115]
	v_mfma_f32_16x16x32_bf16 v[100:103], v[212:215], v[186:189], v[100:103]
	v_mfma_f32_16x16x32_bf16 v[96:99], v[212:215], v[194:197], v[96:99]
	v_mfma_f32_16x16x32_bf16 v[84:87], v[220:223], v[186:189], v[84:87]
	v_mfma_f32_16x16x32_bf16 v[80:83], v[220:223], v[194:197], v[80:83]
	v_mfma_f32_16x16x32_bf16 v[68:71], v[228:231], v[186:189], v[68:71]
	v_mfma_f32_16x16x32_bf16 v[64:67], v[228:231], v[194:197], v[64:67]
	s_setprio 0
	s_barrier
	v_readfirstlane_b32 s61, v140
	v_lshl_add_u64 v[232:233], s[44:45], 0, v[128:129]
	s_mov_b32 m0, s61
	v_readfirstlane_b32 s61, v141
	s_add_u32 s66, s44, 0x40000
	ds_read_b128 v[198:201], v158 offset:16384
	ds_read_b128 v[202:205], v158 offset:17408
	ds_read_b128 v[206:209], v159 offset:16384
	ds_read_b128 v[212:215], v159 offset:17408
	ds_read_b128 v[216:219], v160 offset:16384
	ds_read_b128 v[220:223], v160 offset:17408
	ds_read_b128 v[224:227], v161 offset:16384
	ds_read_b128 v[228:231], v161 offset:17408
	global_load_lds_dwordx4 v[232:233], off
	v_lshl_add_u64 v[234:235], s[44:45], 0, v[130:131]
	s_mov_b32 m0, s61
	s_addc_u32 s67, s45, 0
	v_readfirstlane_b32 s61, v142
	global_load_lds_dwordx4 v[234:235], off
	v_lshl_add_u64 v[236:237], s[66:67], 0, v[128:129]
	s_mov_b32 m0, s61
	v_readfirstlane_b32 s61, v143
	global_load_lds_dwordx4 v[236:237], off
	v_lshl_add_u64 v[236:237], s[66:67], 0, v[130:131]
	s_mov_b32 m0, s61
	v_readfirstlane_b32 s61, v144
	global_load_lds_dwordx4 v[236:237], off
	v_lshl_add_u64 v[236:237], s[46:47], 0, v[128:129]
	s_mov_b32 m0, s61
	v_readfirstlane_b32 s61, v145
	global_load_lds_dwordx4 v[236:237], off
	v_lshl_add_u64 v[238:239], s[46:47], 0, v[130:131]
	s_mov_b32 m0, s61
	s_nop 0
	global_load_lds_dwordx4 v[238:239], off
	s_waitcnt vmcnt(8)
	s_waitcnt lgkmcnt(0)
	s_barrier
; #define STAGE(P, g) do { const char* g_ = (const char*)(g); \
;         __builtin_amdgcn_global_load_lds((const unsigned*)(g_ + so0), (lds_u32*)((lds_u8*)(P) + sb0), 16, 0, 0); \
;         __builtin_amdgcn_global_load_lds((const unsigned*)(g_ + so1), (lds_u32*)((lds_u8*)(P) + sb0 + 8192), 16, 0, 0); } while (0)
; #define LDA(dst, b, h) for (int m = 0; m < 4; ++m) for (int k = 0; k < 2; ++k) \
;         dst[m][k] = *reinterpret_cast<const bf16x8*>((char*)SA(b, h) + lds_byte(wr * 64 + m * 16 + fr, k * 32 + fq * 8))
; #define LDB(dst, b, h) for (int n = 0; n < 2; ++n) for (int k = 0; k < 2; ++k) \
;         dst[n][k] = *reinterpret_cast<const bf16x8*>((char*)SB(b, h) + lds_byte(wc * 32 + n * 16 + fr, k * 32 + fq * 8))
; #define MMA(ai, bj, At_, Bt_) do { __builtin_amdgcn_s_setprio(1); \
;         for (int m = 0; m < 4; ++m) for (int n = 0; n < 2; ++n) for (int k = 0; k < 2; ++k) \
;             acc[ai][bj][m][n] = __builtin_amdgcn_mfma_f32_16x16x32_bf16(At_[m][k], Bt_[n][k], acc[ai][bj][m][n], 0, 0, 0); \
;         __builtin_amdgcn_s_setprio(0); } while (0)
; #define WAIT_V(n) asm volatile("s_waitcnt vmcnt(" #n ")" ::: "memory")
; #define WAIT_L(n) asm volatile("s_waitcnt lgkmcnt(" #n ")" ::: "memory")
; #define BAR __builtin_amdgcn_s_barrier()
; #define SCHED __builtin_amdgcn_sched_barrier(0)
; template <int EPI, int K, int LNI = -1>
; DI void ph_gemm(const Params& p, const bf16_t* __restrict__ A, const bf16_t* __restrict__ Bt, int N, float* s_aux) {
;     ...
;             WAIT_V(8); WAIT_L(0); BAR; MMA(1, 0, At, B0); MMA(1, 1, At, B1); BAR; SCHED;
;             LDB(B0, 1, 0); LDB(B1, 1, 1); SCHED; LDA(At, 1, 0); STAGE(SA(0, 1), a2 + hstep);
;             WAIT_V(8); WAIT_L(0); BAR; MMA(0, 0, At, B0); MMA(0, 1, At, B1); BAR; SCHED;
	s_setprio 1
	s_waitcnt lgkmcnt(0)
	v_mfma_f32_16x16x32_bf16 v[60:63], v[198:201], v[166:169], 0
	v_mfma_f32_16x16x32_bf16 v[56:59], v[198:201], v[174:177], 0
	v_mfma_f32_16x16x32_bf16 v[44:47], v[206:209], v[166:169], 0
	v_mfma_f32_16x16x32_bf16 v[40:43], v[206:209], v[174:177], 0
	v_mfma_f32_16x16x32_bf16 v[28:31], v[216:219], v[166:169], 0
	v_mfma_f32_16x16x32_bf16 v[24:27], v[216:219], v[174:177], 0
	v_mfma_f32_16x16x32_bf16 v[12:15], v[224:227], v[166:169], 0
	v_mfma_f32_16x16x32_bf16 v[8:11], v[224:227], v[174:177], 0
	v_mfma_f32_16x16x32_bf16 v[60:63], v[202:205], v[170:173], v[60:63]
	v_mfma_f32_16x16x32_bf16 v[56:59], v[202:205], v[178:181], v[56:59]
	v_mfma_f32_16x16x32_bf16 v[44:47], v[212:215], v[170:173], v[44:47]
	v_mfma_f32_16x16x32_bf16 v[40:43], v[212:215], v[178:181], v[40:43]
	v_mfma_f32_16x16x32_bf16 v[28:31], v[220:223], v[170:173], v[28:31]
	v_mfma_f32_16x16x32_bf16 v[24:27], v[220:223], v[178:181], v[24:27]
	v_mfma_f32_16x16x32_bf16 v[12:15], v[228:231], v[170:173], v[12:15]
	v_mfma_f32_16x16x32_bf16 v[8:11], v[228:231], v[178:181], v[8:11]
	s_setprio 0
	s_setprio 1
	v_mfma_f32_16x16x32_bf16 v[52:55], v[198:201], v[182:185], 0
	v_mfma_f32_16x16x32_bf16 v[48:51], v[198:201], v[190:193], 0
	v_mfma_f32_16x16x32_bf16 v[36:39], v[206:209], v[182:185], 0
	v_mfma_f32_16x16x32_bf16 v[32:35], v[206:209], v[190:193], 0
	v_mfma_f32_16x16x32_bf16 v[20:23], v[216:219], v[182:185], 0
	v_mfma_f32_16x16x32_bf16 v[16:19], v[216:219], v[190:193], 0
	v_mfma_f32_16x16x32_bf16 v[4:7], v[224:227], v[182:185], 0
	v_mfma_f32_16x16x32_bf16 v[0:3], v[224:227], v[190:193], 0
	v_mfma_f32_16x16x32_bf16 v[52:55], v[202:205], v[186:189], v[52:55]
	v_mfma_f32_16x16x32_bf16 v[48:51], v[202:205], v[194:197], v[48:51]
	v_mfma_f32_16x16x32_bf16 v[36:39], v[212:215], v[186:189], v[36:39]
	v_mfma_f32_16x16x32_bf16 v[32:35], v[212:215], v[194:197], v[32:35]
	v_mfma_f32_16x16x32_bf16 v[20:23], v[220:223], v[186:189], v[20:23]
	v_mfma_f32_16x16x32_bf16 v[16:19], v[220:223], v[194:197], v[16:19]
	v_mfma_f32_16x16x32_bf16 v[4:7], v[228:231], v[186:189], v[4:7]
	v_mfma_f32_16x16x32_bf16 v[0:3], v[228:231], v[194:197], v[0:3]
	s_setprio 0
	s_barrier
	ds_read_b128 v[166:169], v164
	ds_read_b128 v[170:173], v164 offset:1024
	ds_read_b128 v[174:177], v164 offset:2048
	ds_read_b128 v[178:181], v164 offset:3072
	ds_read_b128 v[182:185], v165
	ds_read_b128 v[186:189], v165 offset:1024
	ds_read_b128 v[190:193], v165 offset:2048
	ds_read_b128 v[194:197], v165 offset:3072
	s_add_u32 s46, s46, 0x40000
	s_addc_u32 s47, s47, 0
	v_readfirstlane_b32 s61, v146
	v_lshl_add_u64 v[240:241], s[46:47], 0, v[128:129]
	s_mov_b32 m0, s61
	ds_read_b128 v[198:201], v158 offset:32768
	ds_read_b128 v[202:205], v158 offset:33792
	ds_read_b128 v[206:209], v159 offset:32768
	ds_read_b128 v[212:215], v159 offset:33792
	ds_read_b128 v[216:219], v160 offset:32768
	ds_read_b128 v[220:223], v160 offset:33792
	ds_read_b128 v[224:227], v161 offset:32768
	ds_read_b128 v[228:231], v161 offset:33792
	global_load_lds_dwordx4 v[240:241], off
	v_lshl_add_u64 v[240:241], s[46:47], 0, v[130:131]
	v_readfirstlane_b32 s46, v147
	s_mov_b32 m0, s46
	s_nop 0
	global_load_lds_dwordx4 v[240:241], off
	s_waitcnt vmcnt(8)
	s_waitcnt lgkmcnt(0)
	s_barrier
	s_setprio 1
	s_waitcnt lgkmcnt(0)
	v_mfma_f32_16x16x32_bf16 v[124:127], v[198:201], v[166:169], v[124:127]
	v_mfma_f32_16x16x32_bf16 v[120:123], v[198:201], v[174:177], v[120:123]
	v_mfma_f32_16x16x32_bf16 v[108:111], v[206:209], v[166:169], v[108:111]
	v_mfma_f32_16x16x32_bf16 v[104:107], v[206:209], v[174:177], v[104:107]
	v_mfma_f32_16x16x32_bf16 v[92:95], v[216:219], v[166:169], v[92:95]
	v_mfma_f32_16x16x32_bf16 v[88:91], v[216:219], v[174:177], v[88:91]
	v_mfma_f32_16x16x32_bf16 v[76:79], v[224:227], v[166:169], v[76:79]
	v_mfma_f32_16x16x32_bf16 v[72:75], v[224:227], v[174:177], v[72:75]
	v_mfma_f32_16x16x32_bf16 v[124:127], v[202:205], v[170:173], v[124:127]
	v_mfma_f32_16x16x32_bf16 v[120:123], v[202:205], v[178:181], v[120:123]
	v_mfma_f32_16x16x32_bf16 v[108:111], v[212:215], v[170:173], v[108:111]
	v_mfma_f32_16x16x32_bf16 v[104:107], v[212:215], v[178:181], v[104:107]
	v_mfma_f32_16x16x32_bf16 v[92:95], v[220:223], v[170:173], v[92:95]
	v_mfma_f32_16x16x32_bf16 v[88:91], v[220:223], v[178:181], v[88:91]
	v_mfma_f32_16x16x32_bf16 v[76:79], v[228:231], v[170:173], v[76:79]
	v_mfma_f32_16x16x32_bf16 v[72:75], v[228:231], v[178:181], v[72:75]
	s_setprio 0
	s_setprio 1
	v_mfma_f32_16x16x32_bf16 v[116:119], v[198:201], v[182:185], v[116:119]
	v_mfma_f32_16x16x32_bf16 v[112:115], v[198:201], v[190:193], v[112:115]
	v_mfma_f32_16x16x32_bf16 v[100:103], v[206:209], v[182:185], v[100:103]
	v_mfma_f32_16x16x32_bf16 v[96:99], v[206:209], v[190:193], v[96:99]
	v_mfma_f32_16x16x32_bf16 v[84:87], v[216:219], v[182:185], v[84:87]
	v_mfma_f32_16x16x32_bf16 v[80:83], v[216:219], v[190:193], v[80:83]
	v_mfma_f32_16x16x32_bf16 v[68:71], v[224:227], v[182:185], v[68:71]
	v_mfma_f32_16x16x32_bf16 v[64:67], v[224:227], v[190:193], v[64:67]
	v_mfma_f32_16x16x32_bf16 v[116:119], v[202:205], v[186:189], v[116:119]
	v_mfma_f32_16x16x32_bf16 v[112:115], v[202:205], v[194:197], v[112:115]
	v_mfma_f32_16x16x32_bf16 v[100:103], v[212:215], v[186:189], v[100:103]
	v_mfma_f32_16x16x32_bf16 v[96:99], v[212:215], v[194:197], v[96:99]
	v_mfma_f32_16x16x32_bf16 v[84:87], v[220:223], v[186:189], v[84:87]
	v_mfma_f32_16x16x32_bf16 v[80:83], v[220:223], v[194:197], v[80:83]
	v_mfma_f32_16x16x32_bf16 v[68:71], v[228:231], v[186:189], v[68:71]
	v_mfma_f32_16x16x32_bf16 v[64:67], v[228:231], v[194:197], v[64:67]
	s_setprio 0
	s_barrier
; #define STAGE(P, g) do { const char* g_ = (const char*)(g); \
;         __builtin_amdgcn_global_load_lds((const unsigned*)(g_ + so0), (lds_u32*)((lds_u8*)(P) + sb0), 16, 0, 0); \
;         __builtin_amdgcn_global_load_lds((const unsigned*)(g_ + so1), (lds_u32*)((lds_u8*)(P) + sb0 + 8192), 16, 0, 0); } while (0)
; #define LDA(dst, b, h) for (int m = 0; m < 4; ++m) for (int k = 0; k < 2; ++k) \
;         dst[m][k] = *reinterpret_cast<const bf16x8*>((char*)SA(b, h) + lds_byte(wr * 64 + m * 16 + fr, k * 32 + fq * 8))
; #define MMA(ai, bj, At_, Bt_) do { __builtin_amdgcn_s_setprio(1); \
;         for (int m = 0; m < 4; ++m) for (int n = 0; n < 2; ++n) for (int k = 0; k < 2; ++k) \
;             acc[ai][bj][m][n] = __builtin_amdgcn_mfma_f32_16x16x32_bf16(At_[m][k], Bt_[n][k], acc[ai][bj][m][n], 0, 0, 0); \
;         __builtin_amdgcn_s_setprio(0); } while (0)
; #define WAIT_V(n) asm volatile("s_waitcnt vmcnt(" #n ")" ::: "memory")
; #define WAIT_L(n) asm volatile("s_waitcnt lgkmcnt(" #n ")" ::: "memory")
; #define BAR __builtin_amdgcn_s_barrier()
; #define SCHED __builtin_amdgcn_sched_barrier(0)
; template <int EPI, int K, int LNI = -1>
; DI void ph_gemm(const Params& p, const bf16_t* __restrict__ A, const bf16_t* __restrict__ Bt, int N, float* s_aux) {
;     ...
;         for (int t = 0; t < nt; t += 2) {
;     ...
;             LDA(At, 1, 1); STAGE(SB(1, 0), b3); STAGE(SB(1, 1), b3 + hstep); STAGE(SA(1, 0), a3);
;             WAIT_V(8); WAIT_L(0); BAR; MMA(1, 0, At, B0); MMA(1, 1, At, B1); BAR; SCHED;
	v_readfirstlane_b32 s46, v148
	v_lshl_add_u64 v[232:233], v[232:233], 0, s[10:11]
	s_mov_b32 m0, s46
	v_readfirstlane_b32 s46, v149
	s_add_u32 s44, s44, 0x40080
	ds_read_b128 v[198:201], v158 offset:49152
	ds_read_b128 v[202:205], v158 offset:50176
	ds_read_b128 v[206:209], v159 offset:49152
	ds_read_b128 v[212:215], v159 offset:50176
	ds_read_b128 v[216:219], v160 offset:49152
	ds_read_b128 v[220:223], v160 offset:50176
	ds_read_b128 v[224:227], v161 offset:49152
	ds_read_b128 v[228:231], v161 offset:50176
	global_load_lds_dwordx4 v[232:233], off
	v_lshl_add_u64 v[232:233], v[234:235], 0, s[10:11]
	s_mov_b32 m0, s46
	s_addc_u32 s45, s45, 0
	v_readfirstlane_b32 s46, v152
	global_load_lds_dwordx4 v[232:233], off
	v_lshl_add_u64 v[232:233], s[44:45], 0, v[128:129]
	s_mov_b32 m0, s46
	s_nop 0
	global_load_lds_dwordx4 v[232:233], off
	v_lshl_add_u64 v[232:233], s[44:45], 0, v[130:131]
	v_readfirstlane_b32 s44, v153
	s_mov_b32 m0, s44
	v_readfirstlane_b32 s44, v150
	global_load_lds_dwordx4 v[232:233], off
	v_lshl_add_u64 v[232:233], v[236:237], 0, s[10:11]
	s_mov_b32 m0, s44
	v_readfirstlane_b32 s44, v151
	global_load_lds_dwordx4 v[232:233], off
	v_lshl_add_u64 v[232:233], v[238:239], 0, s[10:11]
	s_mov_b32 m0, s44
	s_nop 0
	global_load_lds_dwordx4 v[232:233], off
	s_waitcnt vmcnt(8)
	s_waitcnt lgkmcnt(0)
	s_barrier
	s_setprio 1
	s_waitcnt lgkmcnt(0)
	v_mfma_f32_16x16x32_bf16 v[60:63], v[198:201], v[166:169], v[60:63]
	v_mfma_f32_16x16x32_bf16 v[56:59], v[198:201], v[174:177], v[56:59]
	v_mfma_f32_16x16x32_bf16 v[44:47], v[206:209], v[166:169], v[44:47]
	v_mfma_f32_16x16x32_bf16 v[40:43], v[206:209], v[174:177], v[40:43]
	v_mfma_f32_16x16x32_bf16 v[28:31], v[216:219], v[166:169], v[28:31]
	v_mfma_f32_16x16x32_bf16 v[24:27], v[216:219], v[174:177], v[24:27]
	v_mfma_f32_16x16x32_bf16 v[12:15], v[224:227], v[166:169], v[12:15]
	v_mfma_f32_16x16x32_bf16 v[8:11], v[224:227], v[174:177], v[8:11]
	v_mfma_f32_16x16x32_bf16 v[60:63], v[202:205], v[170:173], v[60:63]
	v_mfma_f32_16x16x32_bf16 v[56:59], v[202:205], v[178:181], v[56:59]
	v_mfma_f32_16x16x32_bf16 v[44:47], v[212:215], v[170:173], v[44:47]
	v_mfma_f32_16x16x32_bf16 v[40:43], v[212:215], v[178:181], v[40:43]
	v_mfma_f32_16x16x32_bf16 v[28:31], v[220:223], v[170:173], v[28:31]
	v_mfma_f32_16x16x32_bf16 v[24:27], v[220:223], v[178:181], v[24:27]
	v_mfma_f32_16x16x32_bf16 v[12:15], v[228:231], v[170:173], v[12:15]
	v_mfma_f32_16x16x32_bf16 v[8:11], v[228:231], v[178:181], v[8:11]
	s_setprio 0
	s_setprio 1
	v_mfma_f32_16x16x32_bf16 v[52:55], v[198:201], v[182:185], v[52:55]
	v_mfma_f32_16x16x32_bf16 v[48:51], v[198:201], v[190:193], v[48:51]
	v_mfma_f32_16x16x32_bf16 v[36:39], v[206:209], v[182:185], v[36:39]
	v_mfma_f32_16x16x32_bf16 v[32:35], v[206:209], v[190:193], v[32:35]
	v_mfma_f32_16x16x32_bf16 v[20:23], v[216:219], v[182:185], v[20:23]
	v_mfma_f32_16x16x32_bf16 v[16:19], v[216:219], v[190:193], v[16:19]
	v_mfma_f32_16x16x32_bf16 v[4:7], v[224:227], v[182:185], v[4:7]
	v_mfma_f32_16x16x32_bf16 v[0:3], v[224:227], v[190:193], v[0:3]
	v_mfma_f32_16x16x32_bf16 v[52:55], v[202:205], v[186:189], v[52:55]
	v_mfma_f32_16x16x32_bf16 v[48:51], v[202:205], v[194:197], v[48:51]
	v_mfma_f32_16x16x32_bf16 v[36:39], v[212:215], v[186:189], v[36:39]
	v_mfma_f32_16x16x32_bf16 v[32:35], v[212:215], v[194:197], v[32:35]
	v_mfma_f32_16x16x32_bf16 v[20:23], v[220:223], v[186:189], v[20:23]
	v_mfma_f32_16x16x32_bf16 v[16:19], v[220:223], v[194:197], v[16:19]
	v_mfma_f32_16x16x32_bf16 v[4:7], v[228:231], v[186:189], v[4:7]
	v_mfma_f32_16x16x32_bf16 v[0:3], v[228:231], v[194:197], v[0:3]
	s_setprio 0
	s_barrier
	s_add_i32 s60, s60, 2
	s_add_u32 s28, s28, 0x100
	s_addc_u32 s29, s29, 0
	s_cmp_gt_u32 s60, 13

; #define STAGE(P, g) do { const char* g_ = (const char*)(g); \
;         __builtin_amdgcn_global_load_lds((const unsigned*)(g_ + so0), (lds_u32*)((lds_u8*)(P) + sb0), 16, 0, 0); \
;         __builtin_amdgcn_global_load_lds((const unsigned*)(g_ + so1), (lds_u32*)((lds_u8*)(P) + sb0 + 8192), 16, 0, 0); } while (0)
; #define LDA(dst, b, h) for (int m = 0; m < 4; ++m) for (int k = 0; k < 2; ++k) \
;         dst[m][k] = *reinterpret_cast<const bf16x8*>((char*)SA(b, h) + lds_byte(wr * 64 + m * 16 + fr, k * 32 + fq * 8))
; #define LDB(dst, b, h) for (int n = 0; n < 2; ++n) for (int k = 0; k < 2; ++k) \
;         dst[n][k] = *reinterpret_cast<const bf16x8*>((char*)SB(b, h) + lds_byte(wc * 32 + n * 16 + fr, k * 32 + fq * 8))
; #define MMA(ai, bj, At_, Bt_) do { __builtin_amdgcn_s_setprio(1); \
;         for (int m = 0; m < 4; ++m) for (int n = 0; n < 2; ++n) for (int k = 0; k < 2; ++k) \
;             acc[ai][bj][m][n] = __builtin_amdgcn_mfma_f32_16x16x32_bf16(At_[m][k], Bt_[n][k], acc[ai][bj][m][n], 0, 0, 0); \
;         __builtin_amdgcn_s_setprio(0); } while (0)
; #define WAIT_V(n) asm volatile("s_waitcnt vmcnt(" #n ")" ::: "memory")
; #define WAIT_L(n) asm volatile("s_waitcnt lgkmcnt(" #n ")" ::: "memory")
; #define BAR __builtin_amdgcn_s_barrier()
; #define SCHED __builtin_amdgcn_sched_barrier(0)
; template <int EPI, int K, int LNI = -1>
; DI void ph_gemm(const Params& p, const bf16_t* __restrict__ A, const bf16_t* __restrict__ Bt, int N, float* s_aux) {
;     ...
;     f32x4 acc[2][2][4][2] = {};
;     ...
;         for (int t = 0; t < nt; t += 2) {
;             const bool last = (t == nt - 2);
;             const bf16_t* a1 = cA + (size_t)(t + 1) * kstep;
;             const bf16_t* a2 = last ? nA : cA + (size_t)(t + 2) * kstep; const bf16_t* b2 = last ? nB : cB + (size_t)(t + 2) * kstep;
;             const bf16_t* a3 = a2 + kstep; const bf16_t* b3 = b2 + kstep;
;             LDB(B0, 0, 0); LDB(B1, 0, 1); SCHED; LDA(At, 0, 0); STAGE(SA(1, 1), a1 + hstep);
;             WAIT_V(8); WAIT_L(0); BAR; MMA(0, 0, At, B0); MMA(0, 1, At, B1); BAR; SCHED;
;             LDA(At, 0, 1); STAGE(SB(0, 0), b2); STAGE(SB(0, 1), b2 + hstep); STAGE(SA(0, 0), a2);
.LBB0_1004:
	s_ashr_i32 s15, s14, 31
	s_lshl_b64 s[20:21], s[14:15], 21
	s_add_u32 s15, s36, s20
	s_addc_u32 s42, s37, s21
	s_ashr_i32 s13, s12, 31
	s_lshl_b64 s[24:25], s[12:13], 21
	s_add_u32 s13, s3, s24
	s_addc_u32 s43, s35, s25
	s_add_u32 s60, s56, s44
	s_addc_u32 s61, s57, s45
	s_add_u32 s66, s50, s46
	v_lshl_add_u64 v[128:129], v[140:141], 0, s[44:45]
	v_lshl_add_u64 v[130:131], v[142:143], 0, s[44:45]
	s_addc_u32 s67, s51, s47
	s_mov_b32 s68, -2
	s_mov_b64 s[44:45], 0
	ds_read_b128 v[132:135], v176
	ds_read_b128 v[144:147], v176 offset:1024
	ds_read_b128 v[148:151], v176 offset:2048
	ds_read_b128 v[152:155], v176 offset:3072
	ds_read_b128 v[156:159], v177
	ds_read_b128 v[186:189], v177 offset:1024
	ds_read_b128 v[190:193], v177 offset:2048
	ds_read_b128 v[194:197], v177 offset:3072
	s_add_u32 s46, s60, s44
	s_addc_u32 s47, s61, s45
	s_add_u32 s46, s46, 0xfa70100
	s_addc_u32 s47, s47, 0
	s_add_u32 s69, s66, s44
	s_addc_u32 s70, s67, s45
	s_cmpk_eq_i32 s44, 0x1f00
	s_cselect_b32 s49, s42, s47
	s_cselect_b32 s48, s15, s46
	s_cselect_b32 s47, s43, s70
	s_cselect_b32 s46, s13, s69
	v_readfirstlane_b32 s69, v182
	v_lshl_add_u64 v[232:233], v[128:129], 0, s[44:45]
	s_mov_b32 m0, s69
	v_readfirstlane_b32 s69, v183
	ds_read_b128 v[198:201], v178
	ds_read_b128 v[202:205], v178 offset:1024
	ds_read_b128 v[206:209], v179
	ds_read_b128 v[212:215], v179 offset:1024
	ds_read_b128 v[216:219], v180
	ds_read_b128 v[220:223], v180 offset:1024
	ds_read_b128 v[224:227], v181
	ds_read_b128 v[228:231], v181 offset:1024
	global_load_lds_dwordx4 v[232:233], off
	v_lshl_add_u64 v[232:233], v[130:131], 0, s[44:45]
	s_mov_b32 m0, s69
	s_nop 0
	global_load_lds_dwordx4 v[232:233], off
	s_waitcnt vmcnt(8)
	s_waitcnt lgkmcnt(0)
	s_barrier
	s_setprio 1
	s_waitcnt lgkmcnt(0)
	v_mfma_f32_16x16x32_bf16 v[124:127], v[198:201], v[132:135], 0
	v_mfma_f32_16x16x32_bf16 v[120:123], v[198:201], v[148:151], 0
	v_mfma_f32_16x16x32_bf16 v[108:111], v[206:209], v[132:135], 0
	v_mfma_f32_16x16x32_bf16 v[104:107], v[206:209], v[148:151], 0
	v_mfma_f32_16x16x32_bf16 v[92:95], v[216:219], v[132:135], 0
	v_mfma_f32_16x16x32_bf16 v[88:91], v[216:219], v[148:151], 0
	v_mfma_f32_16x16x32_bf16 v[76:79], v[224:227], v[132:135], 0
	v_mfma_f32_16x16x32_bf16 v[72:75], v[224:227], v[148:151], 0
	v_mfma_f32_16x16x32_bf16 v[124:127], v[202:205], v[144:147], v[124:127]
	v_mfma_f32_16x16x32_bf16 v[120:123], v[202:205], v[152:155], v[120:123]
	v_mfma_f32_16x16x32_bf16 v[108:111], v[212:215], v[144:147], v[108:111]
	v_mfma_f32_16x16x32_bf16 v[104:107], v[212:215], v[152:155], v[104:107]
	v_mfma_f32_16x16x32_bf16 v[92:95], v[220:223], v[144:147], v[92:95]
	v_mfma_f32_16x16x32_bf16 v[88:91], v[220:223], v[152:155], v[88:91]
	v_mfma_f32_16x16x32_bf16 v[76:79], v[228:231], v[144:147], v[76:79]
	v_mfma_f32_16x16x32_bf16 v[72:75], v[228:231], v[152:155], v[72:75]
	s_setprio 0
	s_setprio 1
	v_mfma_f32_16x16x32_bf16 v[116:119], v[198:201], v[156:159], 0
	v_mfma_f32_16x16x32_bf16 v[112:115], v[198:201], v[190:193], 0
	v_mfma_f32_16x16x32_bf16 v[100:103], v[206:209], v[156:159], 0
	v_mfma_f32_16x16x32_bf16 v[96:99], v[206:209], v[190:193], 0
	v_mfma_f32_16x16x32_bf16 v[84:87], v[216:219], v[156:159], 0
	v_mfma_f32_16x16x32_bf16 v[80:83], v[216:219], v[190:193], 0
	v_mfma_f32_16x16x32_bf16 v[68:71], v[224:227], v[156:159], 0
	v_mfma_f32_16x16x32_bf16 v[64:67], v[224:227], v[190:193], 0
	v_mfma_f32_16x16x32_bf16 v[116:119], v[202:205], v[186:189], v[116:119]
	v_mfma_f32_16x16x32_bf16 v[112:115], v[202:205], v[194:197], v[112:115]
	v_mfma_f32_16x16x32_bf16 v[100:103], v[212:215], v[186:189], v[100:103]
	v_mfma_f32_16x16x32_bf16 v[96:99], v[212:215], v[194:197], v[96:99]
	v_mfma_f32_16x16x32_bf16 v[84:87], v[220:223], v[186:189], v[84:87]
	v_mfma_f32_16x16x32_bf16 v[80:83], v[220:223], v[194:197], v[80:83]
	v_mfma_f32_16x16x32_bf16 v[68:71], v[228:231], v[186:189], v[68:71]
	v_mfma_f32_16x16x32_bf16 v[64:67], v[228:231], v[194:197], v[64:67]
	s_setprio 0
	s_barrier
	v_readfirstlane_b32 s69, v160
	v_lshl_add_u64 v[232:233], s[46:47], 0, v[136:137]
	s_mov_b32 m0, s69
	v_readfirstlane_b32 s69, v161
	s_add_u32 s70, s46, 0x100000
	ds_read_b128 v[198:201], v178 offset:16384
	ds_read_b128 v[202:205], v178 offset:17408
	ds_read_b128 v[206:209], v179 offset:16384
	ds_read_b128 v[212:215], v179 offset:17408
	ds_read_b128 v[216:219], v180 offset:16384
	ds_read_b128 v[220:223], v180 offset:17408
	ds_read_b128 v[224:227], v181 offset:16384
	ds_read_b128 v[228:231], v181 offset:17408
	global_load_lds_dwordx4 v[232:233], off
	v_lshl_add_u64 v[234:235], s[46:47], 0, v[138:139]
	s_mov_b32 m0, s69
	s_addc_u32 s71, s47, 0
	v_readfirstlane_b32 s69, v162
	global_load_lds_dwordx4 v[234:235], off
	v_lshl_add_u64 v[236:237], s[70:71], 0, v[136:137]
	s_mov_b32 m0, s69
	v_readfirstlane_b32 s69, v163
	global_load_lds_dwordx4 v[236:237], off
	v_lshl_add_u64 v[236:237], s[70:71], 0, v[138:139]
	s_mov_b32 m0, s69
	v_readfirstlane_b32 s69, v164
	global_load_lds_dwordx4 v[236:237], off
	v_lshl_add_u64 v[236:237], s[48:49], 0, v[136:137]
	s_mov_b32 m0, s69
	v_readfirstlane_b32 s69, v165
	global_load_lds_dwordx4 v[236:237], off
	v_lshl_add_u64 v[238:239], s[48:49], 0, v[138:139]
	s_mov_b32 m0, s69
	s_nop 0
	global_load_lds_dwordx4 v[238:239], off
	s_waitcnt vmcnt(8)
	s_waitcnt lgkmcnt(0)
	s_barrier
; #define STAGE(P, g) do { const char* g_ = (const char*)(g); \
;         __builtin_amdgcn_global_load_lds((const unsigned*)(g_ + so0), (lds_u32*)((lds_u8*)(P) + sb0), 16, 0, 0); \
;         __builtin_amdgcn_global_load_lds((const unsigned*)(g_ + so1), (lds_u32*)((lds_u8*)(P) + sb0 + 8192), 16, 0, 0); } while (0)
; #define LDA(dst, b, h) for (int m = 0; m < 4; ++m) for (int k = 0; k < 2; ++k) \
;         dst[m][k] = *reinterpret_cast<const bf16x8*>((char*)SA(b, h) + lds_byte(wr * 64 + m * 16 + fr, k * 32 + fq * 8))
; #define LDB(dst, b, h) for (int n = 0; n < 2; ++n) for (int k = 0; k < 2; ++k) \
;         dst[n][k] = *reinterpret_cast<const bf16x8*>((char*)SB(b, h) + lds_byte(wc * 32 + n * 16 + fr, k * 32 + fq * 8))
; #define MMA(ai, bj, At_, Bt_) do { __builtin_amdgcn_s_setprio(1); \
;         for (int m = 0; m < 4; ++m) for (int n = 0; n < 2; ++n) for (int k = 0; k < 2; ++k) \
;             acc[ai][bj][m][n] = __builtin_amdgcn_mfma_f32_16x16x32_bf16(At_[m][k], Bt_[n][k], acc[ai][bj][m][n], 0, 0, 0); \
;         __builtin_amdgcn_s_setprio(0); } while (0)
; #define WAIT_V(n) asm volatile("s_waitcnt vmcnt(" #n ")" ::: "memory")
; #define WAIT_L(n) asm volatile("s_waitcnt lgkmcnt(" #n ")" ::: "memory")
; #define BAR __builtin_amdgcn_s_barrier()
; #define SCHED __builtin_amdgcn_sched_barrier(0)
; template <int EPI, int K, int LNI = -1>
; DI void ph_gemm(const Params& p, const bf16_t* __restrict__ A, const bf16_t* __restrict__ Bt, int N, float* s_aux) {
;     ...
;             WAIT_V(8); WAIT_L(0); BAR; MMA(1, 0, At, B0); MMA(1, 1, At, B1); BAR; SCHED;
;             LDB(B0, 1, 0); LDB(B1, 1, 1); SCHED; LDA(At, 1, 0); STAGE(SA(0, 1), a2 + hstep);
;             WAIT_V(8); WAIT_L(0); BAR; MMA(0, 0, At, B0); MMA(0, 1, At, B1); BAR; SCHED;
	s_setprio 1
	s_waitcnt lgkmcnt(0)
	v_mfma_f32_16x16x32_bf16 v[60:63], v[198:201], v[132:135], 0
	v_mfma_f32_16x16x32_bf16 v[56:59], v[198:201], v[148:151], 0
	v_mfma_f32_16x16x32_bf16 v[44:47], v[206:209], v[132:135], 0
	v_mfma_f32_16x16x32_bf16 v[40:43], v[206:209], v[148:151], 0
	v_mfma_f32_16x16x32_bf16 v[28:31], v[216:219], v[132:135], 0
	v_mfma_f32_16x16x32_bf16 v[24:27], v[216:219], v[148:151], 0
	v_mfma_f32_16x16x32_bf16 v[12:15], v[224:227], v[132:135], 0
	v_mfma_f32_16x16x32_bf16 v[8:11], v[224:227], v[148:151], 0
	v_mfma_f32_16x16x32_bf16 v[60:63], v[202:205], v[144:147], v[60:63]
	v_mfma_f32_16x16x32_bf16 v[56:59], v[202:205], v[152:155], v[56:59]
	v_mfma_f32_16x16x32_bf16 v[44:47], v[212:215], v[144:147], v[44:47]
	v_mfma_f32_16x16x32_bf16 v[40:43], v[212:215], v[152:155], v[40:43]
	v_mfma_f32_16x16x32_bf16 v[28:31], v[220:223], v[144:147], v[28:31]
	v_mfma_f32_16x16x32_bf16 v[24:27], v[220:223], v[152:155], v[24:27]
	v_mfma_f32_16x16x32_bf16 v[12:15], v[228:231], v[144:147], v[12:15]
	v_mfma_f32_16x16x32_bf16 v[8:11], v[228:231], v[152:155], v[8:11]
	s_setprio 0
	s_setprio 1
	v_mfma_f32_16x16x32_bf16 v[52:55], v[198:201], v[156:159], 0
	v_mfma_f32_16x16x32_bf16 v[48:51], v[198:201], v[190:193], 0
	v_mfma_f32_16x16x32_bf16 v[36:39], v[206:209], v[156:159], 0
	v_mfma_f32_16x16x32_bf16 v[32:35], v[206:209], v[190:193], 0
	v_mfma_f32_16x16x32_bf16 v[20:23], v[216:219], v[156:159], 0
	v_mfma_f32_16x16x32_bf16 v[16:19], v[216:219], v[190:193], 0
	v_mfma_f32_16x16x32_bf16 v[4:7], v[224:227], v[156:159], 0
	v_mfma_f32_16x16x32_bf16 v[0:3], v[224:227], v[190:193], 0
	v_mfma_f32_16x16x32_bf16 v[52:55], v[202:205], v[186:189], v[52:55]
	v_mfma_f32_16x16x32_bf16 v[48:51], v[202:205], v[194:197], v[48:51]
	v_mfma_f32_16x16x32_bf16 v[36:39], v[212:215], v[186:189], v[36:39]
	v_mfma_f32_16x16x32_bf16 v[32:35], v[212:215], v[194:197], v[32:35]
	v_mfma_f32_16x16x32_bf16 v[20:23], v[220:223], v[186:189], v[20:23]
	v_mfma_f32_16x16x32_bf16 v[16:19], v[220:223], v[194:197], v[16:19]
	v_mfma_f32_16x16x32_bf16 v[4:7], v[228:231], v[186:189], v[4:7]
	v_mfma_f32_16x16x32_bf16 v[0:3], v[228:231], v[194:197], v[0:3]
	s_setprio 0
	s_barrier
	ds_read_b128 v[132:135], v184
	ds_read_b128 v[144:147], v184 offset:1024
	ds_read_b128 v[148:151], v184 offset:2048
	ds_read_b128 v[152:155], v184 offset:3072
	ds_read_b128 v[156:159], v185
	ds_read_b128 v[186:189], v185 offset:1024
	ds_read_b128 v[190:193], v185 offset:2048
	ds_read_b128 v[194:197], v185 offset:3072
	s_add_u32 s48, s48, 0x100000
	s_addc_u32 s49, s49, 0
	v_readfirstlane_b32 s69, v166
	v_lshl_add_u64 v[240:241], s[48:49], 0, v[136:137]
	s_mov_b32 m0, s69
	ds_read_b128 v[198:201], v178 offset:32768
	ds_read_b128 v[202:205], v178 offset:33792
	ds_read_b128 v[206:209], v179 offset:32768
	ds_read_b128 v[212:215], v179 offset:33792
	ds_read_b128 v[216:219], v180 offset:32768
	ds_read_b128 v[220:223], v180 offset:33792
	ds_read_b128 v[224:227], v181 offset:32768
	ds_read_b128 v[228:231], v181 offset:33792
	global_load_lds_dwordx4 v[240:241], off
	v_lshl_add_u64 v[240:241], s[48:49], 0, v[138:139]
	v_readfirstlane_b32 s48, v167
	s_mov_b32 m0, s48
	s_nop 0
	global_load_lds_dwordx4 v[240:241], off
	s_waitcnt vmcnt(8)
	s_waitcnt lgkmcnt(0)
	s_barrier
	s_setprio 1
	s_waitcnt lgkmcnt(0)
	v_mfma_f32_16x16x32_bf16 v[124:127], v[198:201], v[132:135], v[124:127]
	v_mfma_f32_16x16x32_bf16 v[120:123], v[198:201], v[148:151], v[120:123]
	v_mfma_f32_16x16x32_bf16 v[108:111], v[206:209], v[132:135], v[108:111]
	v_mfma_f32_16x16x32_bf16 v[104:107], v[206:209], v[148:151], v[104:107]
	v_mfma_f32_16x16x32_bf16 v[92:95], v[216:219], v[132:135], v[92:95]
	v_mfma_f32_16x16x32_bf16 v[88:91], v[216:219], v[148:151], v[88:91]
	v_mfma_f32_16x16x32_bf16 v[76:79], v[224:227], v[132:135], v[76:79]
	v_mfma_f32_16x16x32_bf16 v[72:75], v[224:227], v[148:151], v[72:75]
	v_mfma_f32_16x16x32_bf16 v[124:127], v[202:205], v[144:147], v[124:127]
	v_mfma_f32_16x16x32_bf16 v[120:123], v[202:205], v[152:155], v[120:123]
	v_mfma_f32_16x16x32_bf16 v[108:111], v[212:215], v[144:147], v[108:111]
	v_mfma_f32_16x16x32_bf16 v[104:107], v[212:215], v[152:155], v[104:107]
	v_mfma_f32_16x16x32_bf16 v[92:95], v[220:223], v[144:147], v[92:95]
	v_mfma_f32_16x16x32_bf16 v[88:91], v[220:223], v[152:155], v[88:91]
	v_mfma_f32_16x16x32_bf16 v[76:79], v[228:231], v[144:147], v[76:79]
	v_mfma_f32_16x16x32_bf16 v[72:75], v[228:231], v[152:155], v[72:75]
	s_setprio 0
	s_setprio 1
	v_mfma_f32_16x16x32_bf16 v[116:119], v[198:201], v[156:159], v[116:119]
	v_mfma_f32_16x16x32_bf16 v[112:115], v[198:201], v[190:193], v[112:115]
	v_mfma_f32_16x16x32_bf16 v[100:103], v[206:209], v[156:159], v[100:103]
	v_mfma_f32_16x16x32_bf16 v[96:99], v[206:209], v[190:193], v[96:99]
	v_mfma_f32_16x16x32_bf16 v[84:87], v[216:219], v[156:159], v[84:87]
	v_mfma_f32_16x16x32_bf16 v[80:83], v[216:219], v[190:193], v[80:83]
	v_mfma_f32_16x16x32_bf16 v[68:71], v[224:227], v[156:159], v[68:71]
	v_mfma_f32_16x16x32_bf16 v[64:67], v[224:227], v[190:193], v[64:67]
	v_mfma_f32_16x16x32_bf16 v[116:119], v[202:205], v[186:189], v[116:119]
	v_mfma_f32_16x16x32_bf16 v[112:115], v[202:205], v[194:197], v[112:115]
	v_mfma_f32_16x16x32_bf16 v[100:103], v[212:215], v[186:189], v[100:103]
	v_mfma_f32_16x16x32_bf16 v[96:99], v[212:215], v[194:197], v[96:99]
	v_mfma_f32_16x16x32_bf16 v[84:87], v[220:223], v[186:189], v[84:87]
	v_mfma_f32_16x16x32_bf16 v[80:83], v[220:223], v[194:197], v[80:83]
	v_mfma_f32_16x16x32_bf16 v[68:71], v[228:231], v[186:189], v[68:71]
	v_mfma_f32_16x16x32_bf16 v[64:67], v[228:231], v[194:197], v[64:67]
	s_setprio 0
	s_barrier
; #define STAGE(P, g) do { const char* g_ = (const char*)(g); \
;         __builtin_amdgcn_global_load_lds((const unsigned*)(g_ + so0), (lds_u32*)((lds_u8*)(P) + sb0), 16, 0, 0); \
;         __builtin_amdgcn_global_load_lds((const unsigned*)(g_ + so1), (lds_u32*)((lds_u8*)(P) + sb0 + 8192), 16, 0, 0); } while (0)
; #define LDA(dst, b, h) for (int m = 0; m < 4; ++m) for (int k = 0; k < 2; ++k) \
;         dst[m][k] = *reinterpret_cast<const bf16x8*>((char*)SA(b, h) + lds_byte(wr * 64 + m * 16 + fr, k * 32 + fq * 8))
; #define MMA(ai, bj, At_, Bt_) do { __builtin_amdgcn_s_setprio(1); \
;         for (int m = 0; m < 4; ++m) for (int n = 0; n < 2; ++n) for (int k = 0; k < 2; ++k) \
;             acc[ai][bj][m][n] = __builtin_amdgcn_mfma_f32_16x16x32_bf16(At_[m][k], Bt_[n][k], acc[ai][bj][m][n], 0, 0, 0); \
;         __builtin_amdgcn_s_setprio(0); } while (0)
; #define WAIT_V(n) asm volatile("s_waitcnt vmcnt(" #n ")" ::: "memory")
; #define WAIT_L(n) asm volatile("s_waitcnt lgkmcnt(" #n ")" ::: "memory")
; #define BAR __builtin_amdgcn_s_barrier()
; #define SCHED __builtin_amdgcn_sched_barrier(0)
; template <int EPI, int K, int LNI = -1>
; DI void ph_gemm(const Params& p, const bf16_t* __restrict__ A, const bf16_t* __restrict__ Bt, int N, float* s_aux) {
;     ...
;         for (int t = 0; t < nt; t += 2) {
;     ...
;             LDA(At, 1, 1); STAGE(SB(1, 0), b3); STAGE(SB(1, 1), b3 + hstep); STAGE(SA(1, 0), a3);
;             WAIT_V(8); WAIT_L(0); BAR; MMA(1, 0, At, B0); MMA(1, 1, At, B1); BAR; SCHED;
	v_readfirstlane_b32 s48, v168
	v_lshl_add_u64 v[232:233], v[232:233], 0, s[8:9]
	s_mov_b32 m0, s48
	v_readfirstlane_b32 s48, v169
	s_add_u32 s46, s46, 0x100080
	ds_read_b128 v[198:201], v178 offset:49152
	ds_read_b128 v[202:205], v178 offset:50176
	ds_read_b128 v[206:209], v179 offset:49152
	ds_read_b128 v[212:215], v179 offset:50176
	ds_read_b128 v[216:219], v180 offset:49152
	ds_read_b128 v[220:223], v180 offset:50176
	ds_read_b128 v[224:227], v181 offset:49152
	ds_read_b128 v[228:231], v181 offset:50176
	global_load_lds_dwordx4 v[232:233], off
	v_lshl_add_u64 v[232:233], v[234:235], 0, s[8:9]
	s_mov_b32 m0, s48
	s_addc_u32 s47, s47, 0
	v_readfirstlane_b32 s48, v172
	global_load_lds_dwordx4 v[232:233], off
	v_lshl_add_u64 v[232:233], s[46:47], 0, v[136:137]
	s_mov_b32 m0, s48
	s_nop 0
	global_load_lds_dwordx4 v[232:233], off
	v_lshl_add_u64 v[232:233], s[46:47], 0, v[138:139]
	v_readfirstlane_b32 s46, v173
	s_mov_b32 m0, s46
	v_readfirstlane_b32 s46, v170
	global_load_lds_dwordx4 v[232:233], off
	v_lshl_add_u64 v[232:233], v[236:237], 0, s[8:9]
	s_mov_b32 m0, s46
	v_readfirstlane_b32 s46, v171
	global_load_lds_dwordx4 v[232:233], off
	v_lshl_add_u64 v[232:233], v[238:239], 0, s[8:9]
	s_mov_b32 m0, s46
	s_nop 0
	global_load_lds_dwordx4 v[232:233], off
	s_waitcnt vmcnt(8)
	s_waitcnt lgkmcnt(0)
	s_barrier
	s_setprio 1
	s_waitcnt lgkmcnt(0)
	v_mfma_f32_16x16x32_bf16 v[60:63], v[198:201], v[132:135], v[60:63]
	v_mfma_f32_16x16x32_bf16 v[56:59], v[198:201], v[148:151], v[56:59]
	v_mfma_f32_16x16x32_bf16 v[44:47], v[206:209], v[132:135], v[44:47]
	v_mfma_f32_16x16x32_bf16 v[40:43], v[206:209], v[148:151], v[40:43]
	v_mfma_f32_16x16x32_bf16 v[28:31], v[216:219], v[132:135], v[28:31]
	v_mfma_f32_16x16x32_bf16 v[24:27], v[216:219], v[148:151], v[24:27]
	v_mfma_f32_16x16x32_bf16 v[12:15], v[224:227], v[132:135], v[12:15]
	v_mfma_f32_16x16x32_bf16 v[8:11], v[224:227], v[148:151], v[8:11]
	v_mfma_f32_16x16x32_bf16 v[60:63], v[202:205], v[144:147], v[60:63]
	v_mfma_f32_16x16x32_bf16 v[56:59], v[202:205], v[152:155], v[56:59]
	v_mfma_f32_16x16x32_bf16 v[44:47], v[212:215], v[144:147], v[44:47]
	v_mfma_f32_16x16x32_bf16 v[40:43], v[212:215], v[152:155], v[40:43]
	v_mfma_f32_16x16x32_bf16 v[28:31], v[220:223], v[144:147], v[28:31]
	v_mfma_f32_16x16x32_bf16 v[24:27], v[220:223], v[152:155], v[24:27]
	v_mfma_f32_16x16x32_bf16 v[12:15], v[228:231], v[144:147], v[12:15]
	v_mfma_f32_16x16x32_bf16 v[8:11], v[228:231], v[152:155], v[8:11]
	s_setprio 0
	s_setprio 1
	v_mfma_f32_16x16x32_bf16 v[52:55], v[198:201], v[156:159], v[52:55]
	v_mfma_f32_16x16x32_bf16 v[48:51], v[198:201], v[190:193], v[48:51]
	v_mfma_f32_16x16x32_bf16 v[36:39], v[206:209], v[156:159], v[36:39]
	v_mfma_f32_16x16x32_bf16 v[32:35], v[206:209], v[190:193], v[32:35]
	v_mfma_f32_16x16x32_bf16 v[20:23], v[216:219], v[156:159], v[20:23]
	v_mfma_f32_16x16x32_bf16 v[16:19], v[216:219], v[190:193], v[16:19]
	v_mfma_f32_16x16x32_bf16 v[4:7], v[224:227], v[156:159], v[4:7]
	v_mfma_f32_16x16x32_bf16 v[0:3], v[224:227], v[190:193], v[0:3]
	v_mfma_f32_16x16x32_bf16 v[52:55], v[202:205], v[186:189], v[52:55]
	v_mfma_f32_16x16x32_bf16 v[48:51], v[202:205], v[194:197], v[48:51]
	v_mfma_f32_16x16x32_bf16 v[36:39], v[212:215], v[186:189], v[36:39]
	v_mfma_f32_16x16x32_bf16 v[32:35], v[212:215], v[194:197], v[32:35]
	v_mfma_f32_16x16x32_bf16 v[20:23], v[220:223], v[186:189], v[20:23]
	v_mfma_f32_16x16x32_bf16 v[16:19], v[220:223], v[194:197], v[16:19]
	v_mfma_f32_16x16x32_bf16 v[4:7], v[228:231], v[186:189], v[4:7]
	v_mfma_f32_16x16x32_bf16 v[0:3], v[228:231], v[194:197], v[0:3]
	s_setprio 0
	s_barrier
	s_add_i32 s68, s68, 2
	s_add_u32 s44, s44, 0x100
	s_addc_u32 s45, s45, 0
	s_cmp_gt_u32 s68, 61

; #define STAGE(P, g) do { const char* g_ = (const char*)(g); \
;         __builtin_amdgcn_global_load_lds((const unsigned*)(g_ + so0), (lds_u32*)((lds_u8*)(P) + sb0), 16, 0, 0); \
;         __builtin_amdgcn_global_load_lds((const unsigned*)(g_ + so1), (lds_u32*)((lds_u8*)(P) + sb0 + 8192), 16, 0, 0); } while (0)
; #define LDA(dst, b, h) for (int m = 0; m < 4; ++m) for (int k = 0; k < 2; ++k) \
;         dst[m][k] = *reinterpret_cast<const bf16x8*>((char*)SA(b, h) + lds_byte(wr * 64 + m * 16 + fr, k * 32 + fq * 8))
; #define LDB(dst, b, h) for (int n = 0; n < 2; ++n) for (int k = 0; k < 2; ++k) \
;         dst[n][k] = *reinterpret_cast<const bf16x8*>((char*)SB(b, h) + lds_byte(wc * 32 + n * 16 + fr, k * 32 + fq * 8))
; #define MMA(ai, bj, At_, Bt_) do { __builtin_amdgcn_s_setprio(1); \
;         for (int m = 0; m < 4; ++m) for (int n = 0; n < 2; ++n) for (int k = 0; k < 2; ++k) \
;             acc[ai][bj][m][n] = __builtin_amdgcn_mfma_f32_16x16x32_bf16(At_[m][k], Bt_[n][k], acc[ai][bj][m][n], 0, 0, 0); \
;         __builtin_amdgcn_s_setprio(0); } while (0)
; #define WAIT_V(n) asm volatile("s_waitcnt vmcnt(" #n ")" ::: "memory")
; #define WAIT_L(n) asm volatile("s_waitcnt lgkmcnt(" #n ")" ::: "memory")
; #define BAR __builtin_amdgcn_s_barrier()
; #define SCHED __builtin_amdgcn_sched_barrier(0)
; template <int EPI, int K, int LNI = -1>
; DI void ph_gemm(const Params& p, const bf16_t* __restrict__ A, const bf16_t* __restrict__ Bt, int N, float* s_aux) {
;     ...
;     f32x4 acc[2][2][4][2] = {};
;     ...
;         for (int t = 0; t < nt; t += 2) {
;             const bool last = (t == nt - 2);
;             const bf16_t* a1 = cA + (size_t)(t + 1) * kstep;
;             const bf16_t* a2 = last ? nA : cA + (size_t)(t + 2) * kstep; const bf16_t* b2 = last ? nB : cB + (size_t)(t + 2) * kstep;
;             const bf16_t* a3 = a2 + kstep; const bf16_t* b3 = b2 + kstep;
;             LDB(B0, 0, 0); LDB(B1, 0, 1); SCHED; LDA(At, 0, 0); STAGE(SA(1, 1), a1 + hstep);
;             WAIT_V(8); WAIT_L(0); BAR; MMA(0, 0, At, B0); MMA(0, 1, At, B1); BAR; SCHED;
;             LDA(At, 0, 1); STAGE(SB(0, 0), b2); STAGE(SB(0, 1), b2 + hstep); STAGE(SA(0, 0), a2);
.LBB0_1143:
	s_ashr_i32 s51, s50, 31
	s_lshl_b64 s[52:53], s[50:51], 19
	s_add_u32 s9, s40, s52
	s_addc_u32 s11, s41, s53
	s_ashr_i32 s49, s48, 31
	s_lshl_b64 s[60:61], s[48:49], 19
	s_add_u32 s42, s26, s60
	s_addc_u32 s43, s27, s61
	s_add_u32 s49, s56, s12
	s_addc_u32 s51, s57, s13
	s_add_u32 s68, s45, s14
	v_lshl_add_u64 v[138:139], v[134:135], 0, s[12:13]
	v_lshl_add_u64 v[140:141], v[136:137], 0, s[12:13]
	s_addc_u32 s69, s70, s15
	s_mov_b32 s80, -2
	s_mov_b64 s[12:13], 0
	ds_read_b128 v[142:145], v165
	ds_read_b128 v[176:179], v165 offset:1024
	ds_read_b128 v[180:183], v165 offset:2048
	ds_read_b128 v[184:187], v165 offset:3072
	ds_read_b128 v[188:191], v166
	ds_read_b128 v[192:195], v166 offset:1024
	ds_read_b128 v[196:199], v166 offset:2048
	ds_read_b128 v[200:203], v166 offset:3072
	s_add_u32 s14, s49, s12
	s_addc_u32 s15, s51, s13
	s_add_u32 s14, s14, 0xb840100
	s_addc_u32 s15, s15, 0
	s_add_u32 s91, s68, s12
	s_addc_u32 s92, s69, s13
	s_cmpk_eq_i32 s12, 0x700
	s_cselect_b32 s67, s11, s15
	s_cselect_b32 s66, s9, s14
	s_cselect_b32 s15, s43, s92
	s_cselect_b32 s14, s42, s91
	v_readfirstlane_b32 s91, v171
	v_lshl_add_u64 v[146:147], v[138:139], 0, s[12:13]
	s_mov_b32 m0, s91
	v_readfirstlane_b32 s91, v172
	ds_read_b128 v[204:207], v167
	ds_read_b128 v[212:215], v167 offset:1024
	ds_read_b128 v[216:219], v168
	ds_read_b128 v[220:223], v168 offset:1024
	ds_read_b128 v[224:227], v169
	ds_read_b128 v[228:231], v169 offset:1024
	ds_read_b128 v[232:235], v170
	ds_read_b128 v[236:239], v170 offset:1024
	global_load_lds_dwordx4 v[146:147], off
	v_lshl_add_u64 v[146:147], v[140:141], 0, s[12:13]
	s_mov_b32 m0, s91
	s_nop 0
	global_load_lds_dwordx4 v[146:147], off
	s_waitcnt vmcnt(8)
	s_waitcnt lgkmcnt(0)
	s_barrier
	s_setprio 1
	s_waitcnt lgkmcnt(0)
	v_mfma_f32_16x16x32_bf16 v[124:127], v[204:207], v[142:145], 0
	v_mfma_f32_16x16x32_bf16 v[120:123], v[204:207], v[180:183], 0
	v_mfma_f32_16x16x32_bf16 v[108:111], v[216:219], v[142:145], 0
	v_mfma_f32_16x16x32_bf16 v[104:107], v[216:219], v[180:183], 0
	v_mfma_f32_16x16x32_bf16 v[92:95], v[224:227], v[142:145], 0
	v_mfma_f32_16x16x32_bf16 v[88:91], v[224:227], v[180:183], 0
	v_mfma_f32_16x16x32_bf16 v[76:79], v[232:235], v[142:145], 0
	v_mfma_f32_16x16x32_bf16 v[72:75], v[232:235], v[180:183], 0
	v_mfma_f32_16x16x32_bf16 v[124:127], v[212:215], v[176:179], v[124:127]
	v_mfma_f32_16x16x32_bf16 v[120:123], v[212:215], v[184:187], v[120:123]
	v_mfma_f32_16x16x32_bf16 v[108:111], v[220:223], v[176:179], v[108:111]
	v_mfma_f32_16x16x32_bf16 v[104:107], v[220:223], v[184:187], v[104:107]
	v_mfma_f32_16x16x32_bf16 v[92:95], v[228:231], v[176:179], v[92:95]
	v_mfma_f32_16x16x32_bf16 v[88:91], v[228:231], v[184:187], v[88:91]
	v_mfma_f32_16x16x32_bf16 v[76:79], v[236:239], v[176:179], v[76:79]
	v_mfma_f32_16x16x32_bf16 v[72:75], v[236:239], v[184:187], v[72:75]
	s_setprio 0
	s_setprio 1
	v_mfma_f32_16x16x32_bf16 v[116:119], v[204:207], v[188:191], 0
	v_mfma_f32_16x16x32_bf16 v[112:115], v[204:207], v[196:199], 0
	v_mfma_f32_16x16x32_bf16 v[100:103], v[216:219], v[188:191], 0
	v_mfma_f32_16x16x32_bf16 v[96:99], v[216:219], v[196:199], 0
	v_mfma_f32_16x16x32_bf16 v[84:87], v[224:227], v[188:191], 0
	v_mfma_f32_16x16x32_bf16 v[80:83], v[224:227], v[196:199], 0
	v_mfma_f32_16x16x32_bf16 v[68:71], v[232:235], v[188:191], 0
	v_mfma_f32_16x16x32_bf16 v[64:67], v[232:235], v[196:199], 0
	v_mfma_f32_16x16x32_bf16 v[116:119], v[212:215], v[192:195], v[116:119]
	v_mfma_f32_16x16x32_bf16 v[112:115], v[212:215], v[200:203], v[112:115]
	v_mfma_f32_16x16x32_bf16 v[100:103], v[220:223], v[192:195], v[100:103]
	v_mfma_f32_16x16x32_bf16 v[96:99], v[220:223], v[200:203], v[96:99]
	v_mfma_f32_16x16x32_bf16 v[84:87], v[228:231], v[192:195], v[84:87]
	v_mfma_f32_16x16x32_bf16 v[80:83], v[228:231], v[200:203], v[80:83]
	v_mfma_f32_16x16x32_bf16 v[68:71], v[236:239], v[192:195], v[68:71]
	v_mfma_f32_16x16x32_bf16 v[64:67], v[236:239], v[200:203], v[64:67]
	s_setprio 0
	s_barrier
	v_readfirstlane_b32 s91, v148
	v_lshl_add_u64 v[146:147], s[14:15], 0, v[128:129]
	s_mov_b32 m0, s91
	v_readfirstlane_b32 s91, v149
	s_add_u32 s92, s14, 0x40000
	ds_read_b128 v[204:207], v167 offset:16384
	ds_read_b128 v[212:215], v167 offset:17408
	ds_read_b128 v[216:219], v168 offset:16384
	ds_read_b128 v[220:223], v168 offset:17408
	ds_read_b128 v[224:227], v169 offset:16384
	ds_read_b128 v[228:231], v169 offset:17408
	ds_read_b128 v[232:235], v170 offset:16384
	ds_read_b128 v[236:239], v170 offset:17408
	global_load_lds_dwordx4 v[146:147], off
	v_lshl_add_u64 v[208:209], s[14:15], 0, v[130:131]
	s_mov_b32 m0, s91
	s_addc_u32 s93, s15, 0
	v_readfirstlane_b32 s91, v150
	global_load_lds_dwordx4 v[208:209], off
	v_lshl_add_u64 v[240:241], s[92:93], 0, v[128:129]
	s_mov_b32 m0, s91
	v_readfirstlane_b32 s91, v151
	global_load_lds_dwordx4 v[240:241], off
	v_lshl_add_u64 v[240:241], s[92:93], 0, v[130:131]
	s_mov_b32 m0, s91
	v_readfirstlane_b32 s91, v152
	global_load_lds_dwordx4 v[240:241], off
	v_lshl_add_u64 v[240:241], s[66:67], 0, v[128:129]
	s_mov_b32 m0, s91
	v_readfirstlane_b32 s91, v153
	global_load_lds_dwordx4 v[240:241], off
	v_lshl_add_u64 v[242:243], s[66:67], 0, v[130:131]
	s_mov_b32 m0, s91
	s_nop 0
	global_load_lds_dwordx4 v[242:243], off
	s_waitcnt vmcnt(8)
	s_waitcnt lgkmcnt(0)
	s_barrier
; #define STAGE(P, g) do { const char* g_ = (const char*)(g); \
;         __builtin_amdgcn_global_load_lds((const unsigned*)(g_ + so0), (lds_u32*)((lds_u8*)(P) + sb0), 16, 0, 0); \
;         __builtin_amdgcn_global_load_lds((const unsigned*)(g_ + so1), (lds_u32*)((lds_u8*)(P) + sb0 + 8192), 16, 0, 0); } while (0)
; #define LDA(dst, b, h) for (int m = 0; m < 4; ++m) for (int k = 0; k < 2; ++k) \
;         dst[m][k] = *reinterpret_cast<const bf16x8*>((char*)SA(b, h) + lds_byte(wr * 64 + m * 16 + fr, k * 32 + fq * 8))
; #define LDB(dst, b, h) for (int n = 0; n < 2; ++n) for (int k = 0; k < 2; ++k) \
;         dst[n][k] = *reinterpret_cast<const bf16x8*>((char*)SB(b, h) + lds_byte(wc * 32 + n * 16 + fr, k * 32 + fq * 8))
; #define MMA(ai, bj, At_, Bt_) do { __builtin_amdgcn_s_setprio(1); \
;         for (int m = 0; m < 4; ++m) for (int n = 0; n < 2; ++n) for (int k = 0; k < 2; ++k) \
;             acc[ai][bj][m][n] = __builtin_amdgcn_mfma_f32_16x16x32_bf16(At_[m][k], Bt_[n][k], acc[ai][bj][m][n], 0, 0, 0); \
;         __builtin_amdgcn_s_setprio(0); } while (0)
; #define WAIT_V(n) asm volatile("s_waitcnt vmcnt(" #n ")" ::: "memory")
; #define WAIT_L(n) asm volatile("s_waitcnt lgkmcnt(" #n ")" ::: "memory")
; #define BAR __builtin_amdgcn_s_barrier()
; #define SCHED __builtin_amdgcn_sched_barrier(0)
; template <int EPI, int K, int LNI = -1>
; DI void ph_gemm(const Params& p, const bf16_t* __restrict__ A, const bf16_t* __restrict__ Bt, int N, float* s_aux) {
;     ...
;             WAIT_V(8); WAIT_L(0); BAR; MMA(1, 0, At, B0); MMA(1, 1, At, B1); BAR; SCHED;
;             LDB(B0, 1, 0); LDB(B1, 1, 1); SCHED; LDA(At, 1, 0); STAGE(SA(0, 1), a2 + hstep);
;             WAIT_V(8); WAIT_L(0); BAR; MMA(0, 0, At, B0); MMA(0, 1, At, B1); BAR; SCHED;
	s_setprio 1
	s_waitcnt lgkmcnt(0)
	v_mfma_f32_16x16x32_bf16 v[60:63], v[204:207], v[142:145], 0
	v_mfma_f32_16x16x32_bf16 v[56:59], v[204:207], v[180:183], 0
	v_mfma_f32_16x16x32_bf16 v[44:47], v[216:219], v[142:145], 0
	v_mfma_f32_16x16x32_bf16 v[40:43], v[216:219], v[180:183], 0
	v_mfma_f32_16x16x32_bf16 v[28:31], v[224:227], v[142:145], 0
	v_mfma_f32_16x16x32_bf16 v[24:27], v[224:227], v[180:183], 0
	v_mfma_f32_16x16x32_bf16 v[12:15], v[232:235], v[142:145], 0
	v_mfma_f32_16x16x32_bf16 v[8:11], v[232:235], v[180:183], 0
	v_mfma_f32_16x16x32_bf16 v[60:63], v[212:215], v[176:179], v[60:63]
	v_mfma_f32_16x16x32_bf16 v[56:59], v[212:215], v[184:187], v[56:59]
	v_mfma_f32_16x16x32_bf16 v[44:47], v[220:223], v[176:179], v[44:47]
	v_mfma_f32_16x16x32_bf16 v[40:43], v[220:223], v[184:187], v[40:43]
	v_mfma_f32_16x16x32_bf16 v[28:31], v[228:231], v[176:179], v[28:31]
	v_mfma_f32_16x16x32_bf16 v[24:27], v[228:231], v[184:187], v[24:27]
	v_mfma_f32_16x16x32_bf16 v[12:15], v[236:239], v[176:179], v[12:15]
	v_mfma_f32_16x16x32_bf16 v[8:11], v[236:239], v[184:187], v[8:11]
	s_setprio 0
	s_setprio 1
	v_mfma_f32_16x16x32_bf16 v[52:55], v[204:207], v[188:191], 0
	v_mfma_f32_16x16x32_bf16 v[48:51], v[204:207], v[196:199], 0
	v_mfma_f32_16x16x32_bf16 v[36:39], v[216:219], v[188:191], 0
	v_mfma_f32_16x16x32_bf16 v[32:35], v[216:219], v[196:199], 0
	v_mfma_f32_16x16x32_bf16 v[20:23], v[224:227], v[188:191], 0
	v_mfma_f32_16x16x32_bf16 v[16:19], v[224:227], v[196:199], 0
	v_mfma_f32_16x16x32_bf16 v[4:7], v[232:235], v[188:191], 0
	v_mfma_f32_16x16x32_bf16 v[0:3], v[232:235], v[196:199], 0
	v_mfma_f32_16x16x32_bf16 v[52:55], v[212:215], v[192:195], v[52:55]
	v_mfma_f32_16x16x32_bf16 v[48:51], v[212:215], v[200:203], v[48:51]
	v_mfma_f32_16x16x32_bf16 v[36:39], v[220:223], v[192:195], v[36:39]
	v_mfma_f32_16x16x32_bf16 v[32:35], v[220:223], v[200:203], v[32:35]
	v_mfma_f32_16x16x32_bf16 v[20:23], v[228:231], v[192:195], v[20:23]
	v_mfma_f32_16x16x32_bf16 v[16:19], v[228:231], v[200:203], v[16:19]
	v_mfma_f32_16x16x32_bf16 v[4:7], v[236:239], v[192:195], v[4:7]
	v_mfma_f32_16x16x32_bf16 v[0:3], v[236:239], v[200:203], v[0:3]
	s_setprio 0
	s_barrier
	ds_read_b128 v[142:145], v173
	ds_read_b128 v[176:179], v173 offset:1024
	ds_read_b128 v[180:183], v173 offset:2048
	ds_read_b128 v[184:187], v173 offset:3072
	ds_read_b128 v[188:191], v174
	ds_read_b128 v[192:195], v174 offset:1024
	ds_read_b128 v[196:199], v174 offset:2048
	ds_read_b128 v[200:203], v174 offset:3072
	s_add_u32 s66, s66, 0x40000
	s_addc_u32 s67, s67, 0
	v_readfirstlane_b32 s91, v154
	v_lshl_add_u64 v[244:245], s[66:67], 0, v[128:129]
	s_mov_b32 m0, s91
	ds_read_b128 v[204:207], v167 offset:32768
	ds_read_b128 v[212:215], v167 offset:33792
	ds_read_b128 v[216:219], v168 offset:32768
	ds_read_b128 v[220:223], v168 offset:33792
	ds_read_b128 v[224:227], v169 offset:32768
	ds_read_b128 v[228:231], v169 offset:33792
	ds_read_b128 v[232:235], v170 offset:32768
	ds_read_b128 v[236:239], v170 offset:33792
	global_load_lds_dwordx4 v[244:245], off
	v_lshl_add_u64 v[244:245], s[66:67], 0, v[130:131]
	v_readfirstlane_b32 s66, v155
	s_mov_b32 m0, s66
	s_nop 0
	global_load_lds_dwordx4 v[244:245], off
	s_waitcnt vmcnt(8)
	s_waitcnt lgkmcnt(0)
	s_barrier
	s_setprio 1
	s_waitcnt lgkmcnt(0)
	v_mfma_f32_16x16x32_bf16 v[124:127], v[204:207], v[142:145], v[124:127]
	v_mfma_f32_16x16x32_bf16 v[120:123], v[204:207], v[180:183], v[120:123]
	v_mfma_f32_16x16x32_bf16 v[108:111], v[216:219], v[142:145], v[108:111]
	v_mfma_f32_16x16x32_bf16 v[104:107], v[216:219], v[180:183], v[104:107]
	v_mfma_f32_16x16x32_bf16 v[92:95], v[224:227], v[142:145], v[92:95]
	v_mfma_f32_16x16x32_bf16 v[88:91], v[224:227], v[180:183], v[88:91]
	v_mfma_f32_16x16x32_bf16 v[76:79], v[232:235], v[142:145], v[76:79]
	v_mfma_f32_16x16x32_bf16 v[72:75], v[232:235], v[180:183], v[72:75]
	v_mfma_f32_16x16x32_bf16 v[124:127], v[212:215], v[176:179], v[124:127]
	v_mfma_f32_16x16x32_bf16 v[120:123], v[212:215], v[184:187], v[120:123]
	v_mfma_f32_16x16x32_bf16 v[108:111], v[220:223], v[176:179], v[108:111]
	v_mfma_f32_16x16x32_bf16 v[104:107], v[220:223], v[184:187], v[104:107]
	v_mfma_f32_16x16x32_bf16 v[92:95], v[228:231], v[176:179], v[92:95]
	v_mfma_f32_16x16x32_bf16 v[88:91], v[228:231], v[184:187], v[88:91]
	v_mfma_f32_16x16x32_bf16 v[76:79], v[236:239], v[176:179], v[76:79]
	v_mfma_f32_16x16x32_bf16 v[72:75], v[236:239], v[184:187], v[72:75]
	s_setprio 0
	s_setprio 1
	v_mfma_f32_16x16x32_bf16 v[116:119], v[204:207], v[188:191], v[116:119]
	v_mfma_f32_16x16x32_bf16 v[112:115], v[204:207], v[196:199], v[112:115]
	v_mfma_f32_16x16x32_bf16 v[100:103], v[216:219], v[188:191], v[100:103]
	v_mfma_f32_16x16x32_bf16 v[96:99], v[216:219], v[196:199], v[96:99]
	v_mfma_f32_16x16x32_bf16 v[84:87], v[224:227], v[188:191], v[84:87]
	v_mfma_f32_16x16x32_bf16 v[80:83], v[224:227], v[196:199], v[80:83]
	v_mfma_f32_16x16x32_bf16 v[68:71], v[232:235], v[188:191], v[68:71]
	v_mfma_f32_16x16x32_bf16 v[64:67], v[232:235], v[196:199], v[64:67]
	v_mfma_f32_16x16x32_bf16 v[116:119], v[212:215], v[192:195], v[116:119]
	v_mfma_f32_16x16x32_bf16 v[112:115], v[212:215], v[200:203], v[112:115]
	v_mfma_f32_16x16x32_bf16 v[100:103], v[220:223], v[192:195], v[100:103]
	v_mfma_f32_16x16x32_bf16 v[96:99], v[220:223], v[200:203], v[96:99]
	v_mfma_f32_16x16x32_bf16 v[84:87], v[228:231], v[192:195], v[84:87]
	v_mfma_f32_16x16x32_bf16 v[80:83], v[228:231], v[200:203], v[80:83]
	v_mfma_f32_16x16x32_bf16 v[68:71], v[236:239], v[192:195], v[68:71]
	v_mfma_f32_16x16x32_bf16 v[64:67], v[236:239], v[200:203], v[64:67]
	s_setprio 0
	s_barrier
; #define STAGE(P, g) do { const char* g_ = (const char*)(g); \
;         __builtin_amdgcn_global_load_lds((const unsigned*)(g_ + so0), (lds_u32*)((lds_u8*)(P) + sb0), 16, 0, 0); \
;         __builtin_amdgcn_global_load_lds((const unsigned*)(g_ + so1), (lds_u32*)((lds_u8*)(P) + sb0 + 8192), 16, 0, 0); } while (0)
; #define LDA(dst, b, h) for (int m = 0; m < 4; ++m) for (int k = 0; k < 2; ++k) \
;         dst[m][k] = *reinterpret_cast<const bf16x8*>((char*)SA(b, h) + lds_byte(wr * 64 + m * 16 + fr, k * 32 + fq * 8))
; #define MMA(ai, bj, At_, Bt_) do { __builtin_amdgcn_s_setprio(1); \
;         for (int m = 0; m < 4; ++m) for (int n = 0; n < 2; ++n) for (int k = 0; k < 2; ++k) \
;             acc[ai][bj][m][n] = __builtin_amdgcn_mfma_f32_16x16x32_bf16(At_[m][k], Bt_[n][k], acc[ai][bj][m][n], 0, 0, 0); \
;         __builtin_amdgcn_s_setprio(0); } while (0)
; #define WAIT_V(n) asm volatile("s_waitcnt vmcnt(" #n ")" ::: "memory")
; #define WAIT_L(n) asm volatile("s_waitcnt lgkmcnt(" #n ")" ::: "memory")
; #define BAR __builtin_amdgcn_s_barrier()
; #define SCHED __builtin_amdgcn_sched_barrier(0)
; template <int EPI, int K, int LNI = -1>
; DI void ph_gemm(const Params& p, const bf16_t* __restrict__ A, const bf16_t* __restrict__ Bt, int N, float* s_aux) {
;     ...
;         for (int t = 0; t < nt; t += 2) {
;     ...
;             LDA(At, 1, 1); STAGE(SB(1, 0), b3); STAGE(SB(1, 1), b3 + hstep); STAGE(SA(1, 0), a3);
;             WAIT_V(8); WAIT_L(0); BAR; MMA(1, 0, At, B0); MMA(1, 1, At, B1); BAR; SCHED;
	v_readfirstlane_b32 s66, v156
	v_lshl_add_u64 v[146:147], v[146:147], 0, s[28:29]
	s_mov_b32 m0, s66
	v_readfirstlane_b32 s66, v157
	s_add_u32 s14, s14, 0x40080
	ds_read_b128 v[204:207], v167 offset:49152
	ds_read_b128 v[212:215], v167 offset:50176
	ds_read_b128 v[216:219], v168 offset:49152
	ds_read_b128 v[220:223], v168 offset:50176
	ds_read_b128 v[224:227], v169 offset:49152
	ds_read_b128 v[228:231], v169 offset:50176
	ds_read_b128 v[232:235], v170 offset:49152
	ds_read_b128 v[236:239], v170 offset:50176
	global_load_lds_dwordx4 v[146:147], off
	v_lshl_add_u64 v[146:147], v[208:209], 0, s[28:29]
	s_mov_b32 m0, s66
	s_addc_u32 s15, s15, 0
	v_readfirstlane_b32 s66, v160
	global_load_lds_dwordx4 v[146:147], off
	v_lshl_add_u64 v[146:147], s[14:15], 0, v[128:129]
	s_mov_b32 m0, s66
	s_nop 0
	global_load_lds_dwordx4 v[146:147], off
	v_lshl_add_u64 v[146:147], s[14:15], 0, v[130:131]
	v_readfirstlane_b32 s14, v161
	s_mov_b32 m0, s14
	v_readfirstlane_b32 s14, v158
	global_load_lds_dwordx4 v[146:147], off
	v_lshl_add_u64 v[146:147], v[240:241], 0, s[28:29]
	s_mov_b32 m0, s14
	v_readfirstlane_b32 s14, v159
	global_load_lds_dwordx4 v[146:147], off
	v_lshl_add_u64 v[146:147], v[242:243], 0, s[28:29]
	s_mov_b32 m0, s14
	s_nop 0
	global_load_lds_dwordx4 v[146:147], off
	s_waitcnt vmcnt(8)
	s_waitcnt lgkmcnt(0)
	s_barrier
	s_setprio 1
	s_waitcnt lgkmcnt(0)
	v_mfma_f32_16x16x32_bf16 v[60:63], v[204:207], v[142:145], v[60:63]
	v_mfma_f32_16x16x32_bf16 v[56:59], v[204:207], v[180:183], v[56:59]
	v_mfma_f32_16x16x32_bf16 v[44:47], v[216:219], v[142:145], v[44:47]
	v_mfma_f32_16x16x32_bf16 v[40:43], v[216:219], v[180:183], v[40:43]
	v_mfma_f32_16x16x32_bf16 v[28:31], v[224:227], v[142:145], v[28:31]
	v_mfma_f32_16x16x32_bf16 v[24:27], v[224:227], v[180:183], v[24:27]
	v_mfma_f32_16x16x32_bf16 v[12:15], v[232:235], v[142:145], v[12:15]
	v_mfma_f32_16x16x32_bf16 v[8:11], v[232:235], v[180:183], v[8:11]
	v_mfma_f32_16x16x32_bf16 v[60:63], v[212:215], v[176:179], v[60:63]
	v_mfma_f32_16x16x32_bf16 v[56:59], v[212:215], v[184:187], v[56:59]
	v_mfma_f32_16x16x32_bf16 v[44:47], v[220:223], v[176:179], v[44:47]
	v_mfma_f32_16x16x32_bf16 v[40:43], v[220:223], v[184:187], v[40:43]
	v_mfma_f32_16x16x32_bf16 v[28:31], v[228:231], v[176:179], v[28:31]
	v_mfma_f32_16x16x32_bf16 v[24:27], v[228:231], v[184:187], v[24:27]
	v_mfma_f32_16x16x32_bf16 v[12:15], v[236:239], v[176:179], v[12:15]
	v_mfma_f32_16x16x32_bf16 v[8:11], v[236:239], v[184:187], v[8:11]
	s_setprio 0
	s_setprio 1
	v_mfma_f32_16x16x32_bf16 v[52:55], v[204:207], v[188:191], v[52:55]
	v_mfma_f32_16x16x32_bf16 v[48:51], v[204:207], v[196:199], v[48:51]
	v_mfma_f32_16x16x32_bf16 v[36:39], v[216:219], v[188:191], v[36:39]
	v_mfma_f32_16x16x32_bf16 v[32:35], v[216:219], v[196:199], v[32:35]
	v_mfma_f32_16x16x32_bf16 v[20:23], v[224:227], v[188:191], v[20:23]
	v_mfma_f32_16x16x32_bf16 v[16:19], v[224:227], v[196:199], v[16:19]
	v_mfma_f32_16x16x32_bf16 v[4:7], v[232:235], v[188:191], v[4:7]
	v_mfma_f32_16x16x32_bf16 v[0:3], v[232:235], v[196:199], v[0:3]
	v_mfma_f32_16x16x32_bf16 v[52:55], v[212:215], v[192:195], v[52:55]
	v_mfma_f32_16x16x32_bf16 v[48:51], v[212:215], v[200:203], v[48:51]
	v_mfma_f32_16x16x32_bf16 v[36:39], v[220:223], v[192:195], v[36:39]
	v_mfma_f32_16x16x32_bf16 v[32:35], v[220:223], v[200:203], v[32:35]
	v_mfma_f32_16x16x32_bf16 v[20:23], v[228:231], v[192:195], v[20:23]
	v_mfma_f32_16x16x32_bf16 v[16:19], v[228:231], v[200:203], v[16:19]
	v_mfma_f32_16x16x32_bf16 v[4:7], v[236:239], v[192:195], v[4:7]
	v_mfma_f32_16x16x32_bf16 v[0:3], v[236:239], v[200:203], v[0:3]
	s_setprio 0
	s_barrier
	s_add_i32 s80, s80, 2
	s_add_u32 s12, s12, 0x100
	s_addc_u32 s13, s13, 0
	s_cmp_gt_u32 s80, 13

; DI int opaque_tid() { int t = threadIdx.x; asm volatile("" : "+v"(t)); return t; }
; #define STAGE(P, g) do { const char* g_ = (const char*)(g); \
;         __builtin_amdgcn_global_load_lds((const unsigned*)(g_ + so0), (lds_u32*)((lds_u8*)(P) + sb0), 16, 0, 0); \
;         __builtin_amdgcn_global_load_lds((const unsigned*)(g_ + so1), (lds_u32*)((lds_u8*)(P) + sb0 + 8192), 16, 0, 0); } while (0)
; #define LDA(dst, b, h) for (int m = 0; m < 4; ++m) for (int k = 0; k < 2; ++k) \
;         dst[m][k] = *reinterpret_cast<const bf16x8*>((char*)SA(b, h) + lds_byte(wr * 64 + m * 16 + fr, k * 32 + fq * 8))
; template <int EPI, int K, int LNI = -1>
; DI void ph_gemm(const Params& p, const bf16_t* __restrict__ A, const bf16_t* __restrict__ Bt, int N, float* s_aux) {
;     ...
;         const int itn = it + (int)gridDim.x;
;         const bool has_next = itn < nwg;
;         int npm = pm, npn = pn;
;         if (has_next) unit(itn, npm, npn);
;         const bf16_t* nA = A + (size_t)npm * 256 * K; const bf16_t* nB = Bt + (size_t)npn * 256 * K;
;         const int brow = pm * 256, bcol = pn * 256;
;         float* sa = s_aux + (cnt & 1) * 512;
;         if (EPI == EPI_E5B) {
;             if (opaque_tid() < 256) {
;                 const int row = brow + (int)opaque_tid(); const int hd = bcol >> 9;
;                 const float* pp = (const float*)((unsigned char*)p.out + OFFO_PART) + (size_t)row * 256 + hd * 64;
;                 float sacc = 0.f;
; #pragma unroll
;                 for (int i = 0; i < 16; ++i) { const f32x4 v = *(const f32x4*)(pp + i * 4); sacc += (v[0] + v[1]) + (v[2] + v[3]); }
;                 sa[opaque_tid()] = __frsqrt_rn(sacc * (1.0f / 512.0f) + 1e-6f);
;             }
;         }
;         for (int t = 0; t < nt; t += 2) {
;             const bool last = (t == nt - 2);
;             const bf16_t* a1 = cA + (size_t)(t + 1) * kstep;
;             const bf16_t* a2 = last ? nA : cA + (size_t)(t + 2) * kstep; const bf16_t* b2 = last ? nB : cB + (size_t)(t + 2) * kstep;
;             const bf16_t* a3 = a2 + kstep; const bf16_t* b3 = b2 + kstep;
;             LDB(B0, 0, 0); LDB(B1, 0, 1); SCHED; LDA(At, 0, 0); STAGE(SA(1, 1), a1 + hstep);
;             WAIT_V(8); WAIT_L(0); BAR; MMA(0, 0, At, B0); MMA(0, 1, At, B1); BAR; SCHED;
;             LDA(At, 0, 1); STAGE(SB(0, 0), b2); STAGE(SB(0, 1), b2 + hstep); STAGE(SA(0, 0), a2);
.LBB0_1635:
	s_or_b64 exec, exec, s[48:49]
	s_ashr_i32 s45, s44, 31
	s_lshl_b64 s[48:49], s[44:45], 19
	s_add_u32 s43, s40, s48
	s_addc_u32 s45, s41, s49
	s_ashr_i32 s47, s46, 31
	s_lshl_b64 s[50:51], s[46:47], 19
	s_add_u32 s47, s22, s50
	s_addc_u32 s71, s23, s51
	s_add_u32 s72, s56, s12
	s_addc_u32 s73, s57, s13
	s_add_u32 s74, s66, s14
	v_lshl_add_u64 v[128:129], v[142:143], 0, s[12:13]
	v_lshl_add_u64 v[130:131], v[144:145], 0, s[12:13]
	s_addc_u32 s75, s67, s15
	s_mov_b32 s76, -2
	s_mov_b64 s[12:13], 0
	s_waitcnt vmcnt(0)
	ds_read_b128 v[132:135], v183
	ds_read_b128 v[146:149], v183 offset:1024
	ds_read_b128 v[150:153], v183 offset:2048
	ds_read_b128 v[154:157], v183 offset:3072
	ds_read_b128 v[192:195], v184
	ds_read_b128 v[196:199], v184 offset:1024
	ds_read_b128 v[200:203], v184 offset:2048
	ds_read_b128 v[204:207], v184 offset:3072
	s_add_u32 s14, s72, s12
	s_addc_u32 s15, s73, s13
	s_add_u32 s14, s14, 0xb840100
	s_addc_u32 s15, s15, 0
	s_add_u32 s77, s74, s12
	s_addc_u32 s78, s75, s13
	s_cmpk_eq_i32 s12, 0x700
	s_cselect_b32 s53, s45, s15
	s_cselect_b32 s52, s43, s14
	s_cselect_b32 s15, s71, s78
	s_cselect_b32 s14, s47, s77
	v_add_u32_e32 v140, 0xc000, v162
	v_lshl_add_u64 v[208:209], v[128:129], 0, s[12:13]
	v_readfirstlane_b32 s77, v140
	v_add_u32_e32 v140, 0xe000, v162
	s_mov_b32 m0, s77
	v_readfirstlane_b32 s77, v140
	ds_read_b128 v[212:215], v185
	ds_read_b128 v[216:219], v185 offset:1024
	ds_read_b128 v[220:223], v186
	ds_read_b128 v[224:227], v186 offset:1024
	ds_read_b128 v[228:231], v187
	ds_read_b128 v[232:235], v187 offset:1024
	ds_read_b128 v[236:239], v188
	ds_read_b128 v[240:243], v188 offset:1024
	global_load_lds_dwordx4 v[208:209], off
	v_lshl_add_u64 v[208:209], v[130:131], 0, s[12:13]
	s_mov_b32 m0, s77
	s_nop 0
	global_load_lds_dwordx4 v[208:209], off
	s_waitcnt vmcnt(8)
	s_waitcnt lgkmcnt(0)
	s_barrier
	s_setprio 1
	s_waitcnt lgkmcnt(0)
	v_mfma_f32_16x16x32_bf16 v[124:127], v[212:215], v[132:135], 0
	v_mfma_f32_16x16x32_bf16 v[120:123], v[212:215], v[150:153], 0
	v_mfma_f32_16x16x32_bf16 v[108:111], v[220:223], v[132:135], 0
	v_mfma_f32_16x16x32_bf16 v[104:107], v[220:223], v[150:153], 0
	v_mfma_f32_16x16x32_bf16 v[92:95], v[228:231], v[132:135], 0
	v_mfma_f32_16x16x32_bf16 v[88:91], v[228:231], v[150:153], 0
	v_mfma_f32_16x16x32_bf16 v[76:79], v[236:239], v[132:135], 0
	v_mfma_f32_16x16x32_bf16 v[72:75], v[236:239], v[150:153], 0
	v_mfma_f32_16x16x32_bf16 v[124:127], v[216:219], v[146:149], v[124:127]
	v_mfma_f32_16x16x32_bf16 v[120:123], v[216:219], v[154:157], v[120:123]
	v_mfma_f32_16x16x32_bf16 v[108:111], v[224:227], v[146:149], v[108:111]
	v_mfma_f32_16x16x32_bf16 v[104:107], v[224:227], v[154:157], v[104:107]
	v_mfma_f32_16x16x32_bf16 v[92:95], v[232:235], v[146:149], v[92:95]
	v_mfma_f32_16x16x32_bf16 v[88:91], v[232:235], v[154:157], v[88:91]
	v_mfma_f32_16x16x32_bf16 v[76:79], v[240:243], v[146:149], v[76:79]
	v_mfma_f32_16x16x32_bf16 v[72:75], v[240:243], v[154:157], v[72:75]
	s_setprio 0
	s_setprio 1
	v_mfma_f32_16x16x32_bf16 v[116:119], v[212:215], v[192:195], 0
	v_mfma_f32_16x16x32_bf16 v[112:115], v[212:215], v[200:203], 0
	v_mfma_f32_16x16x32_bf16 v[100:103], v[220:223], v[192:195], 0
	v_mfma_f32_16x16x32_bf16 v[96:99], v[220:223], v[200:203], 0
	v_mfma_f32_16x16x32_bf16 v[84:87], v[228:231], v[192:195], 0
	v_mfma_f32_16x16x32_bf16 v[80:83], v[228:231], v[200:203], 0
	v_mfma_f32_16x16x32_bf16 v[68:71], v[236:239], v[192:195], 0
	v_mfma_f32_16x16x32_bf16 v[64:67], v[236:239], v[200:203], 0
	v_mfma_f32_16x16x32_bf16 v[116:119], v[216:219], v[196:199], v[116:119]
	v_mfma_f32_16x16x32_bf16 v[112:115], v[216:219], v[204:207], v[112:115]
	v_mfma_f32_16x16x32_bf16 v[100:103], v[224:227], v[196:199], v[100:103]
	v_mfma_f32_16x16x32_bf16 v[96:99], v[224:227], v[204:207], v[96:99]
	v_mfma_f32_16x16x32_bf16 v[84:87], v[232:235], v[196:199], v[84:87]
	v_mfma_f32_16x16x32_bf16 v[80:83], v[232:235], v[204:207], v[80:83]
	v_mfma_f32_16x16x32_bf16 v[68:71], v[240:243], v[196:199], v[68:71]
	v_mfma_f32_16x16x32_bf16 v[64:67], v[240:243], v[204:207], v[64:67]
	s_setprio 0
	s_barrier
	v_readfirstlane_b32 s77, v158
	v_lshl_add_u64 v[208:209], s[14:15], 0, v[136:137]
	s_mov_b32 m0, s77
	v_readfirstlane_b32 s77, v159
	s_add_u32 s78, s14, 0x40000
	ds_read_b128 v[212:215], v185 offset:16384
	ds_read_b128 v[216:219], v185 offset:17408
	ds_read_b128 v[220:223], v186 offset:16384
	ds_read_b128 v[224:227], v186 offset:17408
	ds_read_b128 v[228:231], v187 offset:16384
	ds_read_b128 v[232:235], v187 offset:17408
	ds_read_b128 v[236:239], v188 offset:16384
	ds_read_b128 v[240:243], v188 offset:17408
	global_load_lds_dwordx4 v[208:209], off
	v_lshl_add_u64 v[244:245], s[14:15], 0, v[138:139]
	s_mov_b32 m0, s77
	s_addc_u32 s79, s15, 0
	v_readfirstlane_b32 s77, v160
	global_load_lds_dwordx4 v[244:245], off
	v_lshl_add_u64 v[246:247], s[78:79], 0, v[136:137]
	s_mov_b32 m0, s77
	v_readfirstlane_b32 s77, v161
	global_load_lds_dwordx4 v[246:247], off
	v_lshl_add_u64 v[246:247], s[78:79], 0, v[138:139]
	s_mov_b32 m0, s77
	v_readfirstlane_b32 s77, v162
	global_load_lds_dwordx4 v[246:247], off
	v_lshl_add_u64 v[246:247], s[52:53], 0, v[136:137]
	s_mov_b32 m0, s77
	v_readfirstlane_b32 s77, v163
	global_load_lds_dwordx4 v[246:247], off
	v_lshl_add_u64 v[248:249], s[52:53], 0, v[138:139]
	s_mov_b32 m0, s77
	s_nop 0
	global_load_lds_dwordx4 v[248:249], off
	s_waitcnt vmcnt(8)
	s_waitcnt lgkmcnt(0)
	s_barrier
; #define STAGE(P, g) do { const char* g_ = (const char*)(g); \
;         __builtin_amdgcn_global_load_lds((const unsigned*)(g_ + so0), (lds_u32*)((lds_u8*)(P) + sb0), 16, 0, 0); \
;         __builtin_amdgcn_global_load_lds((const unsigned*)(g_ + so1), (lds_u32*)((lds_u8*)(P) + sb0 + 8192), 16, 0, 0); } while (0)
; #define LDA(dst, b, h) for (int m = 0; m < 4; ++m) for (int k = 0; k < 2; ++k) \
;         dst[m][k] = *reinterpret_cast<const bf16x8*>((char*)SA(b, h) + lds_byte(wr * 64 + m * 16 + fr, k * 32 + fq * 8))
; #define LDB(dst, b, h) for (int n = 0; n < 2; ++n) for (int k = 0; k < 2; ++k) \
;         dst[n][k] = *reinterpret_cast<const bf16x8*>((char*)SB(b, h) + lds_byte(wc * 32 + n * 16 + fr, k * 32 + fq * 8))
; #define MMA(ai, bj, At_, Bt_) do { __builtin_amdgcn_s_setprio(1); \
;         for (int m = 0; m < 4; ++m) for (int n = 0; n < 2; ++n) for (int k = 0; k < 2; ++k) \
;             acc[ai][bj][m][n] = __builtin_amdgcn_mfma_f32_16x16x32_bf16(At_[m][k], Bt_[n][k], acc[ai][bj][m][n], 0, 0, 0); \
;         __builtin_amdgcn_s_setprio(0); } while (0)
; #define WAIT_V(n) asm volatile("s_waitcnt vmcnt(" #n ")" ::: "memory")
; #define WAIT_L(n) asm volatile("s_waitcnt lgkmcnt(" #n ")" ::: "memory")
; #define BAR __builtin_amdgcn_s_barrier()
; #define SCHED __builtin_amdgcn_sched_barrier(0)
; template <int EPI, int K, int LNI = -1>
; DI void ph_gemm(const Params& p, const bf16_t* __restrict__ A, const bf16_t* __restrict__ Bt, int N, float* s_aux) {
;     ...
;             WAIT_V(8); WAIT_L(0); BAR; MMA(0, 0, At, B0); MMA(0, 1, At, B1); BAR; SCHED;
;             LDA(At, 0, 1); STAGE(SB(0, 0), b2); STAGE(SB(0, 1), b2 + hstep); STAGE(SA(0, 0), a2);
;             WAIT_V(8); WAIT_L(0); BAR; MMA(1, 0, At, B0); MMA(1, 1, At, B1); BAR; SCHED;
;             LDB(B0, 1, 0); LDB(B1, 1, 1); SCHED; LDA(At, 1, 0); STAGE(SA(0, 1), a2 + hstep);
;             WAIT_V(8); WAIT_L(0); BAR; MMA(0, 0, At, B0); MMA(0, 1, At, B1); BAR; SCHED;
	s_setprio 1
	s_waitcnt lgkmcnt(0)
	v_mfma_f32_16x16x32_bf16 v[60:63], v[212:215], v[132:135], 0
	v_mfma_f32_16x16x32_bf16 v[56:59], v[212:215], v[150:153], 0
	v_mfma_f32_16x16x32_bf16 v[44:47], v[220:223], v[132:135], 0
	v_mfma_f32_16x16x32_bf16 v[40:43], v[220:223], v[150:153], 0
	v_mfma_f32_16x16x32_bf16 v[28:31], v[228:231], v[132:135], 0
	v_mfma_f32_16x16x32_bf16 v[24:27], v[228:231], v[150:153], 0
	v_mfma_f32_16x16x32_bf16 v[12:15], v[236:239], v[132:135], 0
	v_mfma_f32_16x16x32_bf16 v[8:11], v[236:239], v[150:153], 0
	v_mfma_f32_16x16x32_bf16 v[60:63], v[216:219], v[146:149], v[60:63]
	v_mfma_f32_16x16x32_bf16 v[56:59], v[216:219], v[154:157], v[56:59]
	v_mfma_f32_16x16x32_bf16 v[44:47], v[224:227], v[146:149], v[44:47]
	v_mfma_f32_16x16x32_bf16 v[40:43], v[224:227], v[154:157], v[40:43]
	v_mfma_f32_16x16x32_bf16 v[28:31], v[232:235], v[146:149], v[28:31]
	v_mfma_f32_16x16x32_bf16 v[24:27], v[232:235], v[154:157], v[24:27]
	v_mfma_f32_16x16x32_bf16 v[12:15], v[240:243], v[146:149], v[12:15]
	v_mfma_f32_16x16x32_bf16 v[8:11], v[240:243], v[154:157], v[8:11]
	s_setprio 0
	s_setprio 1
	v_mfma_f32_16x16x32_bf16 v[52:55], v[212:215], v[192:195], 0
	v_mfma_f32_16x16x32_bf16 v[48:51], v[212:215], v[200:203], 0
	v_mfma_f32_16x16x32_bf16 v[36:39], v[220:223], v[192:195], 0
	v_mfma_f32_16x16x32_bf16 v[32:35], v[220:223], v[200:203], 0
	v_mfma_f32_16x16x32_bf16 v[20:23], v[228:231], v[192:195], 0
	v_mfma_f32_16x16x32_bf16 v[16:19], v[228:231], v[200:203], 0
	v_mfma_f32_16x16x32_bf16 v[4:7], v[236:239], v[192:195], 0
	v_mfma_f32_16x16x32_bf16 v[0:3], v[236:239], v[200:203], 0
	v_mfma_f32_16x16x32_bf16 v[52:55], v[216:219], v[196:199], v[52:55]
	v_mfma_f32_16x16x32_bf16 v[48:51], v[216:219], v[204:207], v[48:51]
	v_mfma_f32_16x16x32_bf16 v[36:39], v[224:227], v[196:199], v[36:39]
	v_mfma_f32_16x16x32_bf16 v[32:35], v[224:227], v[204:207], v[32:35]
	v_mfma_f32_16x16x32_bf16 v[20:23], v[232:235], v[196:199], v[20:23]
	v_mfma_f32_16x16x32_bf16 v[16:19], v[232:235], v[204:207], v[16:19]
	v_mfma_f32_16x16x32_bf16 v[4:7], v[240:243], v[196:199], v[4:7]
	v_mfma_f32_16x16x32_bf16 v[0:3], v[240:243], v[204:207], v[0:3]
	s_setprio 0
	s_barrier
	ds_read_b128 v[132:135], v189
	ds_read_b128 v[146:149], v189 offset:1024
	ds_read_b128 v[150:153], v189 offset:2048
	ds_read_b128 v[154:157], v189 offset:3072
	ds_read_b128 v[192:195], v190
	ds_read_b128 v[196:199], v190 offset:1024
	ds_read_b128 v[200:203], v190 offset:2048
	ds_read_b128 v[204:207], v190 offset:3072
	s_add_u32 s52, s52, 0x40000
	s_addc_u32 s53, s53, 0
	v_readfirstlane_b32 s77, v164
	v_lshl_add_u64 v[250:251], s[52:53], 0, v[136:137]
	s_mov_b32 m0, s77
	ds_read_b128 v[212:215], v185 offset:32768
	ds_read_b128 v[216:219], v185 offset:33792
	ds_read_b128 v[220:223], v186 offset:32768
	ds_read_b128 v[224:227], v186 offset:33792
	ds_read_b128 v[228:231], v187 offset:32768
	ds_read_b128 v[232:235], v187 offset:33792
	ds_read_b128 v[236:239], v188 offset:32768
	ds_read_b128 v[240:243], v188 offset:33792
	global_load_lds_dwordx4 v[250:251], off
	v_lshl_add_u64 v[250:251], s[52:53], 0, v[138:139]
	v_readfirstlane_b32 s52, v165
	s_mov_b32 m0, s52
	s_nop 0
	global_load_lds_dwordx4 v[250:251], off
	s_waitcnt vmcnt(8)
	s_waitcnt lgkmcnt(0)
	s_barrier
	s_setprio 1
	s_waitcnt lgkmcnt(0)
	v_mfma_f32_16x16x32_bf16 v[124:127], v[212:215], v[132:135], v[124:127]
	v_mfma_f32_16x16x32_bf16 v[120:123], v[212:215], v[150:153], v[120:123]
	v_mfma_f32_16x16x32_bf16 v[108:111], v[220:223], v[132:135], v[108:111]
	v_mfma_f32_16x16x32_bf16 v[104:107], v[220:223], v[150:153], v[104:107]
	v_mfma_f32_16x16x32_bf16 v[92:95], v[228:231], v[132:135], v[92:95]
	v_mfma_f32_16x16x32_bf16 v[88:91], v[228:231], v[150:153], v[88:91]
	v_mfma_f32_16x16x32_bf16 v[76:79], v[236:239], v[132:135], v[76:79]
	v_mfma_f32_16x16x32_bf16 v[72:75], v[236:239], v[150:153], v[72:75]
	v_mfma_f32_16x16x32_bf16 v[124:127], v[216:219], v[146:149], v[124:127]
	v_mfma_f32_16x16x32_bf16 v[120:123], v[216:219], v[154:157], v[120:123]
	v_mfma_f32_16x16x32_bf16 v[108:111], v[224:227], v[146:149], v[108:111]
	v_mfma_f32_16x16x32_bf16 v[104:107], v[224:227], v[154:157], v[104:107]
	v_mfma_f32_16x16x32_bf16 v[92:95], v[232:235], v[146:149], v[92:95]
	v_mfma_f32_16x16x32_bf16 v[88:91], v[232:235], v[154:157], v[88:91]
	v_mfma_f32_16x16x32_bf16 v[76:79], v[240:243], v[146:149], v[76:79]
	v_mfma_f32_16x16x32_bf16 v[72:75], v[240:243], v[154:157], v[72:75]
	s_setprio 0
	s_setprio 1
	v_mfma_f32_16x16x32_bf16 v[116:119], v[212:215], v[192:195], v[116:119]
	v_mfma_f32_16x16x32_bf16 v[112:115], v[212:215], v[200:203], v[112:115]
	v_mfma_f32_16x16x32_bf16 v[100:103], v[220:223], v[192:195], v[100:103]
	v_mfma_f32_16x16x32_bf16 v[96:99], v[220:223], v[200:203], v[96:99]
	v_mfma_f32_16x16x32_bf16 v[84:87], v[228:231], v[192:195], v[84:87]
	v_mfma_f32_16x16x32_bf16 v[80:83], v[228:231], v[200:203], v[80:83]
	v_mfma_f32_16x16x32_bf16 v[68:71], v[236:239], v[192:195], v[68:71]
	v_mfma_f32_16x16x32_bf16 v[64:67], v[236:239], v[200:203], v[64:67]
	v_mfma_f32_16x16x32_bf16 v[116:119], v[216:219], v[196:199], v[116:119]
	v_mfma_f32_16x16x32_bf16 v[112:115], v[216:219], v[204:207], v[112:115]
	v_mfma_f32_16x16x32_bf16 v[100:103], v[224:227], v[196:199], v[100:103]
	v_mfma_f32_16x16x32_bf16 v[96:99], v[224:227], v[204:207], v[96:99]
	v_mfma_f32_16x16x32_bf16 v[84:87], v[232:235], v[196:199], v[84:87]
	v_mfma_f32_16x16x32_bf16 v[80:83], v[232:235], v[204:207], v[80:83]
	v_mfma_f32_16x16x32_bf16 v[68:71], v[240:243], v[196:199], v[68:71]
	v_mfma_f32_16x16x32_bf16 v[64:67], v[240:243], v[204:207], v[64:67]
	s_setprio 0
	s_barrier
; #define STAGE(P, g) do { const char* g_ = (const char*)(g); \
;         __builtin_amdgcn_global_load_lds((const unsigned*)(g_ + so0), (lds_u32*)((lds_u8*)(P) + sb0), 16, 0, 0); \
;         __builtin_amdgcn_global_load_lds((const unsigned*)(g_ + so1), (lds_u32*)((lds_u8*)(P) + sb0 + 8192), 16, 0, 0); } while (0)
; #define LDA(dst, b, h) for (int m = 0; m < 4; ++m) for (int k = 0; k < 2; ++k) \
;         dst[m][k] = *reinterpret_cast<const bf16x8*>((char*)SA(b, h) + lds_byte(wr * 64 + m * 16 + fr, k * 32 + fq * 8))
; #define MMA(ai, bj, At_, Bt_) do { __builtin_amdgcn_s_setprio(1); \
;         for (int m = 0; m < 4; ++m) for (int n = 0; n < 2; ++n) for (int k = 0; k < 2; ++k) \
;             acc[ai][bj][m][n] = __builtin_amdgcn_mfma_f32_16x16x32_bf16(At_[m][k], Bt_[n][k], acc[ai][bj][m][n], 0, 0, 0); \
;         __builtin_amdgcn_s_setprio(0); } while (0)
; #define WAIT_V(n) asm volatile("s_waitcnt vmcnt(" #n ")" ::: "memory")
; #define WAIT_L(n) asm volatile("s_waitcnt lgkmcnt(" #n ")" ::: "memory")
; #define BAR __builtin_amdgcn_s_barrier()
; #define SCHED __builtin_amdgcn_sched_barrier(0)
; template <int EPI, int K, int LNI = -1>
; DI void ph_gemm(const Params& p, const bf16_t* __restrict__ A, const bf16_t* __restrict__ Bt, int N, float* s_aux) {
;     ...
;         for (int t = 0; t < nt; t += 2) {
;     ...
;             LDA(At, 1, 1); STAGE(SB(1, 0), b3); STAGE(SB(1, 1), b3 + hstep); STAGE(SA(1, 0), a3);
;             WAIT_V(8); WAIT_L(0); BAR; MMA(1, 0, At, B0); MMA(1, 1, At, B1); BAR; SCHED;
	v_readfirstlane_b32 s52, v166
	v_lshl_add_u64 v[208:209], v[208:209], 0, s[26:27]
	s_mov_b32 m0, s52
	v_readfirstlane_b32 s52, v167
	s_add_u32 s14, s14, 0x40080
	ds_read_b128 v[212:215], v185 offset:49152
	ds_read_b128 v[216:219], v185 offset:50176
	ds_read_b128 v[220:223], v186 offset:49152
	ds_read_b128 v[224:227], v186 offset:50176
	ds_read_b128 v[228:231], v187 offset:49152
	ds_read_b128 v[232:235], v187 offset:50176
	ds_read_b128 v[236:239], v188 offset:49152
	ds_read_b128 v[240:243], v188 offset:50176
	global_load_lds_dwordx4 v[208:209], off
	v_lshl_add_u64 v[208:209], v[244:245], 0, s[26:27]
	s_mov_b32 m0, s52
	s_addc_u32 s15, s15, 0
	v_readfirstlane_b32 s52, v170
	global_load_lds_dwordx4 v[208:209], off
	v_lshl_add_u64 v[208:209], s[14:15], 0, v[136:137]
	s_mov_b32 m0, s52
	s_nop 0
	global_load_lds_dwordx4 v[208:209], off
	v_lshl_add_u64 v[208:209], s[14:15], 0, v[138:139]
	v_readfirstlane_b32 s14, v171
	s_mov_b32 m0, s14
	v_readfirstlane_b32 s14, v168
	global_load_lds_dwordx4 v[208:209], off
	v_lshl_add_u64 v[208:209], v[246:247], 0, s[26:27]
	s_mov_b32 m0, s14
	v_readfirstlane_b32 s14, v169
	global_load_lds_dwordx4 v[208:209], off
	v_lshl_add_u64 v[208:209], v[248:249], 0, s[26:27]
	s_mov_b32 m0, s14
	s_nop 0
	global_load_lds_dwordx4 v[208:209], off
	s_waitcnt vmcnt(8)
	s_waitcnt lgkmcnt(0)
	s_barrier
	s_setprio 1
	s_waitcnt lgkmcnt(0)
	v_mfma_f32_16x16x32_bf16 v[60:63], v[212:215], v[132:135], v[60:63]
	v_mfma_f32_16x16x32_bf16 v[56:59], v[212:215], v[150:153], v[56:59]
	v_mfma_f32_16x16x32_bf16 v[44:47], v[220:223], v[132:135], v[44:47]
	v_mfma_f32_16x16x32_bf16 v[40:43], v[220:223], v[150:153], v[40:43]
	v_mfma_f32_16x16x32_bf16 v[28:31], v[228:231], v[132:135], v[28:31]
	v_mfma_f32_16x16x32_bf16 v[24:27], v[228:231], v[150:153], v[24:27]
	v_mfma_f32_16x16x32_bf16 v[12:15], v[236:239], v[132:135], v[12:15]
	v_mfma_f32_16x16x32_bf16 v[8:11], v[236:239], v[150:153], v[8:11]
	v_mfma_f32_16x16x32_bf16 v[60:63], v[216:219], v[146:149], v[60:63]
	v_mfma_f32_16x16x32_bf16 v[56:59], v[216:219], v[154:157], v[56:59]
	v_mfma_f32_16x16x32_bf16 v[44:47], v[224:227], v[146:149], v[44:47]
	v_mfma_f32_16x16x32_bf16 v[40:43], v[224:227], v[154:157], v[40:43]
	v_mfma_f32_16x16x32_bf16 v[28:31], v[232:235], v[146:149], v[28:31]
	v_mfma_f32_16x16x32_bf16 v[24:27], v[232:235], v[154:157], v[24:27]
	v_mfma_f32_16x16x32_bf16 v[12:15], v[240:243], v[146:149], v[12:15]
	v_mfma_f32_16x16x32_bf16 v[8:11], v[240:243], v[154:157], v[8:11]
	s_setprio 0
	s_setprio 1
	v_mfma_f32_16x16x32_bf16 v[52:55], v[212:215], v[192:195], v[52:55]
	v_mfma_f32_16x16x32_bf16 v[48:51], v[212:215], v[200:203], v[48:51]
	v_mfma_f32_16x16x32_bf16 v[36:39], v[220:223], v[192:195], v[36:39]
	v_mfma_f32_16x16x32_bf16 v[32:35], v[220:223], v[200:203], v[32:35]
	v_mfma_f32_16x16x32_bf16 v[20:23], v[228:231], v[192:195], v[20:23]
	v_mfma_f32_16x16x32_bf16 v[16:19], v[228:231], v[200:203], v[16:19]
	v_mfma_f32_16x16x32_bf16 v[4:7], v[236:239], v[192:195], v[4:7]
	v_mfma_f32_16x16x32_bf16 v[0:3], v[236:239], v[200:203], v[0:3]
	v_mfma_f32_16x16x32_bf16 v[52:55], v[216:219], v[196:199], v[52:55]
	v_mfma_f32_16x16x32_bf16 v[48:51], v[216:219], v[204:207], v[48:51]
	v_mfma_f32_16x16x32_bf16 v[36:39], v[224:227], v[196:199], v[36:39]
	v_mfma_f32_16x16x32_bf16 v[32:35], v[224:227], v[204:207], v[32:35]
	v_mfma_f32_16x16x32_bf16 v[20:23], v[232:235], v[196:199], v[20:23]
	v_mfma_f32_16x16x32_bf16 v[16:19], v[232:235], v[204:207], v[16:19]
	v_mfma_f32_16x16x32_bf16 v[4:7], v[240:243], v[196:199], v[4:7]
	v_mfma_f32_16x16x32_bf16 v[0:3], v[240:243], v[204:207], v[0:3]
	s_setprio 0
	s_barrier
	s_add_i32 s76, s76, 2
	s_add_u32 s12, s12, 0x100
	s_addc_u32 s13, s13, 0
	s_cmp_gt_u32 s76, 13

; DI int opaque_tid() { int t = threadIdx.x; asm volatile("" : "+v"(t)); return t; }
; #define STAGE(P, g) do { const char* g_ = (const char*)(g); \
;         __builtin_amdgcn_global_load_lds((const unsigned*)(g_ + so0), (lds_u32*)((lds_u8*)(P) + sb0), 16, 0, 0); \
;         __builtin_amdgcn_global_load_lds((const unsigned*)(g_ + so1), (lds_u32*)((lds_u8*)(P) + sb0 + 8192), 16, 0, 0); } while (0)
; #define LDA(dst, b, h) for (int m = 0; m < 4; ++m) for (int k = 0; k < 2; ++k) \
;         dst[m][k] = *reinterpret_cast<const bf16x8*>((char*)SA(b, h) + lds_byte(wr * 64 + m * 16 + fr, k * 32 + fq * 8))
; template <int EPI, int K, int LNI = -1>
; DI void ph_gemm(const Params& p, const bf16_t* __restrict__ A, const bf16_t* __restrict__ Bt, int N, float* s_aux) {
;     ...
;         const int itn = it + (int)gridDim.x;
;         const bool has_next = itn < nwg;
;         int npm = pm, npn = pn;
;         if (has_next) unit(itn, npm, npn);
;         const bf16_t* nA = A + (size_t)npm * 256 * K; const bf16_t* nB = Bt + (size_t)npn * 256 * K;
;         const int brow = pm * 256, bcol = pn * 256;
;         float* sa = s_aux + (cnt & 1) * 512;
;         if (EPI == EPI_E5B) {
;             if (opaque_tid() < 256) {
;                 const int row = brow + (int)opaque_tid(); const int hd = bcol >> 9;
;                 const float* pp = (const float*)((unsigned char*)p.out + OFFO_PART) + (size_t)row * 256 + hd * 64;
;                 float sacc = 0.f;
; #pragma unroll
;                 for (int i = 0; i < 16; ++i) { const f32x4 v = *(const f32x4*)(pp + i * 4); sacc += (v[0] + v[1]) + (v[2] + v[3]); }
;                 sa[opaque_tid()] = __frsqrt_rn(sacc * (1.0f / 512.0f) + 1e-6f);
;             }
;         }
;         for (int t = 0; t < nt; t += 2) {
;             const bool last = (t == nt - 2);
;             const bf16_t* a1 = cA + (size_t)(t + 1) * kstep;
;             const bf16_t* a2 = last ? nA : cA + (size_t)(t + 2) * kstep; const bf16_t* b2 = last ? nB : cB + (size_t)(t + 2) * kstep;
;             const bf16_t* a3 = a2 + kstep; const bf16_t* b3 = b2 + kstep;
;             LDB(B0, 0, 0); LDB(B1, 0, 1); SCHED; LDA(At, 0, 0); STAGE(SA(1, 1), a1 + hstep);
;             WAIT_V(8); WAIT_L(0); BAR; MMA(0, 0, At, B0); MMA(0, 1, At, B1); BAR; SCHED;
;             LDA(At, 0, 1); STAGE(SB(0, 0), b2); STAGE(SB(0, 1), b2 + hstep); STAGE(SA(0, 0), a2);
.LBB0_1716:
	s_ashr_i32 s21, s20, 31
	s_lshl_b64 s[22:23], s[20:21], 20
	s_add_u32 s21, s36, s22
	s_addc_u32 s52, s37, s23
	s_ashr_i32 s15, s14, 31
	s_lshl_b64 s[24:25], s[14:15], 20
	s_add_u32 s15, s3, s24
	s_addc_u32 s53, s35, s25
	s_add_u32 s60, s56, s42
	s_addc_u32 s61, s57, s43
	s_add_u32 s66, s48, s44
	v_lshl_add_u64 v[128:129], v[140:141], 0, s[42:43]
	v_lshl_add_u64 v[130:131], v[142:143], 0, s[42:43]
	s_addc_u32 s67, s49, s45
	s_mov_b32 s68, -2
	s_mov_b64 s[42:43], 0
	ds_read_b128 v[132:135], v177
	ds_read_b128 v[144:147], v177 offset:1024
	ds_read_b128 v[148:151], v177 offset:2048
	ds_read_b128 v[152:155], v177 offset:3072
	ds_read_b128 v[156:159], v178
	ds_read_b128 v[188:191], v178 offset:1024
	ds_read_b128 v[192:195], v178 offset:2048
	ds_read_b128 v[196:199], v178 offset:3072
	s_add_u32 s44, s60, s42
	s_addc_u32 s45, s61, s43
	s_add_u32 s44, s44, 0xfa70100
	s_addc_u32 s45, s45, 0
	s_add_u32 s69, s66, s42
	s_addc_u32 s70, s67, s43
	s_cmpk_eq_i32 s42, 0xf00
	s_cselect_b32 s47, s52, s45
	s_cselect_b32 s46, s21, s44
	s_cselect_b32 s45, s53, s70
	s_cselect_b32 s44, s15, s69
	v_readfirstlane_b32 s69, v183
	v_lshl_add_u64 v[208:209], v[128:129], 0, s[42:43]
	s_mov_b32 m0, s69
	v_readfirstlane_b32 s69, v184
	ds_read_b128 v[200:203], v179
	ds_read_b128 v[204:207], v179 offset:1024
	ds_read_b128 v[212:215], v180
	ds_read_b128 v[216:219], v180 offset:1024
	ds_read_b128 v[220:223], v181
	ds_read_b128 v[224:227], v181 offset:1024
	ds_read_b128 v[228:231], v182
	ds_read_b128 v[232:235], v182 offset:1024
	global_load_lds_dwordx4 v[208:209], off
	v_lshl_add_u64 v[208:209], v[130:131], 0, s[42:43]
	s_mov_b32 m0, s69
	s_nop 0
	global_load_lds_dwordx4 v[208:209], off
	s_waitcnt vmcnt(8)
	s_waitcnt lgkmcnt(0)
	s_barrier
	s_setprio 1
	s_waitcnt lgkmcnt(0)
	v_mfma_f32_16x16x32_bf16 v[124:127], v[200:203], v[132:135], 0
	v_mfma_f32_16x16x32_bf16 v[120:123], v[200:203], v[148:151], 0
	v_mfma_f32_16x16x32_bf16 v[108:111], v[212:215], v[132:135], 0
	v_mfma_f32_16x16x32_bf16 v[104:107], v[212:215], v[148:151], 0
	v_mfma_f32_16x16x32_bf16 v[92:95], v[220:223], v[132:135], 0
	v_mfma_f32_16x16x32_bf16 v[88:91], v[220:223], v[148:151], 0
	v_mfma_f32_16x16x32_bf16 v[76:79], v[228:231], v[132:135], 0
	v_mfma_f32_16x16x32_bf16 v[72:75], v[228:231], v[148:151], 0
	v_mfma_f32_16x16x32_bf16 v[124:127], v[204:207], v[144:147], v[124:127]
	v_mfma_f32_16x16x32_bf16 v[120:123], v[204:207], v[152:155], v[120:123]
	v_mfma_f32_16x16x32_bf16 v[108:111], v[216:219], v[144:147], v[108:111]
	v_mfma_f32_16x16x32_bf16 v[104:107], v[216:219], v[152:155], v[104:107]
	v_mfma_f32_16x16x32_bf16 v[92:95], v[224:227], v[144:147], v[92:95]
	v_mfma_f32_16x16x32_bf16 v[88:91], v[224:227], v[152:155], v[88:91]
	v_mfma_f32_16x16x32_bf16 v[76:79], v[232:235], v[144:147], v[76:79]
	v_mfma_f32_16x16x32_bf16 v[72:75], v[232:235], v[152:155], v[72:75]
	s_setprio 0
	s_setprio 1
	v_mfma_f32_16x16x32_bf16 v[116:119], v[200:203], v[156:159], 0
	v_mfma_f32_16x16x32_bf16 v[112:115], v[200:203], v[192:195], 0
	v_mfma_f32_16x16x32_bf16 v[100:103], v[212:215], v[156:159], 0
	v_mfma_f32_16x16x32_bf16 v[96:99], v[212:215], v[192:195], 0
	v_mfma_f32_16x16x32_bf16 v[84:87], v[220:223], v[156:159], 0
	v_mfma_f32_16x16x32_bf16 v[80:83], v[220:223], v[192:195], 0
	v_mfma_f32_16x16x32_bf16 v[68:71], v[228:231], v[156:159], 0
	v_mfma_f32_16x16x32_bf16 v[64:67], v[228:231], v[192:195], 0
	v_mfma_f32_16x16x32_bf16 v[116:119], v[204:207], v[188:191], v[116:119]
	v_mfma_f32_16x16x32_bf16 v[112:115], v[204:207], v[196:199], v[112:115]
	v_mfma_f32_16x16x32_bf16 v[100:103], v[216:219], v[188:191], v[100:103]
	v_mfma_f32_16x16x32_bf16 v[96:99], v[216:219], v[196:199], v[96:99]
	v_mfma_f32_16x16x32_bf16 v[84:87], v[224:227], v[188:191], v[84:87]
	v_mfma_f32_16x16x32_bf16 v[80:83], v[224:227], v[196:199], v[80:83]
	v_mfma_f32_16x16x32_bf16 v[68:71], v[232:235], v[188:191], v[68:71]
	v_mfma_f32_16x16x32_bf16 v[64:67], v[232:235], v[196:199], v[64:67]
	s_setprio 0
	s_barrier
	v_readfirstlane_b32 s69, v160
	v_lshl_add_u64 v[208:209], s[44:45], 0, v[136:137]
	s_mov_b32 m0, s69
	v_readfirstlane_b32 s69, v161
	s_add_u32 s70, s44, 0x80000
	ds_read_b128 v[200:203], v179 offset:16384
	ds_read_b128 v[204:207], v179 offset:17408
	ds_read_b128 v[212:215], v180 offset:16384
	ds_read_b128 v[216:219], v180 offset:17408
	ds_read_b128 v[220:223], v181 offset:16384
	ds_read_b128 v[224:227], v181 offset:17408
	ds_read_b128 v[228:231], v182 offset:16384
	ds_read_b128 v[232:235], v182 offset:17408
	global_load_lds_dwordx4 v[208:209], off
	v_lshl_add_u64 v[236:237], s[44:45], 0, v[138:139]
	s_mov_b32 m0, s69
	s_addc_u32 s71, s45, 0
	v_readfirstlane_b32 s69, v162
	global_load_lds_dwordx4 v[236:237], off
	v_lshl_add_u64 v[238:239], s[70:71], 0, v[136:137]
	s_mov_b32 m0, s69
	v_readfirstlane_b32 s69, v163
	global_load_lds_dwordx4 v[238:239], off
	v_lshl_add_u64 v[238:239], s[70:71], 0, v[138:139]
	s_mov_b32 m0, s69
	v_readfirstlane_b32 s69, v164
	global_load_lds_dwordx4 v[238:239], off
	v_lshl_add_u64 v[238:239], s[46:47], 0, v[136:137]
	s_mov_b32 m0, s69
	v_readfirstlane_b32 s69, v165
	global_load_lds_dwordx4 v[238:239], off
	v_lshl_add_u64 v[240:241], s[46:47], 0, v[138:139]
	s_mov_b32 m0, s69
	s_nop 0
	global_load_lds_dwordx4 v[240:241], off
	s_waitcnt vmcnt(8)
	s_waitcnt lgkmcnt(0)
	s_barrier
; #define STAGE(P, g) do { const char* g_ = (const char*)(g); \
;         __builtin_amdgcn_global_load_lds((const unsigned*)(g_ + so0), (lds_u32*)((lds_u8*)(P) + sb0), 16, 0, 0); \
;         __builtin_amdgcn_global_load_lds((const unsigned*)(g_ + so1), (lds_u32*)((lds_u8*)(P) + sb0 + 8192), 16, 0, 0); } while (0)
; #define LDA(dst, b, h) for (int m = 0; m < 4; ++m) for (int k = 0; k < 2; ++k) \
;         dst[m][k] = *reinterpret_cast<const bf16x8*>((char*)SA(b, h) + lds_byte(wr * 64 + m * 16 + fr, k * 32 + fq * 8))
; #define LDB(dst, b, h) for (int n = 0; n < 2; ++n) for (int k = 0; k < 2; ++k) \
;         dst[n][k] = *reinterpret_cast<const bf16x8*>((char*)SB(b, h) + lds_byte(wc * 32 + n * 16 + fr, k * 32 + fq * 8))
; #define MMA(ai, bj, At_, Bt_) do { __builtin_amdgcn_s_setprio(1); \
;         for (int m = 0; m < 4; ++m) for (int n = 0; n < 2; ++n) for (int k = 0; k < 2; ++k) \
;             acc[ai][bj][m][n] = __builtin_amdgcn_mfma_f32_16x16x32_bf16(At_[m][k], Bt_[n][k], acc[ai][bj][m][n], 0, 0, 0); \
;         __builtin_amdgcn_s_setprio(0); } while (0)
; #define WAIT_V(n) asm volatile("s_waitcnt vmcnt(" #n ")" ::: "memory")
; #define WAIT_L(n) asm volatile("s_waitcnt lgkmcnt(" #n ")" ::: "memory")
; #define BAR __builtin_amdgcn_s_barrier()
; #define SCHED __builtin_amdgcn_sched_barrier(0)
; template <int EPI, int K, int LNI = -1>
; DI void ph_gemm(const Params& p, const bf16_t* __restrict__ A, const bf16_t* __restrict__ Bt, int N, float* s_aux) {
;     ...
;             WAIT_V(8); WAIT_L(0); BAR; MMA(0, 0, At, B0); MMA(0, 1, At, B1); BAR; SCHED;
;             LDA(At, 0, 1); STAGE(SB(0, 0), b2); STAGE(SB(0, 1), b2 + hstep); STAGE(SA(0, 0), a2);
;             WAIT_V(8); WAIT_L(0); BAR; MMA(1, 0, At, B0); MMA(1, 1, At, B1); BAR; SCHED;
;             LDB(B0, 1, 0); LDB(B1, 1, 1); SCHED; LDA(At, 1, 0); STAGE(SA(0, 1), a2 + hstep);
;             WAIT_V(8); WAIT_L(0); BAR; MMA(0, 0, At, B0); MMA(0, 1, At, B1); BAR; SCHED;
	s_setprio 1
	s_waitcnt lgkmcnt(0)
	v_mfma_f32_16x16x32_bf16 v[60:63], v[200:203], v[132:135], 0
	v_mfma_f32_16x16x32_bf16 v[56:59], v[200:203], v[148:151], 0
	v_mfma_f32_16x16x32_bf16 v[44:47], v[212:215], v[132:135], 0
	v_mfma_f32_16x16x32_bf16 v[40:43], v[212:215], v[148:151], 0
	v_mfma_f32_16x16x32_bf16 v[28:31], v[220:223], v[132:135], 0
	v_mfma_f32_16x16x32_bf16 v[24:27], v[220:223], v[148:151], 0
	v_mfma_f32_16x16x32_bf16 v[12:15], v[228:231], v[132:135], 0
	v_mfma_f32_16x16x32_bf16 v[8:11], v[228:231], v[148:151], 0
	v_mfma_f32_16x16x32_bf16 v[60:63], v[204:207], v[144:147], v[60:63]
	v_mfma_f32_16x16x32_bf16 v[56:59], v[204:207], v[152:155], v[56:59]
	v_mfma_f32_16x16x32_bf16 v[44:47], v[216:219], v[144:147], v[44:47]
	v_mfma_f32_16x16x32_bf16 v[40:43], v[216:219], v[152:155], v[40:43]
	v_mfma_f32_16x16x32_bf16 v[28:31], v[224:227], v[144:147], v[28:31]
	v_mfma_f32_16x16x32_bf16 v[24:27], v[224:227], v[152:155], v[24:27]
	v_mfma_f32_16x16x32_bf16 v[12:15], v[232:235], v[144:147], v[12:15]
	v_mfma_f32_16x16x32_bf16 v[8:11], v[232:235], v[152:155], v[8:11]
	s_setprio 0
	s_setprio 1
	v_mfma_f32_16x16x32_bf16 v[52:55], v[200:203], v[156:159], 0
	v_mfma_f32_16x16x32_bf16 v[48:51], v[200:203], v[192:195], 0
	v_mfma_f32_16x16x32_bf16 v[36:39], v[212:215], v[156:159], 0
	v_mfma_f32_16x16x32_bf16 v[32:35], v[212:215], v[192:195], 0
	v_mfma_f32_16x16x32_bf16 v[20:23], v[220:223], v[156:159], 0
	v_mfma_f32_16x16x32_bf16 v[16:19], v[220:223], v[192:195], 0
	v_mfma_f32_16x16x32_bf16 v[4:7], v[228:231], v[156:159], 0
	v_mfma_f32_16x16x32_bf16 v[0:3], v[228:231], v[192:195], 0
	v_mfma_f32_16x16x32_bf16 v[52:55], v[204:207], v[188:191], v[52:55]
	v_mfma_f32_16x16x32_bf16 v[48:51], v[204:207], v[196:199], v[48:51]
	v_mfma_f32_16x16x32_bf16 v[36:39], v[216:219], v[188:191], v[36:39]
	v_mfma_f32_16x16x32_bf16 v[32:35], v[216:219], v[196:199], v[32:35]
	v_mfma_f32_16x16x32_bf16 v[20:23], v[224:227], v[188:191], v[20:23]
	v_mfma_f32_16x16x32_bf16 v[16:19], v[224:227], v[196:199], v[16:19]
	v_mfma_f32_16x16x32_bf16 v[4:7], v[232:235], v[188:191], v[4:7]
	v_mfma_f32_16x16x32_bf16 v[0:3], v[232:235], v[196:199], v[0:3]
	s_setprio 0
	s_barrier
	ds_read_b128 v[132:135], v185
	ds_read_b128 v[144:147], v185 offset:1024
	ds_read_b128 v[148:151], v185 offset:2048
	ds_read_b128 v[152:155], v185 offset:3072
	ds_read_b128 v[156:159], v186
	ds_read_b128 v[188:191], v186 offset:1024
	ds_read_b128 v[192:195], v186 offset:2048
	ds_read_b128 v[196:199], v186 offset:3072
	s_add_u32 s46, s46, 0x80000
	s_addc_u32 s47, s47, 0
	v_readfirstlane_b32 s69, v166
	v_lshl_add_u64 v[242:243], s[46:47], 0, v[136:137]
	s_mov_b32 m0, s69
	ds_read_b128 v[200:203], v179 offset:32768
	ds_read_b128 v[204:207], v179 offset:33792
	ds_read_b128 v[212:215], v180 offset:32768
	ds_read_b128 v[216:219], v180 offset:33792
	ds_read_b128 v[220:223], v181 offset:32768
	ds_read_b128 v[224:227], v181 offset:33792
	ds_read_b128 v[228:231], v182 offset:32768
	ds_read_b128 v[232:235], v182 offset:33792
	global_load_lds_dwordx4 v[242:243], off
	v_lshl_add_u64 v[242:243], s[46:47], 0, v[138:139]
	v_readfirstlane_b32 s46, v167
	s_mov_b32 m0, s46
	s_nop 0
	global_load_lds_dwordx4 v[242:243], off
	s_waitcnt vmcnt(8)
	s_waitcnt lgkmcnt(0)
	s_barrier
	s_setprio 1
	s_waitcnt lgkmcnt(0)
	v_mfma_f32_16x16x32_bf16 v[124:127], v[200:203], v[132:135], v[124:127]
	v_mfma_f32_16x16x32_bf16 v[120:123], v[200:203], v[148:151], v[120:123]
	v_mfma_f32_16x16x32_bf16 v[108:111], v[212:215], v[132:135], v[108:111]
	v_mfma_f32_16x16x32_bf16 v[104:107], v[212:215], v[148:151], v[104:107]
	v_mfma_f32_16x16x32_bf16 v[92:95], v[220:223], v[132:135], v[92:95]
	v_mfma_f32_16x16x32_bf16 v[88:91], v[220:223], v[148:151], v[88:91]
	v_mfma_f32_16x16x32_bf16 v[76:79], v[228:231], v[132:135], v[76:79]
	v_mfma_f32_16x16x32_bf16 v[72:75], v[228:231], v[148:151], v[72:75]
	v_mfma_f32_16x16x32_bf16 v[124:127], v[204:207], v[144:147], v[124:127]
	v_mfma_f32_16x16x32_bf16 v[120:123], v[204:207], v[152:155], v[120:123]
	v_mfma_f32_16x16x32_bf16 v[108:111], v[216:219], v[144:147], v[108:111]
	v_mfma_f32_16x16x32_bf16 v[104:107], v[216:219], v[152:155], v[104:107]
	v_mfma_f32_16x16x32_bf16 v[92:95], v[224:227], v[144:147], v[92:95]
	v_mfma_f32_16x16x32_bf16 v[88:91], v[224:227], v[152:155], v[88:91]
	v_mfma_f32_16x16x32_bf16 v[76:79], v[232:235], v[144:147], v[76:79]
	v_mfma_f32_16x16x32_bf16 v[72:75], v[232:235], v[152:155], v[72:75]
	s_setprio 0
	s_setprio 1
	v_mfma_f32_16x16x32_bf16 v[116:119], v[200:203], v[156:159], v[116:119]
	v_mfma_f32_16x16x32_bf16 v[112:115], v[200:203], v[192:195], v[112:115]
	v_mfma_f32_16x16x32_bf16 v[100:103], v[212:215], v[156:159], v[100:103]
	v_mfma_f32_16x16x32_bf16 v[96:99], v[212:215], v[192:195], v[96:99]
	v_mfma_f32_16x16x32_bf16 v[84:87], v[220:223], v[156:159], v[84:87]
	v_mfma_f32_16x16x32_bf16 v[80:83], v[220:223], v[192:195], v[80:83]
	v_mfma_f32_16x16x32_bf16 v[68:71], v[228:231], v[156:159], v[68:71]
	v_mfma_f32_16x16x32_bf16 v[64:67], v[228:231], v[192:195], v[64:67]
	v_mfma_f32_16x16x32_bf16 v[116:119], v[204:207], v[188:191], v[116:119]
	v_mfma_f32_16x16x32_bf16 v[112:115], v[204:207], v[196:199], v[112:115]
	v_mfma_f32_16x16x32_bf16 v[100:103], v[216:219], v[188:191], v[100:103]
	v_mfma_f32_16x16x32_bf16 v[96:99], v[216:219], v[196:199], v[96:99]
	v_mfma_f32_16x16x32_bf16 v[84:87], v[224:227], v[188:191], v[84:87]
	v_mfma_f32_16x16x32_bf16 v[80:83], v[224:227], v[196:199], v[80:83]
	v_mfma_f32_16x16x32_bf16 v[68:71], v[232:235], v[188:191], v[68:71]
	v_mfma_f32_16x16x32_bf16 v[64:67], v[232:235], v[196:199], v[64:67]
	s_setprio 0
	s_barrier
; #define STAGE(P, g) do { const char* g_ = (const char*)(g); \
;         __builtin_amdgcn_global_load_lds((const unsigned*)(g_ + so0), (lds_u32*)((lds_u8*)(P) + sb0), 16, 0, 0); \
;         __builtin_amdgcn_global_load_lds((const unsigned*)(g_ + so1), (lds_u32*)((lds_u8*)(P) + sb0 + 8192), 16, 0, 0); } while (0)
; #define LDA(dst, b, h) for (int m = 0; m < 4; ++m) for (int k = 0; k < 2; ++k) \
;         dst[m][k] = *reinterpret_cast<const bf16x8*>((char*)SA(b, h) + lds_byte(wr * 64 + m * 16 + fr, k * 32 + fq * 8))
; #define MMA(ai, bj, At_, Bt_) do { __builtin_amdgcn_s_setprio(1); \
;         for (int m = 0; m < 4; ++m) for (int n = 0; n < 2; ++n) for (int k = 0; k < 2; ++k) \
;             acc[ai][bj][m][n] = __builtin_amdgcn_mfma_f32_16x16x32_bf16(At_[m][k], Bt_[n][k], acc[ai][bj][m][n], 0, 0, 0); \
;         __builtin_amdgcn_s_setprio(0); } while (0)
; #define WAIT_V(n) asm volatile("s_waitcnt vmcnt(" #n ")" ::: "memory")
; #define WAIT_L(n) asm volatile("s_waitcnt lgkmcnt(" #n ")" ::: "memory")
; #define BAR __builtin_amdgcn_s_barrier()
; #define SCHED __builtin_amdgcn_sched_barrier(0)
; template <int EPI, int K, int LNI = -1>
; DI void ph_gemm(const Params& p, const bf16_t* __restrict__ A, const bf16_t* __restrict__ Bt, int N, float* s_aux) {
;     ...
;         for (int t = 0; t < nt; t += 2) {
;     ...
;             LDA(At, 1, 1); STAGE(SB(1, 0), b3); STAGE(SB(1, 1), b3 + hstep); STAGE(SA(1, 0), a3);
;             WAIT_V(8); WAIT_L(0); BAR; MMA(1, 0, At, B0); MMA(1, 1, At, B1); BAR; SCHED;
	v_readfirstlane_b32 s46, v168
	v_lshl_add_u64 v[208:209], v[208:209], 0, s[10:11]
	s_mov_b32 m0, s46
	v_readfirstlane_b32 s46, v169
	s_add_u32 s44, s44, 0x80080
	ds_read_b128 v[200:203], v179 offset:49152
	ds_read_b128 v[204:207], v179 offset:50176
	ds_read_b128 v[212:215], v180 offset:49152
	ds_read_b128 v[216:219], v180 offset:50176
	ds_read_b128 v[220:223], v181 offset:49152
	ds_read_b128 v[224:227], v181 offset:50176
	ds_read_b128 v[228:231], v182 offset:49152
	ds_read_b128 v[232:235], v182 offset:50176
	global_load_lds_dwordx4 v[208:209], off
	v_lshl_add_u64 v[208:209], v[236:237], 0, s[10:11]
	s_mov_b32 m0, s46
	s_addc_u32 s45, s45, 0
	v_readfirstlane_b32 s46, v172
	global_load_lds_dwordx4 v[208:209], off
	v_lshl_add_u64 v[208:209], s[44:45], 0, v[136:137]
	s_mov_b32 m0, s46
	s_nop 0
	global_load_lds_dwordx4 v[208:209], off
	v_lshl_add_u64 v[208:209], s[44:45], 0, v[138:139]
	v_readfirstlane_b32 s44, v173
	s_mov_b32 m0, s44
	v_readfirstlane_b32 s44, v170
	global_load_lds_dwordx4 v[208:209], off
	v_lshl_add_u64 v[208:209], v[238:239], 0, s[10:11]
	s_mov_b32 m0, s44
	v_readfirstlane_b32 s44, v171
	global_load_lds_dwordx4 v[208:209], off
	v_lshl_add_u64 v[208:209], v[240:241], 0, s[10:11]
	s_mov_b32 m0, s44
	s_nop 0
	global_load_lds_dwordx4 v[208:209], off
	s_waitcnt vmcnt(8)
	s_waitcnt lgkmcnt(0)
	s_barrier
	s_setprio 1
	s_waitcnt lgkmcnt(0)
	v_mfma_f32_16x16x32_bf16 v[60:63], v[200:203], v[132:135], v[60:63]
	v_mfma_f32_16x16x32_bf16 v[56:59], v[200:203], v[148:151], v[56:59]
	v_mfma_f32_16x16x32_bf16 v[44:47], v[212:215], v[132:135], v[44:47]
	v_mfma_f32_16x16x32_bf16 v[40:43], v[212:215], v[148:151], v[40:43]
	v_mfma_f32_16x16x32_bf16 v[28:31], v[220:223], v[132:135], v[28:31]
	v_mfma_f32_16x16x32_bf16 v[24:27], v[220:223], v[148:151], v[24:27]
	v_mfma_f32_16x16x32_bf16 v[12:15], v[228:231], v[132:135], v[12:15]
	v_mfma_f32_16x16x32_bf16 v[8:11], v[228:231], v[148:151], v[8:11]
	v_mfma_f32_16x16x32_bf16 v[60:63], v[204:207], v[144:147], v[60:63]
	v_mfma_f32_16x16x32_bf16 v[56:59], v[204:207], v[152:155], v[56:59]
	v_mfma_f32_16x16x32_bf16 v[44:47], v[216:219], v[144:147], v[44:47]
	v_mfma_f32_16x16x32_bf16 v[40:43], v[216:219], v[152:155], v[40:43]
	v_mfma_f32_16x16x32_bf16 v[28:31], v[224:227], v[144:147], v[28:31]
	v_mfma_f32_16x16x32_bf16 v[24:27], v[224:227], v[152:155], v[24:27]
	v_mfma_f32_16x16x32_bf16 v[12:15], v[232:235], v[144:147], v[12:15]
	v_mfma_f32_16x16x32_bf16 v[8:11], v[232:235], v[152:155], v[8:11]
	s_setprio 0
	s_setprio 1
	v_mfma_f32_16x16x32_bf16 v[52:55], v[200:203], v[156:159], v[52:55]
	v_mfma_f32_16x16x32_bf16 v[48:51], v[200:203], v[192:195], v[48:51]
	v_mfma_f32_16x16x32_bf16 v[36:39], v[212:215], v[156:159], v[36:39]
	v_mfma_f32_16x16x32_bf16 v[32:35], v[212:215], v[192:195], v[32:35]
	v_mfma_f32_16x16x32_bf16 v[20:23], v[220:223], v[156:159], v[20:23]
	v_mfma_f32_16x16x32_bf16 v[16:19], v[220:223], v[192:195], v[16:19]
	v_mfma_f32_16x16x32_bf16 v[4:7], v[228:231], v[156:159], v[4:7]
	v_mfma_f32_16x16x32_bf16 v[0:3], v[228:231], v[192:195], v[0:3]
	v_mfma_f32_16x16x32_bf16 v[52:55], v[204:207], v[188:191], v[52:55]
	v_mfma_f32_16x16x32_bf16 v[48:51], v[204:207], v[196:199], v[48:51]
	v_mfma_f32_16x16x32_bf16 v[36:39], v[216:219], v[188:191], v[36:39]
	v_mfma_f32_16x16x32_bf16 v[32:35], v[216:219], v[196:199], v[32:35]
	v_mfma_f32_16x16x32_bf16 v[20:23], v[224:227], v[188:191], v[20:23]
	v_mfma_f32_16x16x32_bf16 v[16:19], v[224:227], v[196:199], v[16:19]
	v_mfma_f32_16x16x32_bf16 v[4:7], v[232:235], v[188:191], v[4:7]
	v_mfma_f32_16x16x32_bf16 v[0:3], v[232:235], v[196:199], v[0:3]
	s_setprio 0
	s_barrier
	s_add_i32 s68, s68, 2
	s_add_u32 s42, s42, 0x100
	s_addc_u32 s43, s43, 0
	s_cmp_gt_u32 s68, 29

; DI int opaque_tid() { int t = threadIdx.x; asm volatile("" : "+v"(t)); return t; }
; #define STAGE(P, g) do { const char* g_ = (const char*)(g); \
;         __builtin_amdgcn_global_load_lds((const unsigned*)(g_ + so0), (lds_u32*)((lds_u8*)(P) + sb0), 16, 0, 0); \
;         __builtin_amdgcn_global_load_lds((const unsigned*)(g_ + so1), (lds_u32*)((lds_u8*)(P) + sb0 + 8192), 16, 0, 0); } while (0)
; #define LDA(dst, b, h) for (int m = 0; m < 4; ++m) for (int k = 0; k < 2; ++k) \
;         dst[m][k] = *reinterpret_cast<const bf16x8*>((char*)SA(b, h) + lds_byte(wr * 64 + m * 16 + fr, k * 32 + fq * 8))
; template <int EPI, int K, int LNI = -1>
; DI void ph_gemm(const Params& p, const bf16_t* __restrict__ A, const bf16_t* __restrict__ Bt, int N, float* s_aux) {
;     ...
;         const int itn = it + (int)gridDim.x;
;         const bool has_next = itn < nwg;
;         int npm = pm, npn = pn;
;         if (has_next) unit(itn, npm, npn);
;         const bf16_t* nA = A + (size_t)npm * 256 * K; const bf16_t* nB = Bt + (size_t)npn * 256 * K;
;         const int brow = pm * 256, bcol = pn * 256;
;         float* sa = s_aux + (cnt & 1) * 512;
;         if (EPI == EPI_E5B) {
;             if (opaque_tid() < 256) {
;                 const int row = brow + (int)opaque_tid(); const int hd = bcol >> 9;
;                 const float* pp = (const float*)((unsigned char*)p.out + OFFO_PART) + (size_t)row * 256 + hd * 64;
;                 float sacc = 0.f;
; #pragma unroll
;                 for (int i = 0; i < 16; ++i) { const f32x4 v = *(const f32x4*)(pp + i * 4); sacc += (v[0] + v[1]) + (v[2] + v[3]); }
;                 sa[opaque_tid()] = __frsqrt_rn(sacc * (1.0f / 512.0f) + 1e-6f);
;             }
;         }
;         for (int t = 0; t < nt; t += 2) {
;             const bool last = (t == nt - 2);
;             const bf16_t* a1 = cA + (size_t)(t + 1) * kstep;
;             const bf16_t* a2 = last ? nA : cA + (size_t)(t + 2) * kstep; const bf16_t* b2 = last ? nB : cB + (size_t)(t + 2) * kstep;
;             const bf16_t* a3 = a2 + kstep; const bf16_t* b3 = b2 + kstep;
;             LDB(B0, 0, 0); LDB(B1, 0, 1); SCHED; LDA(At, 0, 0); STAGE(SA(1, 1), a1 + hstep);
;             WAIT_V(8); WAIT_L(0); BAR; MMA(0, 0, At, B0); MMA(0, 1, At, B1); BAR; SCHED;
;             LDA(At, 0, 1); STAGE(SB(0, 0), b2); STAGE(SB(0, 1), b2 + hstep); STAGE(SA(0, 0), a2);
.LBB0_1852:
	s_ashr_i32 s21, s20, 31
	s_lshl_b64 s[24:25], s[20:21], 19
	s_add_u32 s21, s40, s24
	s_addc_u32 s52, s41, s25
	s_ashr_i32 s23, s22, 31
	s_lshl_b64 s[26:27], s[22:23], 19
	s_add_u32 s23, s10, s26
	s_addc_u32 s53, s11, s27
	s_add_u32 s60, s56, s44
	s_addc_u32 s61, s57, s45
	s_add_u32 s66, s43, s46
	v_lshl_add_u64 v[136:137], v[132:133], 0, s[44:45]
	v_lshl_add_u64 v[138:139], v[134:135], 0, s[44:45]
	s_addc_u32 s67, s50, s47
	s_mov_b32 s68, -2
	s_mov_b64 s[44:45], 0
	ds_read_b128 v[166:169], v156
	ds_read_b128 v[170:173], v156 offset:1024
	ds_read_b128 v[174:177], v156 offset:2048
	ds_read_b128 v[178:181], v156 offset:3072
	ds_read_b128 v[182:185], v157
	ds_read_b128 v[186:189], v157 offset:1024
	ds_read_b128 v[190:193], v157 offset:2048
	ds_read_b128 v[194:197], v157 offset:3072
	s_add_u32 s46, s60, s44
	s_addc_u32 s47, s61, s45
	s_add_u32 s46, s46, 0xb840100
	s_addc_u32 s47, s47, 0
	s_add_u32 s69, s66, s44
	s_addc_u32 s70, s67, s45
	s_cmpk_eq_i32 s44, 0x700
	s_cselect_b32 s49, s52, s47
	s_cselect_b32 s48, s21, s46
	s_cselect_b32 s47, s53, s70
	s_cselect_b32 s46, s23, s69
	v_readfirstlane_b32 s69, v162
	v_lshl_add_u64 v[232:233], v[136:137], 0, s[44:45]
	s_mov_b32 m0, s69
	v_readfirstlane_b32 s69, v163
	ds_read_b128 v[198:201], v158
	ds_read_b128 v[202:205], v158 offset:1024
	ds_read_b128 v[206:209], v159
	ds_read_b128 v[212:215], v159 offset:1024
	ds_read_b128 v[216:219], v160
	ds_read_b128 v[220:223], v160 offset:1024
	ds_read_b128 v[224:227], v161
	ds_read_b128 v[228:231], v161 offset:1024
	global_load_lds_dwordx4 v[232:233], off
	v_lshl_add_u64 v[232:233], v[138:139], 0, s[44:45]
	s_mov_b32 m0, s69
	s_nop 0
	global_load_lds_dwordx4 v[232:233], off
	s_waitcnt vmcnt(8)
	s_waitcnt lgkmcnt(0)
	s_barrier
	s_setprio 1
	s_waitcnt lgkmcnt(0)
	v_mfma_f32_16x16x32_bf16 v[124:127], v[198:201], v[166:169], 0
	v_mfma_f32_16x16x32_bf16 v[120:123], v[198:201], v[174:177], 0
	v_mfma_f32_16x16x32_bf16 v[108:111], v[206:209], v[166:169], 0
	v_mfma_f32_16x16x32_bf16 v[104:107], v[206:209], v[174:177], 0
	v_mfma_f32_16x16x32_bf16 v[92:95], v[216:219], v[166:169], 0
	v_mfma_f32_16x16x32_bf16 v[88:91], v[216:219], v[174:177], 0
	v_mfma_f32_16x16x32_bf16 v[76:79], v[224:227], v[166:169], 0
	v_mfma_f32_16x16x32_bf16 v[72:75], v[224:227], v[174:177], 0
	v_mfma_f32_16x16x32_bf16 v[124:127], v[202:205], v[170:173], v[124:127]
	v_mfma_f32_16x16x32_bf16 v[120:123], v[202:205], v[178:181], v[120:123]
	v_mfma_f32_16x16x32_bf16 v[108:111], v[212:215], v[170:173], v[108:111]
	v_mfma_f32_16x16x32_bf16 v[104:107], v[212:215], v[178:181], v[104:107]
	v_mfma_f32_16x16x32_bf16 v[92:95], v[220:223], v[170:173], v[92:95]
	v_mfma_f32_16x16x32_bf16 v[88:91], v[220:223], v[178:181], v[88:91]
	v_mfma_f32_16x16x32_bf16 v[76:79], v[228:231], v[170:173], v[76:79]
	v_mfma_f32_16x16x32_bf16 v[72:75], v[228:231], v[178:181], v[72:75]
	s_setprio 0
	s_setprio 1
	v_mfma_f32_16x16x32_bf16 v[116:119], v[198:201], v[182:185], 0
	v_mfma_f32_16x16x32_bf16 v[112:115], v[198:201], v[190:193], 0
	v_mfma_f32_16x16x32_bf16 v[100:103], v[206:209], v[182:185], 0
	v_mfma_f32_16x16x32_bf16 v[96:99], v[206:209], v[190:193], 0
	v_mfma_f32_16x16x32_bf16 v[84:87], v[216:219], v[182:185], 0
	v_mfma_f32_16x16x32_bf16 v[80:83], v[216:219], v[190:193], 0
	v_mfma_f32_16x16x32_bf16 v[68:71], v[224:227], v[182:185], 0
	v_mfma_f32_16x16x32_bf16 v[64:67], v[224:227], v[190:193], 0
	v_mfma_f32_16x16x32_bf16 v[116:119], v[202:205], v[186:189], v[116:119]
	v_mfma_f32_16x16x32_bf16 v[112:115], v[202:205], v[194:197], v[112:115]
	v_mfma_f32_16x16x32_bf16 v[100:103], v[212:215], v[186:189], v[100:103]
	v_mfma_f32_16x16x32_bf16 v[96:99], v[212:215], v[194:197], v[96:99]
	v_mfma_f32_16x16x32_bf16 v[84:87], v[220:223], v[186:189], v[84:87]
	v_mfma_f32_16x16x32_bf16 v[80:83], v[220:223], v[194:197], v[80:83]
	v_mfma_f32_16x16x32_bf16 v[68:71], v[228:231], v[186:189], v[68:71]
	v_mfma_f32_16x16x32_bf16 v[64:67], v[228:231], v[194:197], v[64:67]
	s_setprio 0
	s_barrier
	v_readfirstlane_b32 s69, v140
	v_lshl_add_u64 v[232:233], s[46:47], 0, v[128:129]
	s_mov_b32 m0, s69
	v_readfirstlane_b32 s69, v141
	s_add_u32 s70, s46, 0x40000
	ds_read_b128 v[198:201], v158 offset:16384
	ds_read_b128 v[202:205], v158 offset:17408
	ds_read_b128 v[206:209], v159 offset:16384
	ds_read_b128 v[212:215], v159 offset:17408
	ds_read_b128 v[216:219], v160 offset:16384
	ds_read_b128 v[220:223], v160 offset:17408
	ds_read_b128 v[224:227], v161 offset:16384
	ds_read_b128 v[228:231], v161 offset:17408
	global_load_lds_dwordx4 v[232:233], off
	v_lshl_add_u64 v[234:235], s[46:47], 0, v[130:131]
	s_mov_b32 m0, s69
	s_addc_u32 s71, s47, 0
	v_readfirstlane_b32 s69, v142
	global_load_lds_dwordx4 v[234:235], off
	v_lshl_add_u64 v[236:237], s[70:71], 0, v[128:129]
	s_mov_b32 m0, s69
	v_readfirstlane_b32 s69, v143
	global_load_lds_dwordx4 v[236:237], off
	v_lshl_add_u64 v[236:237], s[70:71], 0, v[130:131]
	s_mov_b32 m0, s69
	v_readfirstlane_b32 s69, v144
	global_load_lds_dwordx4 v[236:237], off
	v_lshl_add_u64 v[236:237], s[48:49], 0, v[128:129]
	s_mov_b32 m0, s69
	v_readfirstlane_b32 s69, v145
	global_load_lds_dwordx4 v[236:237], off
	v_lshl_add_u64 v[238:239], s[48:49], 0, v[130:131]
	s_mov_b32 m0, s69
	s_nop 0
	global_load_lds_dwordx4 v[238:239], off
	s_waitcnt vmcnt(8)
	s_waitcnt lgkmcnt(0)
	s_barrier
; #define STAGE(P, g) do { const char* g_ = (const char*)(g); \
;         __builtin_amdgcn_global_load_lds((const unsigned*)(g_ + so0), (lds_u32*)((lds_u8*)(P) + sb0), 16, 0, 0); \
;         __builtin_amdgcn_global_load_lds((const unsigned*)(g_ + so1), (lds_u32*)((lds_u8*)(P) + sb0 + 8192), 16, 0, 0); } while (0)
; #define LDA(dst, b, h) for (int m = 0; m < 4; ++m) for (int k = 0; k < 2; ++k) \
;         dst[m][k] = *reinterpret_cast<const bf16x8*>((char*)SA(b, h) + lds_byte(wr * 64 + m * 16 + fr, k * 32 + fq * 8))
; #define LDB(dst, b, h) for (int n = 0; n < 2; ++n) for (int k = 0; k < 2; ++k) \
;         dst[n][k] = *reinterpret_cast<const bf16x8*>((char*)SB(b, h) + lds_byte(wc * 32 + n * 16 + fr, k * 32 + fq * 8))
; #define MMA(ai, bj, At_, Bt_) do { __builtin_amdgcn_s_setprio(1); \
;         for (int m = 0; m < 4; ++m) for (int n = 0; n < 2; ++n) for (int k = 0; k < 2; ++k) \
;             acc[ai][bj][m][n] = __builtin_amdgcn_mfma_f32_16x16x32_bf16(At_[m][k], Bt_[n][k], acc[ai][bj][m][n], 0, 0, 0); \
;         __builtin_amdgcn_s_setprio(0); } while (0)
; #define WAIT_V(n) asm volatile("s_waitcnt vmcnt(" #n ")" ::: "memory")
; #define WAIT_L(n) asm volatile("s_waitcnt lgkmcnt(" #n ")" ::: "memory")
; #define BAR __builtin_amdgcn_s_barrier()
; #define SCHED __builtin_amdgcn_sched_barrier(0)
; template <int EPI, int K, int LNI = -1>
; DI void ph_gemm(const Params& p, const bf16_t* __restrict__ A, const bf16_t* __restrict__ Bt, int N, float* s_aux) {
;     ...
;             WAIT_V(8); WAIT_L(0); BAR; MMA(0, 0, At, B0); MMA(0, 1, At, B1); BAR; SCHED;
;             LDA(At, 0, 1); STAGE(SB(0, 0), b2); STAGE(SB(0, 1), b2 + hstep); STAGE(SA(0, 0), a2);
;             WAIT_V(8); WAIT_L(0); BAR; MMA(1, 0, At, B0); MMA(1, 1, At, B1); BAR; SCHED;
;             LDB(B0, 1, 0); LDB(B1, 1, 1); SCHED; LDA(At, 1, 0); STAGE(SA(0, 1), a2 + hstep);
;             WAIT_V(8); WAIT_L(0); BAR; MMA(0, 0, At, B0); MMA(0, 1, At, B1); BAR; SCHED;
	s_setprio 1
	s_waitcnt lgkmcnt(0)
	v_mfma_f32_16x16x32_bf16 v[60:63], v[198:201], v[166:169], 0
	v_mfma_f32_16x16x32_bf16 v[56:59], v[198:201], v[174:177], 0
	v_mfma_f32_16x16x32_bf16 v[44:47], v[206:209], v[166:169], 0
	v_mfma_f32_16x16x32_bf16 v[40:43], v[206:209], v[174:177], 0
	v_mfma_f32_16x16x32_bf16 v[28:31], v[216:219], v[166:169], 0
	v_mfma_f32_16x16x32_bf16 v[24:27], v[216:219], v[174:177], 0
	v_mfma_f32_16x16x32_bf16 v[12:15], v[224:227], v[166:169], 0
	v_mfma_f32_16x16x32_bf16 v[8:11], v[224:227], v[174:177], 0
	v_mfma_f32_16x16x32_bf16 v[60:63], v[202:205], v[170:173], v[60:63]
	v_mfma_f32_16x16x32_bf16 v[56:59], v[202:205], v[178:181], v[56:59]
	v_mfma_f32_16x16x32_bf16 v[44:47], v[212:215], v[170:173], v[44:47]
	v_mfma_f32_16x16x32_bf16 v[40:43], v[212:215], v[178:181], v[40:43]
	v_mfma_f32_16x16x32_bf16 v[28:31], v[220:223], v[170:173], v[28:31]
	v_mfma_f32_16x16x32_bf16 v[24:27], v[220:223], v[178:181], v[24:27]
	v_mfma_f32_16x16x32_bf16 v[12:15], v[228:231], v[170:173], v[12:15]
	v_mfma_f32_16x16x32_bf16 v[8:11], v[228:231], v[178:181], v[8:11]
	s_setprio 0
	s_setprio 1
	v_mfma_f32_16x16x32_bf16 v[52:55], v[198:201], v[182:185], 0
	v_mfma_f32_16x16x32_bf16 v[48:51], v[198:201], v[190:193], 0
	v_mfma_f32_16x16x32_bf16 v[36:39], v[206:209], v[182:185], 0
	v_mfma_f32_16x16x32_bf16 v[32:35], v[206:209], v[190:193], 0
	v_mfma_f32_16x16x32_bf16 v[20:23], v[216:219], v[182:185], 0
	v_mfma_f32_16x16x32_bf16 v[16:19], v[216:219], v[190:193], 0
	v_mfma_f32_16x16x32_bf16 v[4:7], v[224:227], v[182:185], 0
	v_mfma_f32_16x16x32_bf16 v[0:3], v[224:227], v[190:193], 0
	v_mfma_f32_16x16x32_bf16 v[52:55], v[202:205], v[186:189], v[52:55]
	v_mfma_f32_16x16x32_bf16 v[48:51], v[202:205], v[194:197], v[48:51]
	v_mfma_f32_16x16x32_bf16 v[36:39], v[212:215], v[186:189], v[36:39]
	v_mfma_f32_16x16x32_bf16 v[32:35], v[212:215], v[194:197], v[32:35]
	v_mfma_f32_16x16x32_bf16 v[20:23], v[220:223], v[186:189], v[20:23]
	v_mfma_f32_16x16x32_bf16 v[16:19], v[220:223], v[194:197], v[16:19]
	v_mfma_f32_16x16x32_bf16 v[4:7], v[228:231], v[186:189], v[4:7]
	v_mfma_f32_16x16x32_bf16 v[0:3], v[228:231], v[194:197], v[0:3]
	s_setprio 0
	s_barrier
	ds_read_b128 v[166:169], v164
	ds_read_b128 v[170:173], v164 offset:1024
	ds_read_b128 v[174:177], v164 offset:2048
	ds_read_b128 v[178:181], v164 offset:3072
	ds_read_b128 v[182:185], v165
	ds_read_b128 v[186:189], v165 offset:1024
	ds_read_b128 v[190:193], v165 offset:2048
	ds_read_b128 v[194:197], v165 offset:3072
	s_add_u32 s48, s48, 0x40000
	s_addc_u32 s49, s49, 0
	v_readfirstlane_b32 s69, v146
	v_lshl_add_u64 v[240:241], s[48:49], 0, v[128:129]
	s_mov_b32 m0, s69
	ds_read_b128 v[198:201], v158 offset:32768
	ds_read_b128 v[202:205], v158 offset:33792
	ds_read_b128 v[206:209], v159 offset:32768
	ds_read_b128 v[212:215], v159 offset:33792
	ds_read_b128 v[216:219], v160 offset:32768
	ds_read_b128 v[220:223], v160 offset:33792
	ds_read_b128 v[224:227], v161 offset:32768
	ds_read_b128 v[228:231], v161 offset:33792
	global_load_lds_dwordx4 v[240:241], off
	v_lshl_add_u64 v[240:241], s[48:49], 0, v[130:131]
	v_readfirstlane_b32 s48, v147
	s_mov_b32 m0, s48
	s_nop 0
	global_load_lds_dwordx4 v[240:241], off
	s_waitcnt vmcnt(8)
	s_waitcnt lgkmcnt(0)
	s_barrier
	s_setprio 1
	s_waitcnt lgkmcnt(0)
	v_mfma_f32_16x16x32_bf16 v[124:127], v[198:201], v[166:169], v[124:127]
	v_mfma_f32_16x16x32_bf16 v[120:123], v[198:201], v[174:177], v[120:123]
	v_mfma_f32_16x16x32_bf16 v[108:111], v[206:209], v[166:169], v[108:111]
	v_mfma_f32_16x16x32_bf16 v[104:107], v[206:209], v[174:177], v[104:107]
	v_mfma_f32_16x16x32_bf16 v[92:95], v[216:219], v[166:169], v[92:95]
	v_mfma_f32_16x16x32_bf16 v[88:91], v[216:219], v[174:177], v[88:91]
	v_mfma_f32_16x16x32_bf16 v[76:79], v[224:227], v[166:169], v[76:79]
	v_mfma_f32_16x16x32_bf16 v[72:75], v[224:227], v[174:177], v[72:75]
	v_mfma_f32_16x16x32_bf16 v[124:127], v[202:205], v[170:173], v[124:127]
	v_mfma_f32_16x16x32_bf16 v[120:123], v[202:205], v[178:181], v[120:123]
	v_mfma_f32_16x16x32_bf16 v[108:111], v[212:215], v[170:173], v[108:111]
	v_mfma_f32_16x16x32_bf16 v[104:107], v[212:215], v[178:181], v[104:107]
	v_mfma_f32_16x16x32_bf16 v[92:95], v[220:223], v[170:173], v[92:95]
	v_mfma_f32_16x16x32_bf16 v[88:91], v[220:223], v[178:181], v[88:91]
	v_mfma_f32_16x16x32_bf16 v[76:79], v[228:231], v[170:173], v[76:79]
	v_mfma_f32_16x16x32_bf16 v[72:75], v[228:231], v[178:181], v[72:75]
	s_setprio 0
	s_setprio 1
	v_mfma_f32_16x16x32_bf16 v[116:119], v[198:201], v[182:185], v[116:119]
	v_mfma_f32_16x16x32_bf16 v[112:115], v[198:201], v[190:193], v[112:115]
	v_mfma_f32_16x16x32_bf16 v[100:103], v[206:209], v[182:185], v[100:103]
	v_mfma_f32_16x16x32_bf16 v[96:99], v[206:209], v[190:193], v[96:99]
	v_mfma_f32_16x16x32_bf16 v[84:87], v[216:219], v[182:185], v[84:87]
	v_mfma_f32_16x16x32_bf16 v[80:83], v[216:219], v[190:193], v[80:83]
	v_mfma_f32_16x16x32_bf16 v[68:71], v[224:227], v[182:185], v[68:71]
	v_mfma_f32_16x16x32_bf16 v[64:67], v[224:227], v[190:193], v[64:67]
	v_mfma_f32_16x16x32_bf16 v[116:119], v[202:205], v[186:189], v[116:119]
	v_mfma_f32_16x16x32_bf16 v[112:115], v[202:205], v[194:197], v[112:115]
	v_mfma_f32_16x16x32_bf16 v[100:103], v[212:215], v[186:189], v[100:103]
	v_mfma_f32_16x16x32_bf16 v[96:99], v[212:215], v[194:197], v[96:99]
	v_mfma_f32_16x16x32_bf16 v[84:87], v[220:223], v[186:189], v[84:87]
	v_mfma_f32_16x16x32_bf16 v[80:83], v[220:223], v[194:197], v[80:83]
	v_mfma_f32_16x16x32_bf16 v[68:71], v[228:231], v[186:189], v[68:71]
	v_mfma_f32_16x16x32_bf16 v[64:67], v[228:231], v[194:197], v[64:67]
	s_setprio 0
	s_barrier
; #define STAGE(P, g) do { const char* g_ = (const char*)(g); \
;         __builtin_amdgcn_global_load_lds((const unsigned*)(g_ + so0), (lds_u32*)((lds_u8*)(P) + sb0), 16, 0, 0); \
;         __builtin_amdgcn_global_load_lds((const unsigned*)(g_ + so1), (lds_u32*)((lds_u8*)(P) + sb0 + 8192), 16, 0, 0); } while (0)
; #define LDA(dst, b, h) for (int m = 0; m < 4; ++m) for (int k = 0; k < 2; ++k) \
;         dst[m][k] = *reinterpret_cast<const bf16x8*>((char*)SA(b, h) + lds_byte(wr * 64 + m * 16 + fr, k * 32 + fq * 8))
; #define MMA(ai, bj, At_, Bt_) do { __builtin_amdgcn_s_setprio(1); \
;         for (int m = 0; m < 4; ++m) for (int n = 0; n < 2; ++n) for (int k = 0; k < 2; ++k) \
;             acc[ai][bj][m][n] = __builtin_amdgcn_mfma_f32_16x16x32_bf16(At_[m][k], Bt_[n][k], acc[ai][bj][m][n], 0, 0, 0); \
;         __builtin_amdgcn_s_setprio(0); } while (0)
; #define WAIT_V(n) asm volatile("s_waitcnt vmcnt(" #n ")" ::: "memory")
; #define WAIT_L(n) asm volatile("s_waitcnt lgkmcnt(" #n ")" ::: "memory")
; #define BAR __builtin_amdgcn_s_barrier()
; #define SCHED __builtin_amdgcn_sched_barrier(0)
; template <int EPI, int K, int LNI = -1>
; DI void ph_gemm(const Params& p, const bf16_t* __restrict__ A, const bf16_t* __restrict__ Bt, int N, float* s_aux) {
;     ...
;         for (int t = 0; t < nt; t += 2) {
;     ...
;             LDA(At, 1, 1); STAGE(SB(1, 0), b3); STAGE(SB(1, 1), b3 + hstep); STAGE(SA(1, 0), a3);
;             WAIT_V(8); WAIT_L(0); BAR; MMA(1, 0, At, B0); MMA(1, 1, At, B1); BAR; SCHED;
	v_readfirstlane_b32 s48, v148
	v_lshl_add_u64 v[232:233], v[232:233], 0, s[12:13]
	s_mov_b32 m0, s48
	v_readfirstlane_b32 s48, v149
	s_add_u32 s46, s46, 0x40080
	ds_read_b128 v[198:201], v158 offset:49152
	ds_read_b128 v[202:205], v158 offset:50176
	ds_read_b128 v[206:209], v159 offset:49152
	ds_read_b128 v[212:215], v159 offset:50176
	ds_read_b128 v[216:219], v160 offset:49152
	ds_read_b128 v[220:223], v160 offset:50176
	ds_read_b128 v[224:227], v161 offset:49152
	ds_read_b128 v[228:231], v161 offset:50176
	global_load_lds_dwordx4 v[232:233], off
	v_lshl_add_u64 v[232:233], v[234:235], 0, s[12:13]
	s_mov_b32 m0, s48
	s_addc_u32 s47, s47, 0
	v_readfirstlane_b32 s48, v152
	global_load_lds_dwordx4 v[232:233], off
	v_lshl_add_u64 v[232:233], s[46:47], 0, v[128:129]
	s_mov_b32 m0, s48
	s_nop 0
	global_load_lds_dwordx4 v[232:233], off
	v_lshl_add_u64 v[232:233], s[46:47], 0, v[130:131]
	v_readfirstlane_b32 s46, v153
	s_mov_b32 m0, s46
	v_readfirstlane_b32 s46, v150
	global_load_lds_dwordx4 v[232:233], off
	v_lshl_add_u64 v[232:233], v[236:237], 0, s[12:13]
	s_mov_b32 m0, s46
	v_readfirstlane_b32 s46, v151
	global_load_lds_dwordx4 v[232:233], off
	v_lshl_add_u64 v[232:233], v[238:239], 0, s[12:13]
	s_mov_b32 m0, s46
	s_nop 0
	global_load_lds_dwordx4 v[232:233], off
	s_waitcnt vmcnt(8)
	s_waitcnt lgkmcnt(0)
	s_barrier
	s_setprio 1
	s_waitcnt lgkmcnt(0)
	v_mfma_f32_16x16x32_bf16 v[60:63], v[198:201], v[166:169], v[60:63]
	v_mfma_f32_16x16x32_bf16 v[56:59], v[198:201], v[174:177], v[56:59]
	v_mfma_f32_16x16x32_bf16 v[44:47], v[206:209], v[166:169], v[44:47]
	v_mfma_f32_16x16x32_bf16 v[40:43], v[206:209], v[174:177], v[40:43]
	v_mfma_f32_16x16x32_bf16 v[28:31], v[216:219], v[166:169], v[28:31]
	v_mfma_f32_16x16x32_bf16 v[24:27], v[216:219], v[174:177], v[24:27]
	v_mfma_f32_16x16x32_bf16 v[12:15], v[224:227], v[166:169], v[12:15]
	v_mfma_f32_16x16x32_bf16 v[8:11], v[224:227], v[174:177], v[8:11]
	v_mfma_f32_16x16x32_bf16 v[60:63], v[202:205], v[170:173], v[60:63]
	v_mfma_f32_16x16x32_bf16 v[56:59], v[202:205], v[178:181], v[56:59]
	v_mfma_f32_16x16x32_bf16 v[44:47], v[212:215], v[170:173], v[44:47]
	v_mfma_f32_16x16x32_bf16 v[40:43], v[212:215], v[178:181], v[40:43]
	v_mfma_f32_16x16x32_bf16 v[28:31], v[220:223], v[170:173], v[28:31]
	v_mfma_f32_16x16x32_bf16 v[24:27], v[220:223], v[178:181], v[24:27]
	v_mfma_f32_16x16x32_bf16 v[12:15], v[228:231], v[170:173], v[12:15]
	v_mfma_f32_16x16x32_bf16 v[8:11], v[228:231], v[178:181], v[8:11]
	s_setprio 0
	s_setprio 1
	v_mfma_f32_16x16x32_bf16 v[52:55], v[198:201], v[182:185], v[52:55]
	v_mfma_f32_16x16x32_bf16 v[48:51], v[198:201], v[190:193], v[48:51]
	v_mfma_f32_16x16x32_bf16 v[36:39], v[206:209], v[182:185], v[36:39]
	v_mfma_f32_16x16x32_bf16 v[32:35], v[206:209], v[190:193], v[32:35]
	v_mfma_f32_16x16x32_bf16 v[20:23], v[216:219], v[182:185], v[20:23]
	v_mfma_f32_16x16x32_bf16 v[16:19], v[216:219], v[190:193], v[16:19]
	v_mfma_f32_16x16x32_bf16 v[4:7], v[224:227], v[182:185], v[4:7]
	v_mfma_f32_16x16x32_bf16 v[0:3], v[224:227], v[190:193], v[0:3]
	v_mfma_f32_16x16x32_bf16 v[52:55], v[202:205], v[186:189], v[52:55]
	v_mfma_f32_16x16x32_bf16 v[48:51], v[202:205], v[194:197], v[48:51]
	v_mfma_f32_16x16x32_bf16 v[36:39], v[212:215], v[186:189], v[36:39]
	v_mfma_f32_16x16x32_bf16 v[32:35], v[212:215], v[194:197], v[32:35]
	v_mfma_f32_16x16x32_bf16 v[20:23], v[220:223], v[186:189], v[20:23]
	v_mfma_f32_16x16x32_bf16 v[16:19], v[220:223], v[194:197], v[16:19]
	v_mfma_f32_16x16x32_bf16 v[4:7], v[228:231], v[186:189], v[4:7]
	v_mfma_f32_16x16x32_bf16 v[0:3], v[228:231], v[194:197], v[0:3]
	s_setprio 0
	s_barrier
	s_add_i32 s68, s68, 2
	s_add_u32 s44, s44, 0x100
	s_addc_u32 s45, s45, 0
	s_cmp_gt_u32 s68, 13

; DI int opaque_tid() { int t = threadIdx.x; asm volatile("" : "+v"(t)); return t; }
; #define STAGE(P, g) do { const char* g_ = (const char*)(g); \
;         __builtin_amdgcn_global_load_lds((const unsigned*)(g_ + so0), (lds_u32*)((lds_u8*)(P) + sb0), 16, 0, 0); \
;         __builtin_amdgcn_global_load_lds((const unsigned*)(g_ + so1), (lds_u32*)((lds_u8*)(P) + sb0 + 8192), 16, 0, 0); } while (0)
; #define LDA(dst, b, h) for (int m = 0; m < 4; ++m) for (int k = 0; k < 2; ++k) \
;         dst[m][k] = *reinterpret_cast<const bf16x8*>((char*)SA(b, h) + lds_byte(wr * 64 + m * 16 + fr, k * 32 + fq * 8))
; template <int EPI, int K, int LNI = -1>
; DI void ph_gemm(const Params& p, const bf16_t* __restrict__ A, const bf16_t* __restrict__ Bt, int N, float* s_aux) {
;     ...
;         const int itn = it + (int)gridDim.x;
;         const bool has_next = itn < nwg;
;         int npm = pm, npn = pn;
;         if (has_next) unit(itn, npm, npn);
;         const bf16_t* nA = A + (size_t)npm * 256 * K; const bf16_t* nB = Bt + (size_t)npn * 256 * K;
;         const int brow = pm * 256, bcol = pn * 256;
;         float* sa = s_aux + (cnt & 1) * 512;
;         if (EPI == EPI_E5B) {
;             if (opaque_tid() < 256) {
;                 const int row = brow + (int)opaque_tid(); const int hd = bcol >> 9;
;                 const float* pp = (const float*)((unsigned char*)p.out + OFFO_PART) + (size_t)row * 256 + hd * 64;
;                 float sacc = 0.f;
; #pragma unroll
;                 for (int i = 0; i < 16; ++i) { const f32x4 v = *(const f32x4*)(pp + i * 4); sacc += (v[0] + v[1]) + (v[2] + v[3]); }
;                 sa[opaque_tid()] = __frsqrt_rn(sacc * (1.0f / 512.0f) + 1e-6f);
;             }
;         }
;         for (int t = 0; t < nt; t += 2) {
;             const bool last = (t == nt - 2);
;             const bf16_t* a1 = cA + (size_t)(t + 1) * kstep;
;             const bf16_t* a2 = last ? nA : cA + (size_t)(t + 2) * kstep; const bf16_t* b2 = last ? nB : cB + (size_t)(t + 2) * kstep;
;             const bf16_t* a3 = a2 + kstep; const bf16_t* b3 = b2 + kstep;
;             LDB(B0, 0, 0); LDB(B1, 0, 1); SCHED; LDA(At, 0, 0); STAGE(SA(1, 1), a1 + hstep);
;             WAIT_V(8); WAIT_L(0); BAR; MMA(0, 0, At, B0); MMA(0, 1, At, B1); BAR; SCHED;
;             LDA(At, 0, 1); STAGE(SB(0, 0), b2); STAGE(SB(0, 1), b2 + hstep); STAGE(SA(0, 0), a2);
.LBB0_1929:
	s_ashr_i32 s15, s14, 31
	s_lshl_b64 s[20:21], s[14:15], 21
	s_add_u32 s15, s36, s20
	s_addc_u32 s46, s37, s21
	s_ashr_i32 s13, s12, 31
	s_lshl_b64 s[22:23], s[12:13], 21
	s_add_u32 s13, s3, s22
	s_addc_u32 s47, s35, s23
	s_add_u32 s48, s56, s28
	s_addc_u32 s49, s57, s29
	s_add_u32 s50, s42, s38
	v_lshl_add_u64 v[128:129], v[140:141], 0, s[28:29]
	v_lshl_add_u64 v[130:131], v[142:143], 0, s[28:29]
	s_addc_u32 s51, s43, s39
	s_mov_b32 s52, -2
	s_mov_b64 s[28:29], 0
	ds_read_b128 v[132:135], v177
	ds_read_b128 v[144:147], v177 offset:1024
	ds_read_b128 v[148:151], v177 offset:2048
	ds_read_b128 v[152:155], v177 offset:3072
	ds_read_b128 v[156:159], v178
	ds_read_b128 v[188:191], v178 offset:1024
	ds_read_b128 v[192:195], v178 offset:2048
	ds_read_b128 v[196:199], v178 offset:3072
	s_add_u32 s38, s48, s28
	s_addc_u32 s39, s49, s29
	s_add_u32 s38, s38, 0xfa70100
	s_addc_u32 s39, s39, 0
	s_add_u32 s53, s50, s28
	s_addc_u32 s60, s51, s29
	s_cmpk_eq_i32 s28, 0x1f00
	s_cselect_b32 s41, s46, s39
	s_cselect_b32 s40, s15, s38
	s_cselect_b32 s39, s47, s60
	s_cselect_b32 s38, s13, s53
	v_readfirstlane_b32 s53, v183
	v_lshl_add_u64 v[208:209], v[128:129], 0, s[28:29]
	s_mov_b32 m0, s53
	v_readfirstlane_b32 s53, v184
	ds_read_b128 v[200:203], v179
	ds_read_b128 v[204:207], v179 offset:1024
	ds_read_b128 v[212:215], v180
	ds_read_b128 v[216:219], v180 offset:1024
	ds_read_b128 v[220:223], v181
	ds_read_b128 v[224:227], v181 offset:1024
	ds_read_b128 v[228:231], v182
	ds_read_b128 v[232:235], v182 offset:1024
	global_load_lds_dwordx4 v[208:209], off
	v_lshl_add_u64 v[208:209], v[130:131], 0, s[28:29]
	s_mov_b32 m0, s53
	s_nop 0
	global_load_lds_dwordx4 v[208:209], off
	s_waitcnt vmcnt(8)
	s_waitcnt lgkmcnt(0)
	s_barrier
	s_setprio 1
	s_waitcnt lgkmcnt(0)
	v_mfma_f32_16x16x32_bf16 v[124:127], v[200:203], v[132:135], 0
	v_mfma_f32_16x16x32_bf16 v[120:123], v[200:203], v[148:151], 0
	v_mfma_f32_16x16x32_bf16 v[108:111], v[212:215], v[132:135], 0
	v_mfma_f32_16x16x32_bf16 v[104:107], v[212:215], v[148:151], 0
	v_mfma_f32_16x16x32_bf16 v[92:95], v[220:223], v[132:135], 0
	v_mfma_f32_16x16x32_bf16 v[88:91], v[220:223], v[148:151], 0
	v_mfma_f32_16x16x32_bf16 v[76:79], v[228:231], v[132:135], 0
	v_mfma_f32_16x16x32_bf16 v[72:75], v[228:231], v[148:151], 0
	v_mfma_f32_16x16x32_bf16 v[124:127], v[204:207], v[144:147], v[124:127]
	v_mfma_f32_16x16x32_bf16 v[120:123], v[204:207], v[152:155], v[120:123]
	v_mfma_f32_16x16x32_bf16 v[108:111], v[216:219], v[144:147], v[108:111]
	v_mfma_f32_16x16x32_bf16 v[104:107], v[216:219], v[152:155], v[104:107]
	v_mfma_f32_16x16x32_bf16 v[92:95], v[224:227], v[144:147], v[92:95]
	v_mfma_f32_16x16x32_bf16 v[88:91], v[224:227], v[152:155], v[88:91]
	v_mfma_f32_16x16x32_bf16 v[76:79], v[232:235], v[144:147], v[76:79]
	v_mfma_f32_16x16x32_bf16 v[72:75], v[232:235], v[152:155], v[72:75]
	s_setprio 0
	s_setprio 1
	v_mfma_f32_16x16x32_bf16 v[116:119], v[200:203], v[156:159], 0
	v_mfma_f32_16x16x32_bf16 v[112:115], v[200:203], v[192:195], 0
	v_mfma_f32_16x16x32_bf16 v[100:103], v[212:215], v[156:159], 0
	v_mfma_f32_16x16x32_bf16 v[96:99], v[212:215], v[192:195], 0
	v_mfma_f32_16x16x32_bf16 v[84:87], v[220:223], v[156:159], 0
	v_mfma_f32_16x16x32_bf16 v[80:83], v[220:223], v[192:195], 0
	v_mfma_f32_16x16x32_bf16 v[68:71], v[228:231], v[156:159], 0
	v_mfma_f32_16x16x32_bf16 v[64:67], v[228:231], v[192:195], 0
	v_mfma_f32_16x16x32_bf16 v[116:119], v[204:207], v[188:191], v[116:119]
	v_mfma_f32_16x16x32_bf16 v[112:115], v[204:207], v[196:199], v[112:115]
	v_mfma_f32_16x16x32_bf16 v[100:103], v[216:219], v[188:191], v[100:103]
	v_mfma_f32_16x16x32_bf16 v[96:99], v[216:219], v[196:199], v[96:99]
	v_mfma_f32_16x16x32_bf16 v[84:87], v[224:227], v[188:191], v[84:87]
	v_mfma_f32_16x16x32_bf16 v[80:83], v[224:227], v[196:199], v[80:83]
	v_mfma_f32_16x16x32_bf16 v[68:71], v[232:235], v[188:191], v[68:71]
	v_mfma_f32_16x16x32_bf16 v[64:67], v[232:235], v[196:199], v[64:67]
	s_setprio 0
	s_barrier
	v_readfirstlane_b32 s53, v160
	v_lshl_add_u64 v[208:209], s[38:39], 0, v[136:137]
	s_mov_b32 m0, s53
	v_readfirstlane_b32 s53, v161
	s_add_u32 s60, s38, 0x100000
	ds_read_b128 v[200:203], v179 offset:16384
	ds_read_b128 v[204:207], v179 offset:17408
	ds_read_b128 v[212:215], v180 offset:16384
	ds_read_b128 v[216:219], v180 offset:17408
	ds_read_b128 v[220:223], v181 offset:16384
	ds_read_b128 v[224:227], v181 offset:17408
	ds_read_b128 v[228:231], v182 offset:16384
	ds_read_b128 v[232:235], v182 offset:17408
	global_load_lds_dwordx4 v[208:209], off
	v_lshl_add_u64 v[236:237], s[38:39], 0, v[138:139]
	s_mov_b32 m0, s53
	s_addc_u32 s61, s39, 0
	v_readfirstlane_b32 s53, v162
	global_load_lds_dwordx4 v[236:237], off
	v_lshl_add_u64 v[238:239], s[60:61], 0, v[136:137]
	s_mov_b32 m0, s53
	v_readfirstlane_b32 s53, v163
	global_load_lds_dwordx4 v[238:239], off
	v_lshl_add_u64 v[238:239], s[60:61], 0, v[138:139]
	s_mov_b32 m0, s53
	v_readfirstlane_b32 s53, v164
	global_load_lds_dwordx4 v[238:239], off
	v_lshl_add_u64 v[238:239], s[40:41], 0, v[136:137]
	s_mov_b32 m0, s53
	v_readfirstlane_b32 s53, v165
	global_load_lds_dwordx4 v[238:239], off
	v_lshl_add_u64 v[240:241], s[40:41], 0, v[138:139]
	s_mov_b32 m0, s53
	s_nop 0
	global_load_lds_dwordx4 v[240:241], off
	s_waitcnt vmcnt(8)
	s_waitcnt lgkmcnt(0)
	s_barrier
; #define STAGE(P, g) do { const char* g_ = (const char*)(g); \
;         __builtin_amdgcn_global_load_lds((const unsigned*)(g_ + so0), (lds_u32*)((lds_u8*)(P) + sb0), 16, 0, 0); \
;         __builtin_amdgcn_global_load_lds((const unsigned*)(g_ + so1), (lds_u32*)((lds_u8*)(P) + sb0 + 8192), 16, 0, 0); } while (0)
; #define LDA(dst, b, h) for (int m = 0; m < 4; ++m) for (int k = 0; k < 2; ++k) \
;         dst[m][k] = *reinterpret_cast<const bf16x8*>((char*)SA(b, h) + lds_byte(wr * 64 + m * 16 + fr, k * 32 + fq * 8))
; #define LDB(dst, b, h) for (int n = 0; n < 2; ++n) for (int k = 0; k < 2; ++k) \
;         dst[n][k] = *reinterpret_cast<const bf16x8*>((char*)SB(b, h) + lds_byte(wc * 32 + n * 16 + fr, k * 32 + fq * 8))
; #define MMA(ai, bj, At_, Bt_) do { __builtin_amdgcn_s_setprio(1); \
;         for (int m = 0; m < 4; ++m) for (int n = 0; n < 2; ++n) for (int k = 0; k < 2; ++k) \
;             acc[ai][bj][m][n] = __builtin_amdgcn_mfma_f32_16x16x32_bf16(At_[m][k], Bt_[n][k], acc[ai][bj][m][n], 0, 0, 0); \
;         __builtin_amdgcn_s_setprio(0); } while (0)
; #define WAIT_V(n) asm volatile("s_waitcnt vmcnt(" #n ")" ::: "memory")
; #define WAIT_L(n) asm volatile("s_waitcnt lgkmcnt(" #n ")" ::: "memory")
; #define BAR __builtin_amdgcn_s_barrier()
; #define SCHED __builtin_amdgcn_sched_barrier(0)
; template <int EPI, int K, int LNI = -1>
; DI void ph_gemm(const Params& p, const bf16_t* __restrict__ A, const bf16_t* __restrict__ Bt, int N, float* s_aux) {
;     ...
;             WAIT_V(8); WAIT_L(0); BAR; MMA(0, 0, At, B0); MMA(0, 1, At, B1); BAR; SCHED;
;             LDA(At, 0, 1); STAGE(SB(0, 0), b2); STAGE(SB(0, 1), b2 + hstep); STAGE(SA(0, 0), a2);
;             WAIT_V(8); WAIT_L(0); BAR; MMA(1, 0, At, B0); MMA(1, 1, At, B1); BAR; SCHED;
;             LDB(B0, 1, 0); LDB(B1, 1, 1); SCHED; LDA(At, 1, 0); STAGE(SA(0, 1), a2 + hstep);
;             WAIT_V(8); WAIT_L(0); BAR; MMA(0, 0, At, B0); MMA(0, 1, At, B1); BAR; SCHED;
	s_setprio 1
	s_waitcnt lgkmcnt(0)
	v_mfma_f32_16x16x32_bf16 v[60:63], v[200:203], v[132:135], 0
	v_mfma_f32_16x16x32_bf16 v[56:59], v[200:203], v[148:151], 0
	v_mfma_f32_16x16x32_bf16 v[44:47], v[212:215], v[132:135], 0
	v_mfma_f32_16x16x32_bf16 v[40:43], v[212:215], v[148:151], 0
	v_mfma_f32_16x16x32_bf16 v[28:31], v[220:223], v[132:135], 0
	v_mfma_f32_16x16x32_bf16 v[24:27], v[220:223], v[148:151], 0
	v_mfma_f32_16x16x32_bf16 v[12:15], v[228:231], v[132:135], 0
	v_mfma_f32_16x16x32_bf16 v[8:11], v[228:231], v[148:151], 0
	v_mfma_f32_16x16x32_bf16 v[60:63], v[204:207], v[144:147], v[60:63]
	v_mfma_f32_16x16x32_bf16 v[56:59], v[204:207], v[152:155], v[56:59]
	v_mfma_f32_16x16x32_bf16 v[44:47], v[216:219], v[144:147], v[44:47]
	v_mfma_f32_16x16x32_bf16 v[40:43], v[216:219], v[152:155], v[40:43]
	v_mfma_f32_16x16x32_bf16 v[28:31], v[224:227], v[144:147], v[28:31]
	v_mfma_f32_16x16x32_bf16 v[24:27], v[224:227], v[152:155], v[24:27]
	v_mfma_f32_16x16x32_bf16 v[12:15], v[232:235], v[144:147], v[12:15]
	v_mfma_f32_16x16x32_bf16 v[8:11], v[232:235], v[152:155], v[8:11]
	s_setprio 0
	s_setprio 1
	v_mfma_f32_16x16x32_bf16 v[52:55], v[200:203], v[156:159], 0
	v_mfma_f32_16x16x32_bf16 v[48:51], v[200:203], v[192:195], 0
	v_mfma_f32_16x16x32_bf16 v[36:39], v[212:215], v[156:159], 0
	v_mfma_f32_16x16x32_bf16 v[32:35], v[212:215], v[192:195], 0
	v_mfma_f32_16x16x32_bf16 v[20:23], v[220:223], v[156:159], 0
	v_mfma_f32_16x16x32_bf16 v[16:19], v[220:223], v[192:195], 0
	v_mfma_f32_16x16x32_bf16 v[4:7], v[228:231], v[156:159], 0
	v_mfma_f32_16x16x32_bf16 v[0:3], v[228:231], v[192:195], 0
	v_mfma_f32_16x16x32_bf16 v[52:55], v[204:207], v[188:191], v[52:55]
	v_mfma_f32_16x16x32_bf16 v[48:51], v[204:207], v[196:199], v[48:51]
	v_mfma_f32_16x16x32_bf16 v[36:39], v[216:219], v[188:191], v[36:39]
	v_mfma_f32_16x16x32_bf16 v[32:35], v[216:219], v[196:199], v[32:35]
	v_mfma_f32_16x16x32_bf16 v[20:23], v[224:227], v[188:191], v[20:23]
	v_mfma_f32_16x16x32_bf16 v[16:19], v[224:227], v[196:199], v[16:19]
	v_mfma_f32_16x16x32_bf16 v[4:7], v[232:235], v[188:191], v[4:7]
	v_mfma_f32_16x16x32_bf16 v[0:3], v[232:235], v[196:199], v[0:3]
	s_setprio 0
	s_barrier
	ds_read_b128 v[132:135], v185
	ds_read_b128 v[144:147], v185 offset:1024
	ds_read_b128 v[148:151], v185 offset:2048
	ds_read_b128 v[152:155], v185 offset:3072
	ds_read_b128 v[156:159], v186
	ds_read_b128 v[188:191], v186 offset:1024
	ds_read_b128 v[192:195], v186 offset:2048
	ds_read_b128 v[196:199], v186 offset:3072
	s_add_u32 s40, s40, 0x100000
	s_addc_u32 s41, s41, 0
	v_readfirstlane_b32 s53, v166
	v_lshl_add_u64 v[242:243], s[40:41], 0, v[136:137]
	s_mov_b32 m0, s53
	ds_read_b128 v[200:203], v179 offset:32768
	ds_read_b128 v[204:207], v179 offset:33792
	ds_read_b128 v[212:215], v180 offset:32768
	ds_read_b128 v[216:219], v180 offset:33792
	ds_read_b128 v[220:223], v181 offset:32768
	ds_read_b128 v[224:227], v181 offset:33792
	ds_read_b128 v[228:231], v182 offset:32768
	ds_read_b128 v[232:235], v182 offset:33792
	global_load_lds_dwordx4 v[242:243], off
	v_lshl_add_u64 v[242:243], s[40:41], 0, v[138:139]
	v_readfirstlane_b32 s40, v167
	s_mov_b32 m0, s40
	s_nop 0
	global_load_lds_dwordx4 v[242:243], off
	s_waitcnt vmcnt(8)
	s_waitcnt lgkmcnt(0)
	s_barrier
	s_setprio 1
	s_waitcnt lgkmcnt(0)
	v_mfma_f32_16x16x32_bf16 v[124:127], v[200:203], v[132:135], v[124:127]
	v_mfma_f32_16x16x32_bf16 v[120:123], v[200:203], v[148:151], v[120:123]
	v_mfma_f32_16x16x32_bf16 v[108:111], v[212:215], v[132:135], v[108:111]
	v_mfma_f32_16x16x32_bf16 v[104:107], v[212:215], v[148:151], v[104:107]
	v_mfma_f32_16x16x32_bf16 v[92:95], v[220:223], v[132:135], v[92:95]
	v_mfma_f32_16x16x32_bf16 v[88:91], v[220:223], v[148:151], v[88:91]
	v_mfma_f32_16x16x32_bf16 v[76:79], v[228:231], v[132:135], v[76:79]
	v_mfma_f32_16x16x32_bf16 v[72:75], v[228:231], v[148:151], v[72:75]
	v_mfma_f32_16x16x32_bf16 v[124:127], v[204:207], v[144:147], v[124:127]
	v_mfma_f32_16x16x32_bf16 v[120:123], v[204:207], v[152:155], v[120:123]
	v_mfma_f32_16x16x32_bf16 v[108:111], v[216:219], v[144:147], v[108:111]
	v_mfma_f32_16x16x32_bf16 v[104:107], v[216:219], v[152:155], v[104:107]
	v_mfma_f32_16x16x32_bf16 v[92:95], v[224:227], v[144:147], v[92:95]
	v_mfma_f32_16x16x32_bf16 v[88:91], v[224:227], v[152:155], v[88:91]
	v_mfma_f32_16x16x32_bf16 v[76:79], v[232:235], v[144:147], v[76:79]
	v_mfma_f32_16x16x32_bf16 v[72:75], v[232:235], v[152:155], v[72:75]
	s_setprio 0
	s_setprio 1
	v_mfma_f32_16x16x32_bf16 v[116:119], v[200:203], v[156:159], v[116:119]
	v_mfma_f32_16x16x32_bf16 v[112:115], v[200:203], v[192:195], v[112:115]
	v_mfma_f32_16x16x32_bf16 v[100:103], v[212:215], v[156:159], v[100:103]
	v_mfma_f32_16x16x32_bf16 v[96:99], v[212:215], v[192:195], v[96:99]
	v_mfma_f32_16x16x32_bf16 v[84:87], v[220:223], v[156:159], v[84:87]
	v_mfma_f32_16x16x32_bf16 v[80:83], v[220:223], v[192:195], v[80:83]
	v_mfma_f32_16x16x32_bf16 v[68:71], v[228:231], v[156:159], v[68:71]
	v_mfma_f32_16x16x32_bf16 v[64:67], v[228:231], v[192:195], v[64:67]
	v_mfma_f32_16x16x32_bf16 v[116:119], v[204:207], v[188:191], v[116:119]
	v_mfma_f32_16x16x32_bf16 v[112:115], v[204:207], v[196:199], v[112:115]
	v_mfma_f32_16x16x32_bf16 v[100:103], v[216:219], v[188:191], v[100:103]
	v_mfma_f32_16x16x32_bf16 v[96:99], v[216:219], v[196:199], v[96:99]
	v_mfma_f32_16x16x32_bf16 v[84:87], v[224:227], v[188:191], v[84:87]
	v_mfma_f32_16x16x32_bf16 v[80:83], v[224:227], v[196:199], v[80:83]
	v_mfma_f32_16x16x32_bf16 v[68:71], v[232:235], v[188:191], v[68:71]
	v_mfma_f32_16x16x32_bf16 v[64:67], v[232:235], v[196:199], v[64:67]
	s_setprio 0
	s_barrier
; #define STAGE(P, g) do { const char* g_ = (const char*)(g); \
;         __builtin_amdgcn_global_load_lds((const unsigned*)(g_ + so0), (lds_u32*)((lds_u8*)(P) + sb0), 16, 0, 0); \
;         __builtin_amdgcn_global_load_lds((const unsigned*)(g_ + so1), (lds_u32*)((lds_u8*)(P) + sb0 + 8192), 16, 0, 0); } while (0)
; #define LDA(dst, b, h) for (int m = 0; m < 4; ++m) for (int k = 0; k < 2; ++k) \
;         dst[m][k] = *reinterpret_cast<const bf16x8*>((char*)SA(b, h) + lds_byte(wr * 64 + m * 16 + fr, k * 32 + fq * 8))
; #define MMA(ai, bj, At_, Bt_) do { __builtin_amdgcn_s_setprio(1); \
;         for (int m = 0; m < 4; ++m) for (int n = 0; n < 2; ++n) for (int k = 0; k < 2; ++k) \
;             acc[ai][bj][m][n] = __builtin_amdgcn_mfma_f32_16x16x32_bf16(At_[m][k], Bt_[n][k], acc[ai][bj][m][n], 0, 0, 0); \
;         __builtin_amdgcn_s_setprio(0); } while (0)
; #define WAIT_V(n) asm volatile("s_waitcnt vmcnt(" #n ")" ::: "memory")
; #define WAIT_L(n) asm volatile("s_waitcnt lgkmcnt(" #n ")" ::: "memory")
; #define BAR __builtin_amdgcn_s_barrier()
; #define SCHED __builtin_amdgcn_sched_barrier(0)
; template <int EPI, int K, int LNI = -1>
; DI void ph_gemm(const Params& p, const bf16_t* __restrict__ A, const bf16_t* __restrict__ Bt, int N, float* s_aux) {
;     ...
;         for (int t = 0; t < nt; t += 2) {
;     ...
;             LDA(At, 1, 1); STAGE(SB(1, 0), b3); STAGE(SB(1, 1), b3 + hstep); STAGE(SA(1, 0), a3);
;             WAIT_V(8); WAIT_L(0); BAR; MMA(1, 0, At, B0); MMA(1, 1, At, B1); BAR; SCHED;
	v_readfirstlane_b32 s40, v168
	v_lshl_add_u64 v[208:209], v[208:209], 0, s[8:9]
	s_mov_b32 m0, s40
	v_readfirstlane_b32 s40, v169
	s_add_u32 s38, s38, 0x100080
	ds_read_b128 v[200:203], v179 offset:49152
	ds_read_b128 v[204:207], v179 offset:50176
	ds_read_b128 v[212:215], v180 offset:49152
	ds_read_b128 v[216:219], v180 offset:50176
	ds_read_b128 v[220:223], v181 offset:49152
	ds_read_b128 v[224:227], v181 offset:50176
	ds_read_b128 v[228:231], v182 offset:49152
	ds_read_b128 v[232:235], v182 offset:50176
	global_load_lds_dwordx4 v[208:209], off
	v_lshl_add_u64 v[208:209], v[236:237], 0, s[8:9]
	s_mov_b32 m0, s40
	s_addc_u32 s39, s39, 0
	v_readfirstlane_b32 s40, v172
	global_load_lds_dwordx4 v[208:209], off
	v_lshl_add_u64 v[208:209], s[38:39], 0, v[136:137]
	s_mov_b32 m0, s40
	s_nop 0
	global_load_lds_dwordx4 v[208:209], off
	v_lshl_add_u64 v[208:209], s[38:39], 0, v[138:139]
	v_readfirstlane_b32 s38, v173
	s_mov_b32 m0, s38
	v_readfirstlane_b32 s38, v170
	global_load_lds_dwordx4 v[208:209], off
	v_lshl_add_u64 v[208:209], v[238:239], 0, s[8:9]
	s_mov_b32 m0, s38
	v_readfirstlane_b32 s38, v171
	global_load_lds_dwordx4 v[208:209], off
	v_lshl_add_u64 v[208:209], v[240:241], 0, s[8:9]
	s_mov_b32 m0, s38
	s_nop 0
	global_load_lds_dwordx4 v[208:209], off
	s_waitcnt vmcnt(8)
	s_waitcnt lgkmcnt(0)
	s_barrier
	s_setprio 1
	s_waitcnt lgkmcnt(0)
	v_mfma_f32_16x16x32_bf16 v[60:63], v[200:203], v[132:135], v[60:63]
	v_mfma_f32_16x16x32_bf16 v[56:59], v[200:203], v[148:151], v[56:59]
	v_mfma_f32_16x16x32_bf16 v[44:47], v[212:215], v[132:135], v[44:47]
	v_mfma_f32_16x16x32_bf16 v[40:43], v[212:215], v[148:151], v[40:43]
	v_mfma_f32_16x16x32_bf16 v[28:31], v[220:223], v[132:135], v[28:31]
	v_mfma_f32_16x16x32_bf16 v[24:27], v[220:223], v[148:151], v[24:27]
	v_mfma_f32_16x16x32_bf16 v[12:15], v[228:231], v[132:135], v[12:15]
	v_mfma_f32_16x16x32_bf16 v[8:11], v[228:231], v[148:151], v[8:11]
	v_mfma_f32_16x16x32_bf16 v[60:63], v[204:207], v[144:147], v[60:63]
	v_mfma_f32_16x16x32_bf16 v[56:59], v[204:207], v[152:155], v[56:59]
	v_mfma_f32_16x16x32_bf16 v[44:47], v[216:219], v[144:147], v[44:47]
	v_mfma_f32_16x16x32_bf16 v[40:43], v[216:219], v[152:155], v[40:43]
	v_mfma_f32_16x16x32_bf16 v[28:31], v[224:227], v[144:147], v[28:31]
	v_mfma_f32_16x16x32_bf16 v[24:27], v[224:227], v[152:155], v[24:27]
	v_mfma_f32_16x16x32_bf16 v[12:15], v[232:235], v[144:147], v[12:15]
	v_mfma_f32_16x16x32_bf16 v[8:11], v[232:235], v[152:155], v[8:11]
	s_setprio 0
	s_setprio 1
	v_mfma_f32_16x16x32_bf16 v[52:55], v[200:203], v[156:159], v[52:55]
	v_mfma_f32_16x16x32_bf16 v[48:51], v[200:203], v[192:195], v[48:51]
	v_mfma_f32_16x16x32_bf16 v[36:39], v[212:215], v[156:159], v[36:39]
	v_mfma_f32_16x16x32_bf16 v[32:35], v[212:215], v[192:195], v[32:35]
	v_mfma_f32_16x16x32_bf16 v[20:23], v[220:223], v[156:159], v[20:23]
	v_mfma_f32_16x16x32_bf16 v[16:19], v[220:223], v[192:195], v[16:19]
	v_mfma_f32_16x16x32_bf16 v[4:7], v[228:231], v[156:159], v[4:7]
	v_mfma_f32_16x16x32_bf16 v[0:3], v[228:231], v[192:195], v[0:3]
	v_mfma_f32_16x16x32_bf16 v[52:55], v[204:207], v[188:191], v[52:55]
	v_mfma_f32_16x16x32_bf16 v[48:51], v[204:207], v[196:199], v[48:51]
	v_mfma_f32_16x16x32_bf16 v[36:39], v[216:219], v[188:191], v[36:39]
	v_mfma_f32_16x16x32_bf16 v[32:35], v[216:219], v[196:199], v[32:35]
	v_mfma_f32_16x16x32_bf16 v[20:23], v[224:227], v[188:191], v[20:23]
	v_mfma_f32_16x16x32_bf16 v[16:19], v[224:227], v[196:199], v[16:19]
	v_mfma_f32_16x16x32_bf16 v[4:7], v[232:235], v[188:191], v[4:7]
	v_mfma_f32_16x16x32_bf16 v[0:3], v[232:235], v[196:199], v[0:3]
	s_setprio 0
	s_barrier
	s_add_i32 s52, s52, 2
	s_add_u32 s28, s28, 0x100
	s_addc_u32 s29, s29, 0
	s_cmp_gt_u32 s52, 61
